# removed the 14 post-barrier s_waitcnt lgkmcnt(0) made redundant by the full wait before the barrier
# baseline (speedup 1.0000x reference)
.LBB0_175:
	ds_read_b128 v[40:43], v234
	ds_read_b128 v[44:47], v234 offset:1024
	ds_read_b128 v[48:51], v234 offset:2048
	ds_read_b128 v[52:55], v234 offset:3072
	ds_read_b128 v[186:189], v234 offset:4096
	ds_read_b128 v[190:193], v234 offset:5120
	ds_read_b128 v[194:197], v234 offset:6144
	ds_read_b128 v[198:201], v234 offset:7168
	ds_read_b128 v[16:19], v233
	ds_read_b128 v[20:23], v233 offset:1024
	ds_read_b128 v[24:27], v233 offset:2048
	ds_read_b128 v[28:31], v233 offset:3072
	s_add_u32 s6, s4, 0xfffc0080
	s_addc_u32 s7, s5, -1
	s_cmp_eq_u32 s34, 12
	s_cselect_b32 s9, s10, s7
	s_cselect_b32 s8, s11, s6
	s_cselect_b32 s7, s25, s31
	s_cselect_b32 s6, s29, s30
	v_lshl_add_u64 v[202:203], s[4:5], 0, v[182:183]
	s_add_i32 m0, s92, 0xc000
	s_nop 0
	global_load_lds_dwordx4 v[202:203], off
	v_lshl_add_u64 v[202:203], s[4:5], 0, v[184:185]
	s_add_i32 m0, s92, 0xe000
	s_nop 0
	global_load_lds_dwordx4 v[202:203], off
	s_waitcnt lgkmcnt(0)
	s_barrier
	v_mfma_f32_16x16x32_bf16 v[156:159], v[16:19], v[40:43], v[156:159]
	v_mfma_f32_16x16x32_bf16 v[152:155], v[24:27], v[40:43], v[152:155]
	v_mfma_f32_16x16x32_bf16 v[140:143], v[16:19], v[48:51], v[140:143]
	v_mfma_f32_16x16x32_bf16 v[136:139], v[24:27], v[48:51], v[136:139]
	v_mfma_f32_16x16x32_bf16 v[124:127], v[16:19], v[186:189], v[124:127]
	v_mfma_f32_16x16x32_bf16 v[120:123], v[24:27], v[186:189], v[120:123]
	v_mfma_f32_16x16x32_bf16 v[108:111], v[16:19], v[194:197], v[108:111]
	v_mfma_f32_16x16x32_bf16 v[104:107], v[24:27], v[194:197], v[104:107]
	v_mfma_f32_16x16x32_bf16 v[156:159], v[20:23], v[44:47], v[156:159]
	v_mfma_f32_16x16x32_bf16 v[152:155], v[28:31], v[44:47], v[152:155]
	v_mfma_f32_16x16x32_bf16 v[140:143], v[20:23], v[52:55], v[140:143]
	v_mfma_f32_16x16x32_bf16 v[136:139], v[28:31], v[52:55], v[136:139]
	v_mfma_f32_16x16x32_bf16 v[124:127], v[20:23], v[190:193], v[124:127]
	v_mfma_f32_16x16x32_bf16 v[120:123], v[28:31], v[190:193], v[120:123]
	v_mfma_f32_16x16x32_bf16 v[108:111], v[20:23], v[198:201], v[108:111]
	v_mfma_f32_16x16x32_bf16 v[104:107], v[28:31], v[198:201], v[104:107]
	s_barrier
	s_add_i32 s35, s1, s33
	v_lshl_add_u64 v[218:219], s[6:7], 0, v[166:167]
	s_mov_b32 m0, s35
	ds_read_b128 v[202:205], v235
	ds_read_b128 v[206:209], v235 offset:1024
	ds_read_b128 v[210:213], v235 offset:2048
	ds_read_b128 v[214:217], v235 offset:3072
	global_load_lds_dwordx4 v[218:219], off
	v_lshl_add_u64 v[246:247], s[6:7], 0, v[162:163]
	s_add_i32 m0, s35, 0x2000
	s_nop 0
	global_load_lds_dwordx4 v[246:247], off
	s_barrier
	s_waitcnt lgkmcnt(0)
	v_mfma_f32_16x16x32_bf16 v[148:151], v[202:205], v[40:43], v[148:151]
	v_mfma_f32_16x16x32_bf16 v[40:43], v[210:213], v[40:43], v[144:147]
	v_mfma_f32_16x16x32_bf16 v[148:151], v[206:209], v[44:47], v[148:151]
	v_mfma_f32_16x16x32_bf16 v[40:43], v[214:217], v[44:47], v[40:43]
	v_mfma_f32_16x16x32_bf16 v[44:47], v[202:205], v[48:51], v[132:135]
	v_mfma_f32_16x16x32_bf16 v[48:51], v[210:213], v[48:51], v[128:131]
	v_mfma_f32_16x16x32_bf16 v[112:115], v[210:213], v[186:189], v[112:115]
	v_mfma_f32_16x16x32_bf16 v[100:103], v[202:205], v[194:197], v[100:103]
	v_mfma_f32_16x16x32_bf16 v[96:99], v[210:213], v[194:197], v[96:99]
	v_mfma_f32_16x16x32_bf16 v[44:47], v[206:209], v[52:55], v[44:47]
	v_mfma_f32_16x16x32_bf16 v[48:51], v[214:217], v[52:55], v[48:51]
	v_mfma_f32_16x16x32_bf16 v[52:55], v[202:205], v[186:189], v[116:119]
	v_mfma_f32_16x16x32_bf16 v[112:115], v[214:217], v[190:193], v[112:115]
	v_mfma_f32_16x16x32_bf16 v[100:103], v[206:209], v[198:201], v[100:103]
	v_mfma_f32_16x16x32_bf16 v[96:99], v[214:217], v[198:201], v[96:99]
	v_mfma_f32_16x16x32_bf16 v[52:55], v[206:209], v[190:193], v[52:55]
	s_mov_b32 m0, s92
	v_lshl_add_u64 v[248:249], s[8:9], 0, v[168:169]
	s_barrier
	ds_read_b128 v[116:119], v234 offset:16384
	ds_read_b128 v[128:131], v234 offset:17408
	ds_read_b128 v[132:135], v234 offset:18432
	ds_read_b128 v[144:147], v234 offset:19456
	ds_read_b128 v[186:189], v234 offset:20480
	ds_read_b128 v[190:193], v234 offset:21504
	ds_read_b128 v[194:197], v234 offset:22528
	ds_read_b128 v[198:201], v234 offset:23552
	global_load_lds_dwordx4 v[248:249], off
	v_lshl_add_u64 v[250:251], s[8:9], 0, v[164:165]
	s_mov_b32 m0, s93
	s_nop 0
	global_load_lds_dwordx4 v[250:251], off
	s_barrier
	s_waitcnt lgkmcnt(0)
	v_mfma_f32_16x16x32_bf16 v[92:95], v[16:19], v[116:119], v[92:95]
	v_mfma_f32_16x16x32_bf16 v[88:91], v[24:27], v[116:119], v[88:91]
	v_mfma_f32_16x16x32_bf16 v[76:79], v[16:19], v[132:135], v[76:79]
	v_mfma_f32_16x16x32_bf16 v[72:75], v[24:27], v[132:135], v[72:75]
	v_mfma_f32_16x16x32_bf16 v[60:63], v[16:19], v[186:189], v[60:63]
	v_mfma_f32_16x16x32_bf16 v[56:59], v[24:27], v[186:189], v[56:59]
	v_mfma_f32_16x16x32_bf16 v[12:15], v[16:19], v[194:197], v[12:15]
	v_mfma_f32_16x16x32_bf16 v[8:11], v[24:27], v[194:197], v[8:11]
	v_mfma_f32_16x16x32_bf16 v[92:95], v[20:23], v[128:131], v[92:95]
	v_mfma_f32_16x16x32_bf16 v[88:91], v[28:31], v[128:131], v[88:91]
	v_mfma_f32_16x16x32_bf16 v[76:79], v[20:23], v[144:147], v[76:79]
	v_mfma_f32_16x16x32_bf16 v[72:75], v[28:31], v[144:147], v[72:75]
	v_mfma_f32_16x16x32_bf16 v[60:63], v[20:23], v[190:193], v[60:63]
	v_mfma_f32_16x16x32_bf16 v[56:59], v[28:31], v[190:193], v[56:59]
	v_mfma_f32_16x16x32_bf16 v[12:15], v[20:23], v[198:201], v[12:15]
	v_mfma_f32_16x16x32_bf16 v[8:11], v[28:31], v[198:201], v[8:11]
	s_barrier
	s_add_u32 s56, s6, 0x40000
	s_addc_u32 s57, s7, 0
	s_add_i32 s35, s18, s33
	v_lshl_add_u64 v[16:17], s[56:57], 0, v[166:167]
	s_mov_b32 m0, s35
	s_nop 0
	global_load_lds_dwordx4 v[16:17], off
	v_lshl_add_u64 v[16:17], s[56:57], 0, v[162:163]
	s_add_i32 m0, s35, 0x2000
	s_nop 0
	global_load_lds_dwordx4 v[16:17], off
	s_waitcnt vmcnt(6)
	s_barrier
	v_mfma_f32_16x16x32_bf16 v[36:39], v[202:205], v[186:189], v[36:39]
	v_mfma_f32_16x16x32_bf16 v[32:35], v[210:213], v[186:189], v[32:35]
	v_mfma_f32_16x16x32_bf16 v[4:7], v[202:205], v[194:197], v[4:7]
	v_mfma_f32_16x16x32_bf16 v[0:3], v[210:213], v[194:197], v[0:3]
	v_mfma_f32_16x16x32_bf16 v[16:19], v[202:205], v[116:119], v[84:87]
	v_mfma_f32_16x16x32_bf16 v[20:23], v[210:213], v[116:119], v[80:83]
	v_mfma_f32_16x16x32_bf16 v[24:27], v[202:205], v[132:135], v[68:71]
	v_mfma_f32_16x16x32_bf16 v[28:31], v[210:213], v[132:135], v[64:67]
	v_mfma_f32_16x16x32_bf16 v[36:39], v[206:209], v[190:193], v[36:39]
	v_mfma_f32_16x16x32_bf16 v[32:35], v[214:217], v[190:193], v[32:35]
	v_mfma_f32_16x16x32_bf16 v[4:7], v[206:209], v[198:201], v[4:7]
	v_mfma_f32_16x16x32_bf16 v[0:3], v[214:217], v[198:201], v[0:3]
	v_mfma_f32_16x16x32_bf16 v[16:19], v[206:209], v[128:131], v[16:19]
	v_mfma_f32_16x16x32_bf16 v[20:23], v[214:217], v[128:131], v[20:23]
	v_mfma_f32_16x16x32_bf16 v[24:27], v[206:209], v[144:147], v[24:27]
	v_mfma_f32_16x16x32_bf16 v[28:31], v[214:217], v[144:147], v[28:31]
	s_add_i32 s35, 0, 0x18000
	v_add_u32_e32 v84, s35, v232
	s_barrier
	ds_read_b128 v[116:119], v234 offset:32768
	ds_read_b128 v[128:131], v234 offset:33792
	ds_read_b128 v[186:189], v234 offset:34816
	ds_read_b128 v[190:193], v234 offset:35840
	ds_read_b128 v[194:197], v234 offset:36864
	ds_read_b128 v[198:201], v234 offset:37888
	ds_read_b128 v[202:205], v234 offset:38912
	ds_read_b128 v[206:209], v234 offset:39936
	ds_read_b128 v[64:67], v84
	ds_read_b128 v[68:71], v84 offset:1024
	ds_read_b128 v[80:83], v84 offset:2048
	ds_read_b128 v[84:87], v84 offset:3072
	s_add_u32 s8, s8, 0x40000
	s_addc_u32 s9, s9, 0
	s_mov_b32 m0, s96
	v_lshl_add_u64 v[132:133], s[8:9], 0, v[168:169]
	global_load_lds_dwordx4 v[132:133], off
	v_lshl_add_u64 v[132:133], s[8:9], 0, v[164:165]
	s_mov_b32 m0, s97
	s_nop 0
	global_load_lds_dwordx4 v[132:133], off
	s_waitcnt lgkmcnt(0)
	s_barrier
	v_mfma_f32_16x16x32_bf16 v[132:135], v[64:67], v[116:119], v[156:159]
	v_mfma_f32_16x16x32_bf16 v[156:159], v[68:71], v[128:131], v[132:135]
	v_mfma_f32_16x16x32_bf16 v[132:135], v[80:83], v[116:119], v[152:155]
	v_mfma_f32_16x16x32_bf16 v[152:155], v[84:87], v[128:131], v[132:135]
	v_mfma_f32_16x16x32_bf16 v[132:135], v[64:67], v[186:189], v[140:143]
	v_mfma_f32_16x16x32_bf16 v[140:143], v[68:71], v[190:193], v[132:135]
	v_mfma_f32_16x16x32_bf16 v[132:135], v[80:83], v[186:189], v[136:139]
	v_mfma_f32_16x16x32_bf16 v[124:127], v[64:67], v[194:197], v[124:127]
	v_mfma_f32_16x16x32_bf16 v[120:123], v[80:83], v[194:197], v[120:123]
	v_mfma_f32_16x16x32_bf16 v[108:111], v[64:67], v[202:205], v[108:111]
	v_mfma_f32_16x16x32_bf16 v[104:107], v[80:83], v[202:205], v[104:107]
	v_mfma_f32_16x16x32_bf16 v[136:139], v[84:87], v[190:193], v[132:135]
	v_mfma_f32_16x16x32_bf16 v[124:127], v[68:71], v[198:201], v[124:127]
	v_mfma_f32_16x16x32_bf16 v[120:123], v[84:87], v[198:201], v[120:123]
	v_mfma_f32_16x16x32_bf16 v[108:111], v[68:71], v[206:209], v[108:111]
	v_mfma_f32_16x16x32_bf16 v[104:107], v[84:87], v[206:209], v[104:107]
	s_barrier
	s_add_i32 s8, 0, 0x1c000
	v_add_u32_e32 v132, s8, v232
	s_add_i32 s9, s35, s33
	ds_read_b128 v[210:213], v132
	ds_read_b128 v[214:217], v132 offset:1024
	ds_read_b128 v[238:241], v132 offset:2048
	ds_read_b128 v[242:245], v132 offset:3072
	v_lshl_add_u64 v[132:133], v[218:219], 0, s[14:15]
	s_mov_b32 m0, s9
	s_nop 0
	global_load_lds_dwordx4 v[132:133], off
	v_lshl_add_u64 v[132:133], v[246:247], 0, s[14:15]
	s_add_i32 m0, s9, 0x2000
	s_nop 0
	global_load_lds_dwordx4 v[132:133], off
	s_barrier
	s_waitcnt lgkmcnt(0)
	v_mfma_f32_16x16x32_bf16 v[40:43], v[238:241], v[116:119], v[40:43]
	v_mfma_f32_16x16x32_bf16 v[132:135], v[210:213], v[116:119], v[148:151]
	v_mfma_f32_16x16x32_bf16 v[144:147], v[242:245], v[128:131], v[40:43]
	v_mfma_f32_16x16x32_bf16 v[40:43], v[210:213], v[186:189], v[44:47]
	v_mfma_f32_16x16x32_bf16 v[148:151], v[214:217], v[128:131], v[132:135]
	v_mfma_f32_16x16x32_bf16 v[132:135], v[214:217], v[190:193], v[40:43]
	v_mfma_f32_16x16x32_bf16 v[40:43], v[238:241], v[186:189], v[48:51]
	v_mfma_f32_16x16x32_bf16 v[128:131], v[242:245], v[190:193], v[40:43]
	v_mfma_f32_16x16x32_bf16 v[40:43], v[210:213], v[194:197], v[52:55]
	v_mfma_f32_16x16x32_bf16 v[116:119], v[214:217], v[198:201], v[40:43]
	v_mfma_f32_16x16x32_bf16 v[40:43], v[238:241], v[194:197], v[112:115]
	v_mfma_f32_16x16x32_bf16 v[112:115], v[242:245], v[198:201], v[40:43]
	v_mfma_f32_16x16x32_bf16 v[40:43], v[210:213], v[202:205], v[100:103]
	v_mfma_f32_16x16x32_bf16 v[100:103], v[214:217], v[206:209], v[40:43]
	v_mfma_f32_16x16x32_bf16 v[40:43], v[238:241], v[202:205], v[96:99]
	v_mfma_f32_16x16x32_bf16 v[96:99], v[242:245], v[206:209], v[40:43]
	s_mov_b32 m0, s53
	v_lshl_add_u64 v[202:203], v[248:249], 0, s[14:15]
	s_barrier
	s_nop 2
	ds_read_b128 v[40:43], v234 offset:49152
	ds_read_b128 v[44:47], v234 offset:50176
	ds_read_b128 v[48:51], v234 offset:51200
	ds_read_b128 v[52:55], v234 offset:52224
	ds_read_b128 v[186:189], v234 offset:53248
	ds_read_b128 v[190:193], v234 offset:54272
	ds_read_b128 v[194:197], v234 offset:55296
	ds_read_b128 v[198:201], v234 offset:56320
	global_load_lds_dwordx4 v[202:203], off
	v_lshl_add_u64 v[202:203], v[250:251], 0, s[14:15]
	s_mov_b32 m0, s23
	s_nop 0
	global_load_lds_dwordx4 v[202:203], off
	s_barrier
	s_waitcnt lgkmcnt(0)
	v_mfma_f32_16x16x32_bf16 v[92:95], v[64:67], v[40:43], v[92:95]
	v_mfma_f32_16x16x32_bf16 v[88:91], v[80:83], v[40:43], v[88:91]
	v_mfma_f32_16x16x32_bf16 v[76:79], v[64:67], v[48:51], v[76:79]
	v_mfma_f32_16x16x32_bf16 v[72:75], v[80:83], v[48:51], v[72:75]
	v_mfma_f32_16x16x32_bf16 v[60:63], v[64:67], v[186:189], v[60:63]
	v_mfma_f32_16x16x32_bf16 v[56:59], v[80:83], v[186:189], v[56:59]
	v_mfma_f32_16x16x32_bf16 v[12:15], v[64:67], v[194:197], v[12:15]
	v_mfma_f32_16x16x32_bf16 v[8:11], v[80:83], v[194:197], v[8:11]
	v_mfma_f32_16x16x32_bf16 v[92:95], v[68:71], v[44:47], v[92:95]
	v_mfma_f32_16x16x32_bf16 v[88:91], v[84:87], v[44:47], v[88:91]
	v_mfma_f32_16x16x32_bf16 v[76:79], v[68:71], v[52:55], v[76:79]
	v_mfma_f32_16x16x32_bf16 v[72:75], v[84:87], v[52:55], v[72:75]
	v_mfma_f32_16x16x32_bf16 v[60:63], v[68:71], v[190:193], v[60:63]
	v_mfma_f32_16x16x32_bf16 v[56:59], v[84:87], v[190:193], v[56:59]
	v_mfma_f32_16x16x32_bf16 v[12:15], v[68:71], v[198:201], v[12:15]
	v_mfma_f32_16x16x32_bf16 v[8:11], v[84:87], v[198:201], v[8:11]
	s_barrier
	s_add_u32 s6, s6, 0x40080
	s_addc_u32 s7, s7, 0
	s_add_i32 s8, s8, s33
	v_lshl_add_u64 v[64:65], s[6:7], 0, v[166:167]
	s_mov_b32 m0, s8
	s_nop 0
	global_load_lds_dwordx4 v[64:65], off
	v_lshl_add_u64 v[64:65], s[6:7], 0, v[162:163]
	s_add_i32 m0, s8, 0x2000
	s_nop 0
	global_load_lds_dwordx4 v[64:65], off
	s_waitcnt vmcnt(6)
	s_barrier
	v_mfma_f32_16x16x32_bf16 v[16:19], v[210:213], v[40:43], v[16:19]
	v_mfma_f32_16x16x32_bf16 v[84:87], v[214:217], v[44:47], v[16:19]
	v_mfma_f32_16x16x32_bf16 v[16:19], v[238:241], v[40:43], v[20:23]
	v_mfma_f32_16x16x32_bf16 v[80:83], v[242:245], v[44:47], v[16:19]
	v_mfma_f32_16x16x32_bf16 v[16:19], v[210:213], v[48:51], v[24:27]
	v_mfma_f32_16x16x32_bf16 v[68:71], v[214:217], v[52:55], v[16:19]
	v_mfma_f32_16x16x32_bf16 v[16:19], v[238:241], v[48:51], v[28:31]
	v_mfma_f32_16x16x32_bf16 v[64:67], v[242:245], v[52:55], v[16:19]
	v_mfma_f32_16x16x32_bf16 v[16:19], v[210:213], v[186:189], v[36:39]
	v_mfma_f32_16x16x32_bf16 v[36:39], v[214:217], v[190:193], v[16:19]
	v_mfma_f32_16x16x32_bf16 v[16:19], v[238:241], v[186:189], v[32:35]
	v_mfma_f32_16x16x32_bf16 v[4:7], v[210:213], v[194:197], v[4:7]
	v_mfma_f32_16x16x32_bf16 v[0:3], v[238:241], v[194:197], v[0:3]
	v_mfma_f32_16x16x32_bf16 v[32:35], v[242:245], v[190:193], v[16:19]
	v_mfma_f32_16x16x32_bf16 v[4:7], v[214:217], v[198:201], v[4:7]
	v_mfma_f32_16x16x32_bf16 v[0:3], v[242:245], v[198:201], v[0:3]
	s_add_i32 s34, s34, 2
	s_add_u32 s4, s4, 0x100
	s_addc_u32 s5, s5, 0
	s_add_u32 s30, s30, 0x100
	s_addc_u32 s31, s31, 0
	s_cmp_gt_u32 s34, 13
	s_barrier
	s_cbranch_scc0 .LBB0_175
	s_cmp_gt_i32 s28, 1
	s_cselect_b64 s[6:7], -1, 0
	s_cmp_lt_i32 s28, 2
	s_cselect_b64 s[4:5], -1, 0
	s_add_i32 s8, s28, -3
	s_cmp_lt_u32 s8, 2
	s_cselect_b64 s[8:9], -1, 0
	s_lshl_b32 s29, s12, 8
	s_add_i32 s29, s29, s52
	v_or_b32_e32 v196, s29, v179
	s_nop 0
	v_ashrrev_i32_e32 v197, 31, v196
	v_readlane_b32 s72, v253, 63
	v_readlane_b32 s73, v252, 0
	s_or_b64 s[4:5], s[4:5], s[8:9]
	s_and_b32 s8, s29, 0xfc0
	v_lshl_add_u64 v[16:17], v[196:197], 2, s[72:73]
	global_load_dword v204, v[16:17], off
	global_load_dword v200, v[16:17], off offset:64
	global_load_dword v198, v[16:17], off offset:128
	global_load_dword v194, v[16:17], off offset:192
	global_load_dword v192, v[16:17], off offset:512
	global_load_dword v190, v[16:17], off offset:576
	global_load_dword v188, v[16:17], off offset:640
	global_load_dword v186, v[16:17], off offset:704
	v_or_b32_e32 v16, s8, v179
	v_readlane_b32 s8, v252, 45
	v_readlane_b32 s9, v252, 46
	s_and_b64 s[62:63], s[8:9], s[4:5]
	v_cndmask_b32_e64 v17, 0, 1, s[62:63]
	v_readlane_b32 s68, v253, 59
	v_readlane_b32 s69, v253, 60
	v_readlane_b32 s76, v252, 3
	v_readlane_b32 s77, v252, 4
	v_readlane_b32 s78, v252, 5
	v_readlane_b32 s79, v252, 6
	v_cmp_ne_u32_e64 s[4:5], 1, v17
	s_andn2_b64 vcc, exec, s[62:63]
	v_lshlrev_b32_e32 v187, 6, v16
	s_nop 6
	s_cbranch_vccnz .LBB0_178
	global_load_dwordx4 v[40:43], v187, s[76:77] offset:48
	global_load_dwordx4 v[44:47], v187, s[76:77] offset:32
	global_load_dwordx4 v[48:51], v187, s[76:77] offset:16
	global_load_dwordx4 v[52:55], v187, s[76:77]
	global_load_dwordx4 v[16:19], v187, s[76:77] offset:1072
	global_load_dwordx4 v[20:23], v187, s[76:77] offset:1056
	global_load_dwordx4 v[24:27], v187, s[76:77] offset:1040
	global_load_dwordx4 v[28:31], v187, s[76:77] offset:1024

.LBB0_612:
	ds_read_b128 v[188:191], v162
	ds_read_b128 v[192:195], v162 offset:1024
	ds_read_b128 v[196:199], v162 offset:2048
	ds_read_b128 v[200:203], v162 offset:3072
	ds_read_b128 v[204:207], v162 offset:4096
	ds_read_b128 v[208:211], v162 offset:5120
	ds_read_b128 v[212:215], v162 offset:6144
	ds_read_b128 v[216:219], v162 offset:7168
	ds_read_b128 v[164:167], v159
	ds_read_b128 v[168:171], v159 offset:1024
	ds_read_b128 v[180:183], v159 offset:2048
	ds_read_b128 v[184:187], v159 offset:3072
	s_add_u32 s24, s22, 0xfffc0080
	s_addc_u32 s25, s23, -1
	s_cmp_eq_u32 s45, 4
	s_cselect_b32 s35, s9, s25
	s_cselect_b32 s34, s41, s24
	s_cselect_b32 s25, s7, s44
	s_cselect_b32 s24, s42, s43
	v_lshl_add_u64 v[172:173], s[22:23], 0, v[154:155]
	s_add_i32 m0, s3, 0xc000
	s_nop 0
	global_load_lds_dwordx4 v[172:173], off
	v_lshl_add_u64 v[172:173], s[22:23], 0, v[156:157]
	s_add_i32 m0, s3, 0xe000
	s_nop 0
	global_load_lds_dwordx4 v[172:173], off
	s_waitcnt lgkmcnt(0)
	s_barrier
	v_mfma_f32_16x16x32_bf16 v[124:127], v[164:167], v[188:191], v[124:127]
	v_mfma_f32_16x16x32_bf16 v[120:123], v[180:183], v[188:191], v[120:123]
	v_mfma_f32_16x16x32_bf16 v[116:119], v[164:167], v[196:199], v[116:119]
	v_mfma_f32_16x16x32_bf16 v[112:115], v[180:183], v[196:199], v[112:115]
	v_mfma_f32_16x16x32_bf16 v[108:111], v[164:167], v[204:207], v[108:111]
	v_mfma_f32_16x16x32_bf16 v[100:103], v[180:183], v[204:207], v[100:103]
	v_mfma_f32_16x16x32_bf16 v[92:95], v[164:167], v[212:215], v[92:95]
	v_mfma_f32_16x16x32_bf16 v[84:87], v[180:183], v[212:215], v[84:87]
	v_mfma_f32_16x16x32_bf16 v[124:127], v[168:171], v[192:195], v[124:127]
	v_mfma_f32_16x16x32_bf16 v[120:123], v[184:187], v[192:195], v[120:123]
	v_mfma_f32_16x16x32_bf16 v[116:119], v[168:171], v[200:203], v[116:119]
	v_mfma_f32_16x16x32_bf16 v[112:115], v[184:187], v[200:203], v[112:115]
	v_mfma_f32_16x16x32_bf16 v[108:111], v[168:171], v[208:211], v[108:111]
	v_mfma_f32_16x16x32_bf16 v[100:103], v[184:187], v[208:211], v[100:103]
	v_mfma_f32_16x16x32_bf16 v[92:95], v[168:171], v[216:219], v[92:95]
	v_mfma_f32_16x16x32_bf16 v[84:87], v[184:187], v[216:219], v[84:87]
	s_barrier
	s_add_i32 s52, s31, s19
	v_lshl_add_u64 v[172:173], s[24:25], 0, v[130:131]
	s_mov_b32 m0, s52
	ds_read_b128 v[232:235], v163
	ds_read_b128 v[236:239], v163 offset:1024
	ds_read_b128 v[240:243], v163 offset:2048
	ds_read_b128 v[244:247], v163 offset:3072
	global_load_lds_dwordx4 v[172:173], off
	v_lshl_add_u64 v[176:177], s[24:25], 0, v[134:135]
	s_add_i32 m0, s52, 0x2000
	s_nop 0
	global_load_lds_dwordx4 v[176:177], off
	s_barrier
	s_waitcnt lgkmcnt(0)
	v_mfma_f32_16x16x32_bf16 v[104:107], v[232:235], v[188:191], v[104:107]
	v_mfma_f32_16x16x32_bf16 v[96:99], v[240:243], v[188:191], v[96:99]
	v_mfma_f32_16x16x32_bf16 v[88:91], v[232:235], v[196:199], v[88:91]
	v_mfma_f32_16x16x32_bf16 v[80:83], v[240:243], v[196:199], v[80:83]
	v_mfma_f32_16x16x32_bf16 v[76:79], v[232:235], v[204:207], v[76:79]
	v_mfma_f32_16x16x32_bf16 v[72:75], v[240:243], v[204:207], v[72:75]
	v_mfma_f32_16x16x32_bf16 v[68:71], v[232:235], v[212:215], v[68:71]
	v_mfma_f32_16x16x32_bf16 v[64:67], v[240:243], v[212:215], v[64:67]
	v_mfma_f32_16x16x32_bf16 v[104:107], v[236:239], v[192:195], v[104:107]
	v_mfma_f32_16x16x32_bf16 v[96:99], v[244:247], v[192:195], v[96:99]
	v_mfma_f32_16x16x32_bf16 v[88:91], v[236:239], v[200:203], v[88:91]
	v_mfma_f32_16x16x32_bf16 v[80:83], v[244:247], v[200:203], v[80:83]
	v_mfma_f32_16x16x32_bf16 v[76:79], v[236:239], v[208:211], v[76:79]
	v_mfma_f32_16x16x32_bf16 v[72:75], v[244:247], v[208:211], v[72:75]
	v_mfma_f32_16x16x32_bf16 v[68:71], v[236:239], v[216:219], v[68:71]
	v_mfma_f32_16x16x32_bf16 v[64:67], v[244:247], v[216:219], v[64:67]
	s_mov_b32 m0, s3
	v_lshl_add_u64 v[248:249], s[34:35], 0, v[128:129]
	s_barrier
	ds_read_b128 v[188:191], v162 offset:16384
	ds_read_b128 v[192:195], v162 offset:17408
	ds_read_b128 v[196:199], v162 offset:18432
	ds_read_b128 v[200:203], v162 offset:19456
	ds_read_b128 v[204:207], v162 offset:20480
	ds_read_b128 v[208:211], v162 offset:21504
	ds_read_b128 v[212:215], v162 offset:22528
	ds_read_b128 v[216:219], v162 offset:23552
	global_load_lds_dwordx4 v[248:249], off
	v_lshl_add_u64 v[250:251], s[34:35], 0, v[132:133]
	s_mov_b32 m0, s20
	s_nop 0
	global_load_lds_dwordx4 v[250:251], off
	s_barrier
	s_waitcnt lgkmcnt(0)
	v_mfma_f32_16x16x32_bf16 v[60:63], v[164:167], v[188:191], v[60:63]
	v_mfma_f32_16x16x32_bf16 v[56:59], v[180:183], v[188:191], v[56:59]
	v_mfma_f32_16x16x32_bf16 v[52:55], v[164:167], v[196:199], v[52:55]
	v_mfma_f32_16x16x32_bf16 v[48:51], v[180:183], v[196:199], v[48:51]
	v_mfma_f32_16x16x32_bf16 v[44:47], v[164:167], v[204:207], v[44:47]
	v_mfma_f32_16x16x32_bf16 v[40:43], v[180:183], v[204:207], v[40:43]
	v_mfma_f32_16x16x32_bf16 v[28:31], v[164:167], v[212:215], v[28:31]
	v_mfma_f32_16x16x32_bf16 v[24:27], v[180:183], v[212:215], v[24:27]
	v_mfma_f32_16x16x32_bf16 v[60:63], v[168:171], v[192:195], v[60:63]
	v_mfma_f32_16x16x32_bf16 v[56:59], v[184:187], v[192:195], v[56:59]
	v_mfma_f32_16x16x32_bf16 v[52:55], v[168:171], v[200:203], v[52:55]
	v_mfma_f32_16x16x32_bf16 v[48:51], v[184:187], v[200:203], v[48:51]
	v_mfma_f32_16x16x32_bf16 v[44:47], v[168:171], v[208:211], v[44:47]
	v_mfma_f32_16x16x32_bf16 v[40:43], v[184:187], v[208:211], v[40:43]
	v_mfma_f32_16x16x32_bf16 v[28:31], v[168:171], v[216:219], v[28:31]
	v_mfma_f32_16x16x32_bf16 v[24:27], v[184:187], v[216:219], v[24:27]
	s_barrier
	s_add_u32 s52, s24, 0x80000
	s_addc_u32 s53, s25, 0
	s_add_i32 s54, s33, s19
	v_lshl_add_u64 v[164:165], s[52:53], 0, v[130:131]
	s_mov_b32 m0, s54
	s_nop 0
	global_load_lds_dwordx4 v[164:165], off
	v_lshl_add_u64 v[164:165], s[52:53], 0, v[134:135]
	s_add_i32 m0, s54, 0x2000
	s_nop 0
	global_load_lds_dwordx4 v[164:165], off
	s_waitcnt vmcnt(6)
	s_barrier
	v_mfma_f32_16x16x32_bf16 v[36:39], v[232:235], v[188:191], v[36:39]
	v_mfma_f32_16x16x32_bf16 v[32:35], v[240:243], v[188:191], v[32:35]
	v_mfma_f32_16x16x32_bf16 v[20:23], v[232:235], v[196:199], v[20:23]
	v_mfma_f32_16x16x32_bf16 v[16:19], v[240:243], v[196:199], v[16:19]
	v_mfma_f32_16x16x32_bf16 v[12:15], v[232:235], v[204:207], v[12:15]
	v_mfma_f32_16x16x32_bf16 v[8:11], v[240:243], v[204:207], v[8:11]
	v_mfma_f32_16x16x32_bf16 v[4:7], v[232:235], v[212:215], v[4:7]
	v_mfma_f32_16x16x32_bf16 v[0:3], v[240:243], v[212:215], v[0:3]
	v_mfma_f32_16x16x32_bf16 v[36:39], v[236:239], v[192:195], v[36:39]
	v_mfma_f32_16x16x32_bf16 v[32:35], v[244:247], v[192:195], v[32:35]
	v_mfma_f32_16x16x32_bf16 v[20:23], v[236:239], v[200:203], v[20:23]
	v_mfma_f32_16x16x32_bf16 v[16:19], v[244:247], v[200:203], v[16:19]
	v_mfma_f32_16x16x32_bf16 v[12:15], v[236:239], v[208:211], v[12:15]
	v_mfma_f32_16x16x32_bf16 v[8:11], v[244:247], v[208:211], v[8:11]
	v_mfma_f32_16x16x32_bf16 v[4:7], v[236:239], v[216:219], v[4:7]
	v_mfma_f32_16x16x32_bf16 v[0:3], v[244:247], v[216:219], v[0:3]
	s_add_i32 s52, 0, 0x18000
	v_add_u32_e32 v174, s52, v158
	s_barrier
	ds_read_b128 v[188:191], v162 offset:32768
	ds_read_b128 v[192:195], v162 offset:33792
	ds_read_b128 v[196:199], v162 offset:34816
	ds_read_b128 v[200:203], v162 offset:35840
	ds_read_b128 v[204:207], v162 offset:36864
	ds_read_b128 v[208:211], v162 offset:37888
	ds_read_b128 v[212:215], v162 offset:38912
	ds_read_b128 v[216:219], v162 offset:39936
	ds_read_b128 v[164:167], v174
	ds_read_b128 v[168:171], v174 offset:1024
	ds_read_b128 v[180:183], v174 offset:2048
	ds_read_b128 v[184:187], v174 offset:3072
	s_add_u32 s34, s34, 0x40000
	s_addc_u32 s35, s35, 0
	s_mov_b32 m0, s21
	v_lshl_add_u64 v[232:233], s[34:35], 0, v[128:129]
	global_load_lds_dwordx4 v[232:233], off
	v_lshl_add_u64 v[232:233], s[34:35], 0, v[132:133]
	s_mov_b32 m0, s27
	s_nop 0
	global_load_lds_dwordx4 v[232:233], off
	s_waitcnt lgkmcnt(0)
	s_barrier
	v_mfma_f32_16x16x32_bf16 v[124:127], v[164:167], v[188:191], v[124:127]
	v_mfma_f32_16x16x32_bf16 v[120:123], v[180:183], v[188:191], v[120:123]
	v_mfma_f32_16x16x32_bf16 v[116:119], v[164:167], v[196:199], v[116:119]
	v_mfma_f32_16x16x32_bf16 v[112:115], v[180:183], v[196:199], v[112:115]
	v_mfma_f32_16x16x32_bf16 v[108:111], v[164:167], v[204:207], v[108:111]
	v_mfma_f32_16x16x32_bf16 v[100:103], v[180:183], v[204:207], v[100:103]
	v_mfma_f32_16x16x32_bf16 v[92:95], v[164:167], v[212:215], v[92:95]
	v_mfma_f32_16x16x32_bf16 v[84:87], v[180:183], v[212:215], v[84:87]
	v_mfma_f32_16x16x32_bf16 v[124:127], v[168:171], v[192:195], v[124:127]
	v_mfma_f32_16x16x32_bf16 v[120:123], v[184:187], v[192:195], v[120:123]
	v_mfma_f32_16x16x32_bf16 v[116:119], v[168:171], v[200:203], v[116:119]
	v_mfma_f32_16x16x32_bf16 v[112:115], v[184:187], v[200:203], v[112:115]
	v_mfma_f32_16x16x32_bf16 v[108:111], v[168:171], v[208:211], v[108:111]
	v_mfma_f32_16x16x32_bf16 v[100:103], v[184:187], v[208:211], v[100:103]
	v_mfma_f32_16x16x32_bf16 v[92:95], v[168:171], v[216:219], v[92:95]
	v_mfma_f32_16x16x32_bf16 v[84:87], v[184:187], v[216:219], v[84:87]
	s_barrier
	s_add_i32 s34, 0, 0x1c000
	s_add_i32 s35, s52, s19
	v_add_u32_e32 v174, s34, v158
	v_lshl_add_u64 v[172:173], v[172:173], 0, s[4:5]
	s_mov_b32 m0, s35
	ds_read_b128 v[232:235], v174
	ds_read_b128 v[236:239], v174 offset:1024
	ds_read_b128 v[240:243], v174 offset:2048
	ds_read_b128 v[244:247], v174 offset:3072
	global_load_lds_dwordx4 v[172:173], off
	v_lshl_add_u64 v[172:173], v[176:177], 0, s[4:5]
	s_add_i32 m0, s35, 0x2000
	s_nop 0
	global_load_lds_dwordx4 v[172:173], off
	s_barrier
	s_waitcnt lgkmcnt(0)
	v_mfma_f32_16x16x32_bf16 v[104:107], v[232:235], v[188:191], v[104:107]
	v_mfma_f32_16x16x32_bf16 v[96:99], v[240:243], v[188:191], v[96:99]
	v_mfma_f32_16x16x32_bf16 v[88:91], v[232:235], v[196:199], v[88:91]
	v_mfma_f32_16x16x32_bf16 v[80:83], v[240:243], v[196:199], v[80:83]
	v_mfma_f32_16x16x32_bf16 v[76:79], v[232:235], v[204:207], v[76:79]
	v_mfma_f32_16x16x32_bf16 v[72:75], v[240:243], v[204:207], v[72:75]
	v_mfma_f32_16x16x32_bf16 v[68:71], v[232:235], v[212:215], v[68:71]
	v_mfma_f32_16x16x32_bf16 v[64:67], v[240:243], v[212:215], v[64:67]
	v_mfma_f32_16x16x32_bf16 v[104:107], v[236:239], v[192:195], v[104:107]
	v_mfma_f32_16x16x32_bf16 v[96:99], v[244:247], v[192:195], v[96:99]
	v_mfma_f32_16x16x32_bf16 v[88:91], v[236:239], v[200:203], v[88:91]
	v_mfma_f32_16x16x32_bf16 v[80:83], v[244:247], v[200:203], v[80:83]
	v_mfma_f32_16x16x32_bf16 v[76:79], v[236:239], v[208:211], v[76:79]
	v_mfma_f32_16x16x32_bf16 v[72:75], v[244:247], v[208:211], v[72:75]
	v_mfma_f32_16x16x32_bf16 v[68:71], v[236:239], v[216:219], v[68:71]
	v_mfma_f32_16x16x32_bf16 v[64:67], v[244:247], v[216:219], v[64:67]
	s_mov_b32 m0, s29
	v_lshl_add_u64 v[172:173], v[248:249], 0, s[4:5]
	s_barrier
	ds_read_b128 v[188:191], v162 offset:49152
	ds_read_b128 v[192:195], v162 offset:50176
	ds_read_b128 v[196:199], v162 offset:51200
	ds_read_b128 v[200:203], v162 offset:52224
	ds_read_b128 v[204:207], v162 offset:53248
	ds_read_b128 v[208:211], v162 offset:54272
	ds_read_b128 v[212:215], v162 offset:55296
	ds_read_b128 v[216:219], v162 offset:56320
	global_load_lds_dwordx4 v[172:173], off
	v_lshl_add_u64 v[172:173], v[250:251], 0, s[4:5]
	s_mov_b32 m0, s30
	s_nop 0
	global_load_lds_dwordx4 v[172:173], off
	s_barrier
	s_waitcnt lgkmcnt(0)
	v_mfma_f32_16x16x32_bf16 v[60:63], v[164:167], v[188:191], v[60:63]
	v_mfma_f32_16x16x32_bf16 v[56:59], v[180:183], v[188:191], v[56:59]
	v_mfma_f32_16x16x32_bf16 v[52:55], v[164:167], v[196:199], v[52:55]
	v_mfma_f32_16x16x32_bf16 v[48:51], v[180:183], v[196:199], v[48:51]
	v_mfma_f32_16x16x32_bf16 v[44:47], v[164:167], v[204:207], v[44:47]
	v_mfma_f32_16x16x32_bf16 v[40:43], v[180:183], v[204:207], v[40:43]
	v_mfma_f32_16x16x32_bf16 v[28:31], v[164:167], v[212:215], v[28:31]
	v_mfma_f32_16x16x32_bf16 v[24:27], v[180:183], v[212:215], v[24:27]
	v_mfma_f32_16x16x32_bf16 v[60:63], v[168:171], v[192:195], v[60:63]
	v_mfma_f32_16x16x32_bf16 v[56:59], v[184:187], v[192:195], v[56:59]
	v_mfma_f32_16x16x32_bf16 v[52:55], v[168:171], v[200:203], v[52:55]
	v_mfma_f32_16x16x32_bf16 v[48:51], v[184:187], v[200:203], v[48:51]
	v_mfma_f32_16x16x32_bf16 v[44:47], v[168:171], v[208:211], v[44:47]
	v_mfma_f32_16x16x32_bf16 v[40:43], v[184:187], v[208:211], v[40:43]
	v_mfma_f32_16x16x32_bf16 v[28:31], v[168:171], v[216:219], v[28:31]
	v_mfma_f32_16x16x32_bf16 v[24:27], v[184:187], v[216:219], v[24:27]
	s_barrier
	s_add_u32 s24, s24, 0x80080
	s_addc_u32 s25, s25, 0
	s_add_i32 s34, s34, s19
	v_lshl_add_u64 v[164:165], s[24:25], 0, v[130:131]
	s_mov_b32 m0, s34
	s_nop 0
	global_load_lds_dwordx4 v[164:165], off
	v_lshl_add_u64 v[164:165], s[24:25], 0, v[134:135]
	s_add_i32 m0, s34, 0x2000
	s_nop 0
	global_load_lds_dwordx4 v[164:165], off
	s_waitcnt vmcnt(6)
	s_barrier
	v_mfma_f32_16x16x32_bf16 v[36:39], v[232:235], v[188:191], v[36:39]
	v_mfma_f32_16x16x32_bf16 v[32:35], v[240:243], v[188:191], v[32:35]
	v_mfma_f32_16x16x32_bf16 v[20:23], v[232:235], v[196:199], v[20:23]
	v_mfma_f32_16x16x32_bf16 v[16:19], v[240:243], v[196:199], v[16:19]
	v_mfma_f32_16x16x32_bf16 v[12:15], v[232:235], v[204:207], v[12:15]
	v_mfma_f32_16x16x32_bf16 v[8:11], v[240:243], v[204:207], v[8:11]
	v_mfma_f32_16x16x32_bf16 v[4:7], v[232:235], v[212:215], v[4:7]
	v_mfma_f32_16x16x32_bf16 v[0:3], v[240:243], v[212:215], v[0:3]
	v_mfma_f32_16x16x32_bf16 v[36:39], v[236:239], v[192:195], v[36:39]
	v_mfma_f32_16x16x32_bf16 v[32:35], v[244:247], v[192:195], v[32:35]
	v_mfma_f32_16x16x32_bf16 v[20:23], v[236:239], v[200:203], v[20:23]
	v_mfma_f32_16x16x32_bf16 v[16:19], v[244:247], v[200:203], v[16:19]
	v_mfma_f32_16x16x32_bf16 v[12:15], v[236:239], v[208:211], v[12:15]
	v_mfma_f32_16x16x32_bf16 v[8:11], v[244:247], v[208:211], v[8:11]
	v_mfma_f32_16x16x32_bf16 v[4:7], v[236:239], v[216:219], v[4:7]
	v_mfma_f32_16x16x32_bf16 v[0:3], v[244:247], v[216:219], v[0:3]
	s_add_i32 s45, s45, 2
	s_add_u32 s22, s22, 0x100
	s_addc_u32 s23, s23, 0
	s_add_u32 s43, s43, 0x100
	s_addc_u32 s44, s44, 0
	s_cmp_gt_u32 s45, 5
	s_barrier
	s_cbranch_scc0 .LBB0_612
	s_lshl_b32 s7, s26, 2
	s_and_b32 s7, s7, 0x7fffffe0
	s_add_i32 s22, s7, s2
	s_ashr_i32 s23, s22, 31
	s_lshl_b64 s[22:23], s[22:23], 18
	s_add_u32 s22, s82, s22
	s_addc_u32 s23, s83, s23
	v_lshl_add_u64 v[164:165], s[22:23], 0, v[138:139]
	v_lshl_add_u64 v[164:165], v[164:165], 0, v[136:137]
	global_store_dwordx4 v[164:165], v[124:127], off
	global_store_dwordx4 v[164:165], v[120:123], off offset:16
	global_store_dwordx4 v[164:165], v[104:107], off offset:512
	global_store_dwordx4 v[164:165], v[96:99], off offset:528
	s_and_b64 vcc, exec, s[10:11]
	s_mov_b32 s26, s40
	v_lshl_add_u64 v[96:97], s[22:23], 0, v[140:141]
	v_lshl_add_u64 v[96:97], v[96:97], 0, v[136:137]
	global_store_dwordx4 v[96:97], v[116:119], off
	global_store_dwordx4 v[96:97], v[112:115], off offset:16
	global_store_dwordx4 v[96:97], v[88:91], off offset:512
	global_store_dwordx4 v[96:97], v[80:83], off offset:528
	s_mov_b32 s2, s8
	s_mov_b64 s[24:25], s[16:17]
	v_lshl_add_u64 v[80:81], s[22:23], 0, v[142:143]
	v_lshl_add_u64 v[80:81], v[80:81], 0, v[136:137]
	global_store_dwordx4 v[80:81], v[108:111], off
	global_store_dwordx4 v[80:81], v[100:103], off offset:16
	global_store_dwordx4 v[80:81], v[76:79], off offset:512
	global_store_dwordx4 v[80:81], v[72:75], off offset:528
	s_nop 1
	v_lshl_add_u64 v[72:73], s[22:23], 0, v[144:145]
	v_lshl_add_u64 v[72:73], v[72:73], 0, v[136:137]
	global_store_dwordx4 v[72:73], v[92:95], off
	global_store_dwordx4 v[72:73], v[84:87], off offset:16
	global_store_dwordx4 v[72:73], v[68:71], off offset:512
	global_store_dwordx4 v[72:73], v[64:67], off offset:528
	s_nop 1
	v_lshl_add_u64 v[64:65], s[22:23], 0, v[146:147]
	v_lshl_add_u64 v[64:65], v[64:65], 0, v[136:137]
	global_store_dwordx4 v[64:65], v[60:63], off
	global_store_dwordx4 v[64:65], v[56:59], off offset:16
	global_store_dwordx4 v[64:65], v[36:39], off offset:512
	global_store_dwordx4 v[64:65], v[32:35], off offset:528
	s_nop 1
	v_lshl_add_u64 v[32:33], s[22:23], 0, v[148:149]
	v_lshl_add_u64 v[32:33], v[32:33], 0, v[136:137]
	global_store_dwordx4 v[32:33], v[52:55], off
	global_store_dwordx4 v[32:33], v[48:51], off offset:16
	global_store_dwordx4 v[32:33], v[20:23], off offset:512
	global_store_dwordx4 v[32:33], v[16:19], off offset:528
	s_nop 1
	v_lshl_add_u64 v[16:17], s[22:23], 0, v[150:151]
	v_lshl_add_u64 v[16:17], v[16:17], 0, v[136:137]
	global_store_dwordx4 v[16:17], v[44:47], off
	global_store_dwordx4 v[16:17], v[40:43], off offset:16
	global_store_dwordx4 v[16:17], v[12:15], off offset:512
	global_store_dwordx4 v[16:17], v[8:11], off offset:528
	s_nop 1
	v_lshl_add_u64 v[8:9], s[22:23], 0, v[152:153]
	v_lshl_add_u64 v[8:9], v[8:9], 0, v[136:137]
	s_mov_b64 s[22:23], s[14:15]
	global_store_dwordx4 v[8:9], v[28:31], off
	global_store_dwordx4 v[8:9], v[24:27], off offset:16
	global_store_dwordx4 v[8:9], v[4:7], off offset:512
	global_store_dwordx4 v[8:9], v[0:3], off offset:528
	s_cbranch_vccz .LBB0_606
	s_waitcnt vmcnt(0)
	s_cmpk_gt_u32 s18, 0xff
	s_cbranch_scc1 .LBB0_616
	s_barrier

.LBB0_1268:
	ds_read_b128 v[164:167], v150
	ds_read_b128 v[168:171], v150 offset:1024
	ds_read_b128 v[172:175], v150 offset:2048
	ds_read_b128 v[180:183], v150 offset:3072
	ds_read_b128 v[184:187], v150 offset:4096
	ds_read_b128 v[188:191], v150 offset:5120
	ds_read_b128 v[192:195], v150 offset:6144
	ds_read_b128 v[196:199], v150 offset:7168
	ds_read_b128 v[140:143], v149
	ds_read_b128 v[152:155], v149 offset:1024
	ds_read_b128 v[156:159], v149 offset:2048
	ds_read_b128 v[160:163], v149 offset:3072
	s_add_u32 s22, s10, 0xfffe0080
	s_addc_u32 s23, s11, -1
	s_cmp_eq_u32 s44, 4
	s_cselect_b32 s25, s13, s23
	s_cselect_b32 s24, s40, s22
	s_cselect_b32 s23, s15, s43
	s_cselect_b32 s22, s41, s42
	v_lshl_add_u64 v[144:145], s[10:11], 0, v[136:137]
	s_add_i32 m0, s1, 0xc000
	s_nop 0
	global_load_lds_dwordx4 v[144:145], off
	v_lshl_add_u64 v[144:145], s[10:11], 0, v[138:139]
	s_add_i32 m0, s1, 0xe000
	s_nop 0
	global_load_lds_dwordx4 v[144:145], off
	s_waitcnt lgkmcnt(0)
	s_barrier
	v_mfma_f32_16x16x32_bf16 v[124:127], v[140:143], v[164:167], v[124:127]
	v_mfma_f32_16x16x32_bf16 v[120:123], v[156:159], v[164:167], v[120:123]
	v_mfma_f32_16x16x32_bf16 v[112:115], v[140:143], v[172:175], v[112:115]
	v_mfma_f32_16x16x32_bf16 v[104:107], v[156:159], v[172:175], v[104:107]
	v_mfma_f32_16x16x32_bf16 v[96:99], v[140:143], v[184:187], v[96:99]
	v_mfma_f32_16x16x32_bf16 v[88:91], v[156:159], v[184:187], v[88:91]
	v_mfma_f32_16x16x32_bf16 v[80:83], v[140:143], v[192:195], v[80:83]
	v_mfma_f32_16x16x32_bf16 v[72:75], v[156:159], v[192:195], v[72:75]
	v_mfma_f32_16x16x32_bf16 v[124:127], v[152:155], v[168:171], v[124:127]
	v_mfma_f32_16x16x32_bf16 v[120:123], v[160:163], v[168:171], v[120:123]
	v_mfma_f32_16x16x32_bf16 v[112:115], v[152:155], v[180:183], v[112:115]
	v_mfma_f32_16x16x32_bf16 v[104:107], v[160:163], v[180:183], v[104:107]
	v_mfma_f32_16x16x32_bf16 v[96:99], v[152:155], v[188:191], v[96:99]
	v_mfma_f32_16x16x32_bf16 v[88:91], v[160:163], v[188:191], v[88:91]
	v_mfma_f32_16x16x32_bf16 v[80:83], v[152:155], v[196:199], v[80:83]
	v_mfma_f32_16x16x32_bf16 v[72:75], v[160:163], v[196:199], v[72:75]
	s_barrier
	s_add_i32 s45, s35, s27
	v_lshl_add_u64 v[144:145], s[22:23], 0, v[132:133]
	s_mov_b32 m0, s45
	ds_read_b128 v[200:203], v151
	ds_read_b128 v[204:207], v151 offset:1024
	ds_read_b128 v[208:211], v151 offset:2048
	ds_read_b128 v[212:215], v151 offset:3072
	global_load_lds_dwordx4 v[144:145], off
	v_lshl_add_u64 v[176:177], s[22:23], 0, v[128:129]
	s_add_i32 m0, s45, 0x2000
	s_nop 0
	global_load_lds_dwordx4 v[176:177], off
	s_barrier
	s_waitcnt lgkmcnt(0)
	v_mfma_f32_16x16x32_bf16 v[116:119], v[200:203], v[164:167], v[116:119]
	v_mfma_f32_16x16x32_bf16 v[108:111], v[208:211], v[164:167], v[108:111]
	v_mfma_f32_16x16x32_bf16 v[100:103], v[200:203], v[172:175], v[100:103]
	v_mfma_f32_16x16x32_bf16 v[92:95], v[208:211], v[172:175], v[92:95]
	v_mfma_f32_16x16x32_bf16 v[84:87], v[200:203], v[184:187], v[84:87]
	v_mfma_f32_16x16x32_bf16 v[76:79], v[208:211], v[184:187], v[76:79]
	v_mfma_f32_16x16x32_bf16 v[68:71], v[200:203], v[192:195], v[68:71]
	v_mfma_f32_16x16x32_bf16 v[64:67], v[208:211], v[192:195], v[64:67]
	v_mfma_f32_16x16x32_bf16 v[116:119], v[204:207], v[168:171], v[116:119]
	v_mfma_f32_16x16x32_bf16 v[108:111], v[212:215], v[168:171], v[108:111]
	v_mfma_f32_16x16x32_bf16 v[100:103], v[204:207], v[180:183], v[100:103]
	v_mfma_f32_16x16x32_bf16 v[92:95], v[212:215], v[180:183], v[92:95]
	v_mfma_f32_16x16x32_bf16 v[84:87], v[204:207], v[188:191], v[84:87]
	v_mfma_f32_16x16x32_bf16 v[76:79], v[212:215], v[188:191], v[76:79]
	v_mfma_f32_16x16x32_bf16 v[68:71], v[204:207], v[196:199], v[68:71]
	v_mfma_f32_16x16x32_bf16 v[64:67], v[212:215], v[196:199], v[64:67]
	s_mov_b32 m0, s1
	v_lshl_add_u64 v[216:217], s[24:25], 0, v[134:135]
	s_barrier
	ds_read_b128 v[164:167], v150 offset:16384
	ds_read_b128 v[168:171], v150 offset:17408
	ds_read_b128 v[172:175], v150 offset:18432
	ds_read_b128 v[180:183], v150 offset:19456
	ds_read_b128 v[184:187], v150 offset:20480
	ds_read_b128 v[188:191], v150 offset:21504
	ds_read_b128 v[192:195], v150 offset:22528
	ds_read_b128 v[196:199], v150 offset:23552
	global_load_lds_dwordx4 v[216:217], off
	v_lshl_add_u64 v[218:219], s[24:25], 0, v[130:131]
	s_mov_b32 m0, s7
	s_nop 0
	global_load_lds_dwordx4 v[218:219], off
	s_barrier
	s_waitcnt lgkmcnt(0)
	v_mfma_f32_16x16x32_bf16 v[60:63], v[140:143], v[164:167], v[60:63]
	v_mfma_f32_16x16x32_bf16 v[56:59], v[156:159], v[164:167], v[56:59]
	v_mfma_f32_16x16x32_bf16 v[48:51], v[140:143], v[172:175], v[48:51]
	v_mfma_f32_16x16x32_bf16 v[40:43], v[156:159], v[172:175], v[40:43]
	v_mfma_f32_16x16x32_bf16 v[32:35], v[140:143], v[184:187], v[32:35]
	v_mfma_f32_16x16x32_bf16 v[24:27], v[156:159], v[184:187], v[24:27]
	v_mfma_f32_16x16x32_bf16 v[16:19], v[140:143], v[192:195], v[16:19]
	v_mfma_f32_16x16x32_bf16 v[8:11], v[156:159], v[192:195], v[8:11]
	v_mfma_f32_16x16x32_bf16 v[60:63], v[152:155], v[168:171], v[60:63]
	v_mfma_f32_16x16x32_bf16 v[56:59], v[160:163], v[168:171], v[56:59]
	v_mfma_f32_16x16x32_bf16 v[48:51], v[152:155], v[180:183], v[48:51]
	v_mfma_f32_16x16x32_bf16 v[40:43], v[160:163], v[180:183], v[40:43]
	v_mfma_f32_16x16x32_bf16 v[32:35], v[152:155], v[188:191], v[32:35]
	v_mfma_f32_16x16x32_bf16 v[24:27], v[160:163], v[188:191], v[24:27]
	v_mfma_f32_16x16x32_bf16 v[16:19], v[152:155], v[196:199], v[16:19]
	v_mfma_f32_16x16x32_bf16 v[8:11], v[160:163], v[196:199], v[8:11]
	s_barrier
	s_add_u32 s46, s22, 0x20000
	s_addc_u32 s47, s23, 0
	s_add_i32 s45, s36, s27
	v_lshl_add_u64 v[140:141], s[46:47], 0, v[132:133]
	s_mov_b32 m0, s45
	s_nop 0
	global_load_lds_dwordx4 v[140:141], off
	v_lshl_add_u64 v[140:141], s[46:47], 0, v[128:129]
	s_add_i32 m0, s45, 0x2000
	s_nop 0
	global_load_lds_dwordx4 v[140:141], off
	s_waitcnt vmcnt(6)
	s_barrier
	v_mfma_f32_16x16x32_bf16 v[52:55], v[200:203], v[164:167], v[52:55]
	v_mfma_f32_16x16x32_bf16 v[44:47], v[208:211], v[164:167], v[44:47]
	v_mfma_f32_16x16x32_bf16 v[36:39], v[200:203], v[172:175], v[36:39]
	v_mfma_f32_16x16x32_bf16 v[28:31], v[208:211], v[172:175], v[28:31]
	v_mfma_f32_16x16x32_bf16 v[20:23], v[200:203], v[184:187], v[20:23]
	v_mfma_f32_16x16x32_bf16 v[12:15], v[208:211], v[184:187], v[12:15]
	v_mfma_f32_16x16x32_bf16 v[4:7], v[200:203], v[192:195], v[4:7]
	v_mfma_f32_16x16x32_bf16 v[0:3], v[208:211], v[192:195], v[0:3]
	v_mfma_f32_16x16x32_bf16 v[52:55], v[204:207], v[168:171], v[52:55]
	v_mfma_f32_16x16x32_bf16 v[44:47], v[212:215], v[168:171], v[44:47]
	v_mfma_f32_16x16x32_bf16 v[36:39], v[204:207], v[180:183], v[36:39]
	v_mfma_f32_16x16x32_bf16 v[28:31], v[212:215], v[180:183], v[28:31]
	v_mfma_f32_16x16x32_bf16 v[20:23], v[204:207], v[188:191], v[20:23]
	v_mfma_f32_16x16x32_bf16 v[12:15], v[212:215], v[188:191], v[12:15]
	v_mfma_f32_16x16x32_bf16 v[4:7], v[204:207], v[196:199], v[4:7]
	v_mfma_f32_16x16x32_bf16 v[0:3], v[212:215], v[196:199], v[0:3]
	s_add_i32 s45, 0, 0x18000
	v_add_u32_e32 v160, s45, v147
	s_barrier
	ds_read_b128 v[164:167], v150 offset:32768
	ds_read_b128 v[168:171], v150 offset:33792
	ds_read_b128 v[172:175], v150 offset:34816
	ds_read_b128 v[180:183], v150 offset:35840
	ds_read_b128 v[184:187], v150 offset:36864
	ds_read_b128 v[188:191], v150 offset:37888
	ds_read_b128 v[192:195], v150 offset:38912
	ds_read_b128 v[196:199], v150 offset:39936
	ds_read_b128 v[140:143], v160
	ds_read_b128 v[152:155], v160 offset:1024
	ds_read_b128 v[156:159], v160 offset:2048
	ds_read_b128 v[160:163], v160 offset:3072
	s_add_u32 s24, s24, 0x20000
	s_addc_u32 s25, s25, 0
	s_mov_b32 m0, s28
	v_lshl_add_u64 v[200:201], s[24:25], 0, v[134:135]
	global_load_lds_dwordx4 v[200:201], off
	v_lshl_add_u64 v[200:201], s[24:25], 0, v[130:131]
	s_mov_b32 m0, s29
	s_nop 0
	global_load_lds_dwordx4 v[200:201], off
	s_waitcnt lgkmcnt(0)
	s_barrier
	v_mfma_f32_16x16x32_bf16 v[124:127], v[140:143], v[164:167], v[124:127]
	v_mfma_f32_16x16x32_bf16 v[120:123], v[156:159], v[164:167], v[120:123]
	v_mfma_f32_16x16x32_bf16 v[112:115], v[140:143], v[172:175], v[112:115]
	v_mfma_f32_16x16x32_bf16 v[104:107], v[156:159], v[172:175], v[104:107]
	v_mfma_f32_16x16x32_bf16 v[96:99], v[140:143], v[184:187], v[96:99]
	v_mfma_f32_16x16x32_bf16 v[88:91], v[156:159], v[184:187], v[88:91]
	v_mfma_f32_16x16x32_bf16 v[80:83], v[140:143], v[192:195], v[80:83]
	v_mfma_f32_16x16x32_bf16 v[72:75], v[156:159], v[192:195], v[72:75]
	v_mfma_f32_16x16x32_bf16 v[124:127], v[152:155], v[168:171], v[124:127]
	v_mfma_f32_16x16x32_bf16 v[120:123], v[160:163], v[168:171], v[120:123]
	v_mfma_f32_16x16x32_bf16 v[112:115], v[152:155], v[180:183], v[112:115]
	v_mfma_f32_16x16x32_bf16 v[104:107], v[160:163], v[180:183], v[104:107]
	v_mfma_f32_16x16x32_bf16 v[96:99], v[152:155], v[188:191], v[96:99]
	v_mfma_f32_16x16x32_bf16 v[88:91], v[160:163], v[188:191], v[88:91]
	v_mfma_f32_16x16x32_bf16 v[80:83], v[152:155], v[196:199], v[80:83]
	v_mfma_f32_16x16x32_bf16 v[72:75], v[160:163], v[196:199], v[72:75]
	s_barrier
	s_add_i32 s24, 0, 0x1c000
	s_add_i32 s25, s45, s27
	v_add_u32_e32 v179, s24, v147
	v_lshl_add_u64 v[144:145], v[144:145], 0, s[2:3]
	s_mov_b32 m0, s25
	ds_read_b128 v[200:203], v179
	ds_read_b128 v[204:207], v179 offset:1024
	ds_read_b128 v[208:211], v179 offset:2048
	ds_read_b128 v[212:215], v179 offset:3072
	global_load_lds_dwordx4 v[144:145], off
	v_lshl_add_u64 v[144:145], v[176:177], 0, s[2:3]
	s_add_i32 m0, s25, 0x2000
	s_nop 0
	global_load_lds_dwordx4 v[144:145], off
	s_barrier
	s_waitcnt lgkmcnt(0)
	v_mfma_f32_16x16x32_bf16 v[116:119], v[200:203], v[164:167], v[116:119]
	v_mfma_f32_16x16x32_bf16 v[108:111], v[208:211], v[164:167], v[108:111]
	v_mfma_f32_16x16x32_bf16 v[100:103], v[200:203], v[172:175], v[100:103]
	v_mfma_f32_16x16x32_bf16 v[92:95], v[208:211], v[172:175], v[92:95]
	v_mfma_f32_16x16x32_bf16 v[84:87], v[200:203], v[184:187], v[84:87]
	v_mfma_f32_16x16x32_bf16 v[76:79], v[208:211], v[184:187], v[76:79]
	v_mfma_f32_16x16x32_bf16 v[68:71], v[200:203], v[192:195], v[68:71]
	v_mfma_f32_16x16x32_bf16 v[64:67], v[208:211], v[192:195], v[64:67]
	v_mfma_f32_16x16x32_bf16 v[116:119], v[204:207], v[168:171], v[116:119]
	v_mfma_f32_16x16x32_bf16 v[108:111], v[212:215], v[168:171], v[108:111]
	v_mfma_f32_16x16x32_bf16 v[100:103], v[204:207], v[180:183], v[100:103]
	v_mfma_f32_16x16x32_bf16 v[92:95], v[212:215], v[180:183], v[92:95]
	v_mfma_f32_16x16x32_bf16 v[84:87], v[204:207], v[188:191], v[84:87]
	v_mfma_f32_16x16x32_bf16 v[76:79], v[212:215], v[188:191], v[76:79]
	v_mfma_f32_16x16x32_bf16 v[68:71], v[204:207], v[196:199], v[68:71]
	v_mfma_f32_16x16x32_bf16 v[64:67], v[212:215], v[196:199], v[64:67]
	s_mov_b32 m0, s31
	v_lshl_add_u64 v[144:145], v[216:217], 0, s[2:3]
	s_barrier
	ds_read_b128 v[164:167], v150 offset:49152
	ds_read_b128 v[168:171], v150 offset:50176
	ds_read_b128 v[172:175], v150 offset:51200
	ds_read_b128 v[180:183], v150 offset:52224
	ds_read_b128 v[184:187], v150 offset:53248
	ds_read_b128 v[188:191], v150 offset:54272
	ds_read_b128 v[192:195], v150 offset:55296
	ds_read_b128 v[196:199], v150 offset:56320
	global_load_lds_dwordx4 v[144:145], off
	v_lshl_add_u64 v[144:145], v[218:219], 0, s[2:3]
	s_mov_b32 m0, s33
	s_nop 0
	global_load_lds_dwordx4 v[144:145], off
	s_barrier
	s_waitcnt lgkmcnt(0)
	v_mfma_f32_16x16x32_bf16 v[60:63], v[140:143], v[164:167], v[60:63]
	v_mfma_f32_16x16x32_bf16 v[56:59], v[156:159], v[164:167], v[56:59]
	v_mfma_f32_16x16x32_bf16 v[48:51], v[140:143], v[172:175], v[48:51]
	v_mfma_f32_16x16x32_bf16 v[40:43], v[156:159], v[172:175], v[40:43]
	v_mfma_f32_16x16x32_bf16 v[32:35], v[140:143], v[184:187], v[32:35]
	v_mfma_f32_16x16x32_bf16 v[24:27], v[156:159], v[184:187], v[24:27]
	v_mfma_f32_16x16x32_bf16 v[16:19], v[140:143], v[192:195], v[16:19]
	v_mfma_f32_16x16x32_bf16 v[8:11], v[156:159], v[192:195], v[8:11]
	v_mfma_f32_16x16x32_bf16 v[60:63], v[152:155], v[168:171], v[60:63]
	v_mfma_f32_16x16x32_bf16 v[56:59], v[160:163], v[168:171], v[56:59]
	v_mfma_f32_16x16x32_bf16 v[48:51], v[152:155], v[180:183], v[48:51]
	v_mfma_f32_16x16x32_bf16 v[40:43], v[160:163], v[180:183], v[40:43]
	v_mfma_f32_16x16x32_bf16 v[32:35], v[152:155], v[188:191], v[32:35]
	v_mfma_f32_16x16x32_bf16 v[24:27], v[160:163], v[188:191], v[24:27]
	v_mfma_f32_16x16x32_bf16 v[16:19], v[152:155], v[196:199], v[16:19]
	v_mfma_f32_16x16x32_bf16 v[8:11], v[160:163], v[196:199], v[8:11]
	s_barrier
	s_add_u32 s22, s22, 0x20080
	s_addc_u32 s23, s23, 0
	s_add_i32 s24, s24, s27
	v_lshl_add_u64 v[140:141], s[22:23], 0, v[132:133]
	s_mov_b32 m0, s24
	s_nop 0
	global_load_lds_dwordx4 v[140:141], off
	v_lshl_add_u64 v[140:141], s[22:23], 0, v[128:129]
	s_add_i32 m0, s24, 0x2000
	s_nop 0
	global_load_lds_dwordx4 v[140:141], off
	s_waitcnt vmcnt(6)
	s_barrier
	v_mfma_f32_16x16x32_bf16 v[52:55], v[200:203], v[164:167], v[52:55]
	v_mfma_f32_16x16x32_bf16 v[44:47], v[208:211], v[164:167], v[44:47]
	v_mfma_f32_16x16x32_bf16 v[36:39], v[200:203], v[172:175], v[36:39]
	v_mfma_f32_16x16x32_bf16 v[28:31], v[208:211], v[172:175], v[28:31]
	v_mfma_f32_16x16x32_bf16 v[20:23], v[200:203], v[184:187], v[20:23]
	v_mfma_f32_16x16x32_bf16 v[12:15], v[208:211], v[184:187], v[12:15]
	v_mfma_f32_16x16x32_bf16 v[4:7], v[200:203], v[192:195], v[4:7]
	v_mfma_f32_16x16x32_bf16 v[0:3], v[208:211], v[192:195], v[0:3]
	v_mfma_f32_16x16x32_bf16 v[52:55], v[204:207], v[168:171], v[52:55]
	v_mfma_f32_16x16x32_bf16 v[44:47], v[212:215], v[168:171], v[44:47]
	v_mfma_f32_16x16x32_bf16 v[36:39], v[204:207], v[180:183], v[36:39]
	v_mfma_f32_16x16x32_bf16 v[28:31], v[212:215], v[180:183], v[28:31]
	v_mfma_f32_16x16x32_bf16 v[20:23], v[204:207], v[188:191], v[20:23]
	v_mfma_f32_16x16x32_bf16 v[12:15], v[212:215], v[188:191], v[12:15]
	v_mfma_f32_16x16x32_bf16 v[4:7], v[204:207], v[196:199], v[4:7]
	v_mfma_f32_16x16x32_bf16 v[0:3], v[212:215], v[196:199], v[0:3]
	s_add_i32 s44, s44, 2
	s_add_u32 s10, s10, 0x100
	s_addc_u32 s11, s11, 0
	s_add_u32 s42, s42, 0x100
	s_addc_u32 s43, s43, 0
	s_cmp_gt_u32 s44, 5
	s_barrier
	s_cbranch_scc0 .LBB0_1268
	v_lshl_add_u32 v142, s39, 8, v146
	s_nop 0
	v_lshl_or_b32 v140, s38, 8, v148
	v_ashrrev_i32_e32 v143, 31, v142
	s_nop 1
	v_readlane_b32 s46, v252, 13
	v_readlane_b32 s47, v252, 14
	v_ashrrev_i32_e32 v141, 31, v140
	v_lshlrev_b64 v[144:145], 12, v[142:143]
	s_mov_b64 s[42:43], s[46:47]
	v_lshl_add_u64 v[144:145], s[42:43], 0, v[144:145]
	v_lshlrev_b64 v[140:141], 1, v[140:141]
	v_or_b32_e32 v172, 16, v142
	v_lshl_add_u64 v[144:145], v[144:145], 0, v[140:141]
	v_ashrrev_i32_e32 v173, 31, v172
	global_load_dwordx4 v[152:155], v[144:145], off
	global_load_dwordx4 v[156:159], v[144:145], off offset:256
	v_lshlrev_b64 v[144:145], 12, v[172:173]
	v_lshl_add_u64 v[144:145], s[42:43], 0, v[144:145]
	v_lshl_add_u64 v[144:145], v[144:145], 0, v[140:141]
	global_load_dwordx4 v[160:163], v[144:145], off
	global_load_dwordx4 v[164:167], v[144:145], off offset:256
	v_or_b32_e32 v176, 32, v142
	v_ashrrev_i32_e32 v177, 31, v176
	v_lshlrev_b64 v[168:169], 12, v[176:177]
	v_lshl_add_u64 v[168:169], s[42:43], 0, v[168:169]
	v_lshl_add_u64 v[182:183], v[168:169], 0, v[140:141]
	global_load_dwordx4 v[168:171], v[182:183], off
	v_or_b32_e32 v144, 48, v142
	v_ashrrev_i32_e32 v145, 31, v144
	v_lshlrev_b64 v[180:181], 12, v[144:145]
	v_lshlrev_b64 v[174:175], 11, v[142:143]
	v_lshlrev_b64 v[172:173], 11, v[172:173]
	v_lshl_add_u64 v[180:181], s[42:43], 0, v[180:181]
	v_lshl_add_u64 v[174:175], s[82:83], 0, v[174:175]
	v_lshl_add_u64 v[172:173], s[82:83], 0, v[172:173]
	v_lshl_add_u64 v[184:185], v[180:181], 0, v[140:141]
	v_lshl_add_u64 v[188:189], v[174:175], 0, v[140:141]
	v_lshl_add_u64 v[190:191], v[172:173], 0, v[140:141]
	global_load_dwordx4 v[172:175], v[182:183], off offset:256
	s_nop 0
	global_load_dwordx4 v[180:183], v[184:185], off
	s_nop 0
	global_load_dwordx4 v[184:187], v[184:185], off offset:256
	v_add_u32_e32 v234, 0x80, v142
	v_ashrrev_i32_e32 v235, 31, v234
	v_lshlrev_b64 v[236:237], 12, v[234:235]
	v_lshl_add_u64 v[236:237], s[42:43], 0, v[236:237]
	v_lshl_add_u64 v[236:237], v[236:237], 0, v[140:141]
	global_load_dwordx4 v[200:203], v[236:237], off
	global_load_dwordx4 v[204:207], v[236:237], off offset:256
	v_add_u32_e32 v234, 0x90, v142
	v_ashrrev_i32_e32 v235, 31, v234
	v_lshlrev_b64 v[236:237], 12, v[234:235]
	v_lshl_add_u64 v[236:237], s[42:43], 0, v[236:237]
	v_lshl_add_u64 v[236:237], v[236:237], 0, v[140:141]
	global_load_dwordx4 v[208:211], v[236:237], off
	global_load_dwordx4 v[212:215], v[236:237], off offset:256
	v_add_u32_e32 v234, 0xa0, v142
	v_ashrrev_i32_e32 v235, 31, v234
	v_lshlrev_b64 v[236:237], 12, v[234:235]
	v_lshl_add_u64 v[236:237], s[42:43], 0, v[236:237]
	v_lshl_add_u64 v[236:237], v[236:237], 0, v[140:141]
	global_load_dwordx4 v[216:219], v[236:237], off
	global_load_dwordx4 v[222:225], v[236:237], off offset:256
	v_add_u32_e32 v234, 0xb0, v142
	v_ashrrev_i32_e32 v235, 31, v234
	v_lshlrev_b64 v[236:237], 12, v[234:235]
	v_lshl_add_u64 v[236:237], s[42:43], 0, v[236:237]
	v_lshl_add_u64 v[236:237], v[236:237], 0, v[140:141]
	global_load_dwordx4 v[226:229], v[236:237], off
	global_load_dwordx4 v[230:233], v[236:237], off offset:256
	s_and_b64 vcc, exec, s[18:19]
	s_mov_b32 s38, s14
	s_mov_b32 s39, s12
	s_mov_b32 s15, s14
	s_mov_b32 s18, s12
	s_mov_b64 s[22:23], s[20:21]
	s_mov_b64 s[10:11], s[16:17]
	s_mov_b32 s13, s37
	s_nop 7
	s_nop 2
	s_waitcnt vmcnt(8)
	v_lshlrev_b32_e32 v194, 16, v154
	v_and_b32_e32 v195, 0xffff0000, v154
	v_lshlrev_b32_e32 v154, 16, v155
	v_and_b32_e32 v155, 0xffff0000, v155
	v_lshlrev_b32_e32 v196, 16, v156
	v_and_b32_e32 v197, 0xffff0000, v156
	v_lshlrev_b32_e32 v156, 16, v157
	v_and_b32_e32 v157, 0xffff0000, v157
	v_lshlrev_b32_e32 v198, 16, v158
	v_and_b32_e32 v199, 0xffff0000, v158
	v_lshlrev_b32_e32 v158, 16, v159
	v_and_b32_e32 v159, 0xffff0000, v159
	v_lshlrev_b32_e32 v192, 16, v152
	v_and_b32_e32 v193, 0xffff0000, v152
	v_lshlrev_b32_e32 v152, 16, v153
	v_and_b32_e32 v153, 0xffff0000, v153
	v_pk_mul_f32 v[120:121], v[120:121], v[194:195]
	v_pk_mul_f32 v[122:123], v[122:123], v[154:155]
	v_pk_mul_f32 v[118:119], v[118:119], v[156:157]
	v_pk_mul_f32 v[154:155], v[110:111], v[158:159]
	v_lshlrev_b32_e32 v156, 16, v160
	v_and_b32_e32 v157, 0xffff0000, v160
	v_lshlrev_b32_e32 v158, 16, v161
	v_and_b32_e32 v159, 0xffff0000, v161
	v_lshlrev_b32_e32 v160, 16, v162
	v_and_b32_e32 v161, 0xffff0000, v162
	v_lshlrev_b32_e32 v162, 16, v163
	v_and_b32_e32 v163, 0xffff0000, v163
	v_pk_mul_f32 v[124:125], v[124:125], v[192:193]
	v_pk_mul_f32 v[126:127], v[126:127], v[152:153]
	v_cvt_pk_bf16_f32 v110, v120, v121
	v_cvt_pk_bf16_f32 v111, v122, v123
	v_pk_mul_f32 v[112:113], v[112:113], v[156:157]
	v_pk_mul_f32 v[114:115], v[114:115], v[158:159]
	v_pk_mul_f32 v[120:121], v[104:105], v[160:161]
	v_pk_mul_f32 v[122:123], v[106:107], v[162:163]
	v_pk_mul_f32 v[116:117], v[116:117], v[196:197]
	v_pk_mul_f32 v[152:153], v[108:109], v[198:199]
	v_cvt_pk_bf16_f32 v108, v124, v125
	v_cvt_pk_bf16_f32 v109, v126, v127
	v_cvt_pk_bf16_f32 v104, v112, v113
	v_cvt_pk_bf16_f32 v105, v114, v115
	v_cvt_pk_bf16_f32 v106, v120, v121
	v_cvt_pk_bf16_f32 v107, v122, v123
	v_cvt_pk_bf16_f32 v116, v116, v117
	v_cvt_pk_bf16_f32 v117, v118, v119
	v_cvt_pk_bf16_f32 v118, v152, v153
	v_cvt_pk_bf16_f32 v119, v154, v155
	global_store_dwordx4 v[188:189], v[108:111], off
	global_store_dwordx4 v[188:189], v[116:119], off offset:256
	global_store_dwordx4 v[190:191], v[104:107], off
	v_lshlrev_b32_e32 v192, 16, v164
	v_and_b32_e32 v193, 0xffff0000, v164
	v_lshlrev_b32_e32 v104, 16, v165
	v_and_b32_e32 v105, 0xffff0000, v165
	v_pk_mul_f32 v[102:103], v[102:103], v[104:105]
	v_lshlrev_b32_e32 v104, 16, v166
	v_and_b32_e32 v105, 0xffff0000, v166
	v_pk_mul_f32 v[104:105], v[92:93], v[104:105]
	v_lshlrev_b32_e32 v92, 16, v167
	v_and_b32_e32 v93, 0xffff0000, v167
	v_pk_mul_f32 v[100:101], v[100:101], v[192:193]
	v_pk_mul_f32 v[106:107], v[94:95], v[92:93]
	v_cvt_pk_bf16_f32 v92, v100, v101
	v_cvt_pk_bf16_f32 v93, v102, v103
	v_cvt_pk_bf16_f32 v94, v104, v105
	v_cvt_pk_bf16_f32 v95, v106, v107
	global_store_dwordx4 v[190:191], v[92:95], off offset:256
	v_add_u32_e32 v102, 0xb0, v142
	v_ashrrev_i32_e32 v103, 31, v102
	v_lshlrev_b32_e32 v94, 16, v168
	v_and_b32_e32 v95, 0xffff0000, v168
	v_pk_mul_f32 v[94:95], v[96:97], v[94:95]
	v_lshlrev_b32_e32 v96, 16, v169
	v_and_b32_e32 v97, 0xffff0000, v169
	v_pk_mul_f32 v[96:97], v[98:99], v[96:97]
	v_lshlrev_b32_e32 v98, 16, v170
	v_and_b32_e32 v99, 0xffff0000, v170
	v_lshlrev_b64 v[92:93], 11, v[176:177]
	v_pk_mul_f32 v[98:99], v[88:89], v[98:99]
	v_lshlrev_b32_e32 v88, 16, v171
	v_and_b32_e32 v89, 0xffff0000, v171
	v_pk_mul_f32 v[100:101], v[90:91], v[88:89]
	v_lshl_add_u64 v[92:93], s[82:83], 0, v[92:93]
	v_cvt_pk_bf16_f32 v88, v94, v95
	v_cvt_pk_bf16_f32 v89, v96, v97
	v_cvt_pk_bf16_f32 v90, v98, v99
	v_cvt_pk_bf16_f32 v91, v100, v101
	v_lshl_add_u64 v[92:93], v[92:93], 0, v[140:141]
	global_store_dwordx4 v[92:93], v[88:91], off
	v_add_u32_e32 v96, 0x80, v142
	v_ashrrev_i32_e32 v97, 31, v96
	v_lshlrev_b32_e32 v88, 16, v172
	v_and_b32_e32 v89, 0xffff0000, v172
	v_pk_mul_f32 v[84:85], v[84:85], v[88:89]
	v_lshlrev_b32_e32 v88, 16, v173
	v_and_b32_e32 v89, 0xffff0000, v173
	v_pk_mul_f32 v[86:87], v[86:87], v[88:89]
	v_lshlrev_b32_e32 v88, 16, v174
	v_and_b32_e32 v89, 0xffff0000, v174
	v_pk_mul_f32 v[88:89], v[76:77], v[88:89]
	v_lshlrev_b32_e32 v76, 16, v175
	v_and_b32_e32 v77, 0xffff0000, v175
	v_pk_mul_f32 v[90:91], v[78:79], v[76:77]
	v_cvt_pk_bf16_f32 v76, v84, v85
	v_cvt_pk_bf16_f32 v77, v86, v87
	v_cvt_pk_bf16_f32 v78, v88, v89
	v_cvt_pk_bf16_f32 v79, v90, v91
	global_store_dwordx4 v[92:93], v[76:79], off offset:256
	v_add_u32_e32 v98, 0x90, v142
	v_ashrrev_i32_e32 v99, 31, v98
	v_lshlrev_b32_e32 v78, 16, v180
	v_and_b32_e32 v79, 0xffff0000, v180
	v_pk_mul_f32 v[78:79], v[80:81], v[78:79]
	v_lshlrev_b32_e32 v80, 16, v181
	v_and_b32_e32 v81, 0xffff0000, v181
	v_pk_mul_f32 v[80:81], v[82:83], v[80:81]
	v_lshlrev_b32_e32 v82, 16, v182
	v_and_b32_e32 v83, 0xffff0000, v182
	v_lshlrev_b64 v[76:77], 11, v[144:145]
	v_pk_mul_f32 v[82:83], v[72:73], v[82:83]
	v_lshlrev_b32_e32 v72, 16, v183
	v_and_b32_e32 v73, 0xffff0000, v183
	v_pk_mul_f32 v[84:85], v[74:75], v[72:73]
	v_lshl_add_u64 v[76:77], s[82:83], 0, v[76:77]
	v_cvt_pk_bf16_f32 v72, v78, v79
	v_cvt_pk_bf16_f32 v73, v80, v81
	v_cvt_pk_bf16_f32 v74, v82, v83
	v_cvt_pk_bf16_f32 v75, v84, v85
	v_lshl_add_u64 v[76:77], v[76:77], 0, v[140:141]
	global_store_dwordx4 v[76:77], v[72:75], off
	v_add_u32_e32 v100, 0xa0, v142
	v_ashrrev_i32_e32 v101, 31, v100
	v_lshlrev_b32_e32 v72, 16, v184
	v_and_b32_e32 v73, 0xffff0000, v184
	v_pk_mul_f32 v[68:69], v[68:69], v[72:73]
	v_lshlrev_b32_e32 v72, 16, v185
	v_and_b32_e32 v73, 0xffff0000, v185
	v_pk_mul_f32 v[70:71], v[70:71], v[72:73]
	v_lshlrev_b32_e32 v72, 16, v186
	v_and_b32_e32 v73, 0xffff0000, v186
	v_pk_mul_f32 v[72:73], v[64:65], v[72:73]
	v_lshlrev_b32_e32 v64, 16, v187
	v_and_b32_e32 v65, 0xffff0000, v187
	v_pk_mul_f32 v[74:75], v[66:67], v[64:65]
	v_cvt_pk_bf16_f32 v64, v68, v69
	v_cvt_pk_bf16_f32 v65, v70, v71
	v_cvt_pk_bf16_f32 v66, v72, v73
	v_cvt_pk_bf16_f32 v67, v74, v75
	global_store_dwordx4 v[76:77], v[64:67], off offset:256
	s_nop 1
	v_lshlrev_b64 v[64:65], 12, v[96:97]
	v_lshl_add_u64 v[64:65], s[42:43], 0, v[64:65]
	v_lshl_add_u64 v[64:65], v[64:65], 0, v[140:141]
	v_lshlrev_b64 v[64:65], 12, v[98:99]
	v_lshl_add_u64 v[64:65], s[42:43], 0, v[64:65]
	v_lshl_add_u64 v[64:65], v[64:65], 0, v[140:141]
	v_lshlrev_b64 v[64:65], 12, v[100:101]
	v_lshl_add_u64 v[64:65], s[42:43], 0, v[64:65]
	v_lshl_add_u64 v[64:65], v[64:65], 0, v[140:141]
	v_lshlrev_b64 v[64:65], 12, v[102:103]
	v_lshl_add_u64 v[64:65], s[42:43], 0, v[64:65]
	v_lshl_add_u64 v[64:65], v[64:65], 0, v[140:141]
	s_nop 0
	v_lshlrev_b64 v[96:97], 11, v[96:97]
	s_waitcnt vmcnt(8)
	v_lshlrev_b32_e32 v104, 16, v200
	v_and_b32_e32 v105, 0xffff0000, v200
	v_lshlrev_b32_e32 v68, 16, v201
	v_and_b32_e32 v69, 0xffff0000, v201
	v_pk_mul_f32 v[62:63], v[62:63], v[68:69]
	v_lshlrev_b32_e32 v68, 16, v202
	v_and_b32_e32 v69, 0xffff0000, v202
	v_pk_mul_f32 v[60:61], v[60:61], v[104:105]
	v_pk_mul_f32 v[68:69], v[56:57], v[68:69]
	v_lshlrev_b32_e32 v56, 16, v203
	v_and_b32_e32 v57, 0xffff0000, v203
	v_pk_mul_f32 v[70:71], v[58:59], v[56:57]
	v_cvt_pk_bf16_f32 v56, v60, v61
	v_lshl_add_u64 v[60:61], s[82:83], 0, v[96:97]
	v_cvt_pk_bf16_f32 v57, v62, v63
	v_cvt_pk_bf16_f32 v58, v68, v69
	v_cvt_pk_bf16_f32 v59, v70, v71
	v_lshl_add_u64 v[60:61], v[60:61], 0, v[140:141]
	global_store_dwordx4 v[60:61], v[56:59], off
	s_nop 1
	v_lshlrev_b32_e32 v56, 16, v204
	v_and_b32_e32 v57, 0xffff0000, v204
	v_pk_mul_f32 v[52:53], v[52:53], v[56:57]
	v_lshlrev_b32_e32 v56, 16, v205
	v_and_b32_e32 v57, 0xffff0000, v205
	v_pk_mul_f32 v[54:55], v[54:55], v[56:57]
	v_lshlrev_b32_e32 v56, 16, v206
	v_and_b32_e32 v57, 0xffff0000, v206
	v_pk_mul_f32 v[56:57], v[44:45], v[56:57]
	v_lshlrev_b32_e32 v44, 16, v207
	v_and_b32_e32 v45, 0xffff0000, v207
	v_pk_mul_f32 v[58:59], v[46:47], v[44:45]
	v_cvt_pk_bf16_f32 v44, v52, v53
	v_cvt_pk_bf16_f32 v45, v54, v55
	v_cvt_pk_bf16_f32 v46, v56, v57
	v_cvt_pk_bf16_f32 v47, v58, v59
	global_store_dwordx4 v[60:61], v[44:47], off offset:256
	s_nop 1
	v_lshlrev_b32_e32 v46, 16, v208
	v_and_b32_e32 v47, 0xffff0000, v208
	v_pk_mul_f32 v[46:47], v[48:49], v[46:47]
	v_lshlrev_b32_e32 v48, 16, v209
	v_and_b32_e32 v49, 0xffff0000, v209
	v_pk_mul_f32 v[48:49], v[50:51], v[48:49]
	v_lshlrev_b32_e32 v50, 16, v210
	v_and_b32_e32 v51, 0xffff0000, v210
	v_lshlrev_b64 v[44:45], 11, v[98:99]
	v_pk_mul_f32 v[50:51], v[40:41], v[50:51]
	v_lshlrev_b32_e32 v40, 16, v211
	v_and_b32_e32 v41, 0xffff0000, v211
	v_pk_mul_f32 v[52:53], v[42:43], v[40:41]
	v_lshl_add_u64 v[44:45], s[82:83], 0, v[44:45]
	v_cvt_pk_bf16_f32 v40, v46, v47
	v_cvt_pk_bf16_f32 v41, v48, v49
	v_cvt_pk_bf16_f32 v42, v50, v51
	v_cvt_pk_bf16_f32 v43, v52, v53
	v_lshl_add_u64 v[44:45], v[44:45], 0, v[140:141]
	global_store_dwordx4 v[44:45], v[40:43], off
	s_nop 1
	v_lshlrev_b32_e32 v40, 16, v212
	v_and_b32_e32 v41, 0xffff0000, v212
	v_pk_mul_f32 v[36:37], v[36:37], v[40:41]
	v_lshlrev_b32_e32 v40, 16, v213
	v_and_b32_e32 v41, 0xffff0000, v213
	v_pk_mul_f32 v[38:39], v[38:39], v[40:41]
	v_lshlrev_b32_e32 v40, 16, v214
	v_and_b32_e32 v41, 0xffff0000, v214
	v_pk_mul_f32 v[40:41], v[28:29], v[40:41]
	v_lshlrev_b32_e32 v28, 16, v215
	v_and_b32_e32 v29, 0xffff0000, v215
	v_pk_mul_f32 v[42:43], v[30:31], v[28:29]
	v_cvt_pk_bf16_f32 v28, v36, v37
	v_cvt_pk_bf16_f32 v29, v38, v39
	v_cvt_pk_bf16_f32 v30, v40, v41
	v_cvt_pk_bf16_f32 v31, v42, v43
	global_store_dwordx4 v[44:45], v[28:31], off offset:256
	s_nop 1
	v_lshlrev_b32_e32 v30, 16, v216
	v_and_b32_e32 v31, 0xffff0000, v216
	v_pk_mul_f32 v[30:31], v[32:33], v[30:31]
	v_lshlrev_b32_e32 v32, 16, v217
	v_and_b32_e32 v33, 0xffff0000, v217
	v_pk_mul_f32 v[32:33], v[34:35], v[32:33]
	v_lshlrev_b32_e32 v34, 16, v218
	v_and_b32_e32 v35, 0xffff0000, v218
	v_lshlrev_b64 v[28:29], 11, v[100:101]
	v_pk_mul_f32 v[34:35], v[24:25], v[34:35]
	v_lshlrev_b32_e32 v24, 16, v219
	v_and_b32_e32 v25, 0xffff0000, v219
	v_pk_mul_f32 v[36:37], v[26:27], v[24:25]
	v_lshl_add_u64 v[28:29], s[82:83], 0, v[28:29]
	v_cvt_pk_bf16_f32 v24, v30, v31
	v_cvt_pk_bf16_f32 v25, v32, v33
	v_cvt_pk_bf16_f32 v26, v34, v35
	v_cvt_pk_bf16_f32 v27, v36, v37
	v_lshl_add_u64 v[28:29], v[28:29], 0, v[140:141]
	global_store_dwordx4 v[28:29], v[24:27], off
	s_nop 1
	v_lshlrev_b32_e32 v24, 16, v222
	v_and_b32_e32 v25, 0xffff0000, v222
	v_pk_mul_f32 v[20:21], v[20:21], v[24:25]
	v_lshlrev_b32_e32 v24, 16, v223
	v_and_b32_e32 v25, 0xffff0000, v223
	v_pk_mul_f32 v[22:23], v[22:23], v[24:25]
	v_lshlrev_b32_e32 v24, 16, v224
	v_and_b32_e32 v25, 0xffff0000, v224
	v_pk_mul_f32 v[24:25], v[12:13], v[24:25]
	v_lshlrev_b32_e32 v12, 16, v225
	v_and_b32_e32 v13, 0xffff0000, v225
	v_pk_mul_f32 v[26:27], v[14:15], v[12:13]
	v_cvt_pk_bf16_f32 v12, v20, v21
	v_cvt_pk_bf16_f32 v13, v22, v23
	v_cvt_pk_bf16_f32 v14, v24, v25
	v_cvt_pk_bf16_f32 v15, v26, v27
	global_store_dwordx4 v[28:29], v[12:15], off offset:256
	s_nop 1
	v_lshlrev_b32_e32 v14, 16, v226
	v_and_b32_e32 v15, 0xffff0000, v226
	v_pk_mul_f32 v[14:15], v[16:17], v[14:15]
	v_lshlrev_b32_e32 v16, 16, v227
	v_and_b32_e32 v17, 0xffff0000, v227
	v_pk_mul_f32 v[16:17], v[18:19], v[16:17]
	v_lshlrev_b32_e32 v18, 16, v228
	v_and_b32_e32 v19, 0xffff0000, v228
	v_lshlrev_b64 v[12:13], 11, v[102:103]
	v_pk_mul_f32 v[18:19], v[8:9], v[18:19]
	v_lshlrev_b32_e32 v8, 16, v229
	v_and_b32_e32 v9, 0xffff0000, v229
	v_pk_mul_f32 v[20:21], v[10:11], v[8:9]
	v_lshl_add_u64 v[12:13], s[82:83], 0, v[12:13]
	v_cvt_pk_bf16_f32 v8, v14, v15
	v_cvt_pk_bf16_f32 v9, v16, v17
	v_cvt_pk_bf16_f32 v10, v18, v19
	v_cvt_pk_bf16_f32 v11, v20, v21
	v_lshl_add_u64 v[12:13], v[12:13], 0, v[140:141]
	global_store_dwordx4 v[12:13], v[8:11], off
	s_nop 1
	v_lshlrev_b32_e32 v8, 16, v230
	v_and_b32_e32 v9, 0xffff0000, v230
	v_pk_mul_f32 v[4:5], v[4:5], v[8:9]
	v_lshlrev_b32_e32 v8, 16, v231
	v_and_b32_e32 v9, 0xffff0000, v231
	v_pk_mul_f32 v[6:7], v[6:7], v[8:9]
	v_lshlrev_b32_e32 v8, 16, v232
	v_and_b32_e32 v9, 0xffff0000, v232
	v_pk_mul_f32 v[8:9], v[0:1], v[8:9]
	v_lshlrev_b32_e32 v0, 16, v233
	v_and_b32_e32 v1, 0xffff0000, v233
	v_pk_mul_f32 v[10:11], v[2:3], v[0:1]
	v_cvt_pk_bf16_f32 v0, v4, v5
	v_cvt_pk_bf16_f32 v1, v6, v7
	v_cvt_pk_bf16_f32 v2, v8, v9
	v_cvt_pk_bf16_f32 v3, v10, v11
	global_store_dwordx4 v[12:13], v[0:3], off offset:256
	s_cbranch_vccz .LBB0_1260
	s_waitcnt vmcnt(0)
	s_cmpk_gt_u32 s26, 0xff
	s_cbranch_scc1 .LBB0_1272
	s_barrier

.LBB0_1285:
	ds_read_b128 v[144:147], v176
	ds_read_b128 v[148:151], v176 offset:1024
	ds_read_b128 v[164:167], v176 offset:2048
	ds_read_b128 v[168:171], v176 offset:3072
	ds_read_b128 v[180:183], v176 offset:4096
	ds_read_b128 v[184:187], v176 offset:5120
	ds_read_b128 v[188:191], v176 offset:6144
	ds_read_b128 v[192:195], v176 offset:7168
	ds_read_b128 v[128:131], v175
	ds_read_b128 v[132:135], v175 offset:1024
	ds_read_b128 v[136:139], v175 offset:2048
	ds_read_b128 v[140:143], v175 offset:3072
	s_add_u32 s22, s10, 0xfffe0080
	s_addc_u32 s23, s11, -1
	s_cmp_eq_u32 s43, 4
	s_cselect_b32 s25, s13, s23
	s_cselect_b32 s24, s39, s22
	s_cselect_b32 s23, s15, s42
	s_cselect_b32 s22, s40, s41
	v_lshl_add_u64 v[196:197], s[10:11], 0, v[160:161]
	s_add_i32 m0, s1, 0xc000
	s_nop 0
	global_load_lds_dwordx4 v[196:197], off
	v_lshl_add_u64 v[196:197], s[10:11], 0, v[162:163]
	s_add_i32 m0, s1, 0xe000
	s_nop 0
	global_load_lds_dwordx4 v[196:197], off
	s_waitcnt lgkmcnt(0)
	s_barrier
	v_mfma_f32_16x16x32_bf16 v[124:127], v[128:131], v[144:147], v[124:127]
	v_mfma_f32_16x16x32_bf16 v[120:123], v[136:139], v[144:147], v[120:123]
	v_mfma_f32_16x16x32_bf16 v[108:111], v[128:131], v[164:167], v[108:111]
	v_mfma_f32_16x16x32_bf16 v[104:107], v[136:139], v[164:167], v[104:107]
	v_mfma_f32_16x16x32_bf16 v[92:95], v[128:131], v[180:183], v[92:95]
	v_mfma_f32_16x16x32_bf16 v[88:91], v[136:139], v[180:183], v[88:91]
	v_mfma_f32_16x16x32_bf16 v[76:79], v[128:131], v[188:191], v[76:79]
	v_mfma_f32_16x16x32_bf16 v[72:75], v[136:139], v[188:191], v[72:75]
	v_mfma_f32_16x16x32_bf16 v[124:127], v[132:135], v[148:151], v[124:127]
	v_mfma_f32_16x16x32_bf16 v[120:123], v[140:143], v[148:151], v[120:123]
	v_mfma_f32_16x16x32_bf16 v[108:111], v[132:135], v[168:171], v[108:111]
	v_mfma_f32_16x16x32_bf16 v[104:107], v[140:143], v[168:171], v[104:107]
	v_mfma_f32_16x16x32_bf16 v[92:95], v[132:135], v[184:187], v[92:95]
	v_mfma_f32_16x16x32_bf16 v[88:91], v[140:143], v[184:187], v[88:91]
	v_mfma_f32_16x16x32_bf16 v[76:79], v[132:135], v[192:195], v[76:79]
	v_mfma_f32_16x16x32_bf16 v[72:75], v[140:143], v[192:195], v[72:75]
	s_barrier
	s_add_i32 s44, s35, s27
	v_lshl_add_u64 v[212:213], s[22:23], 0, v[156:157]
	s_mov_b32 m0, s44
	ds_read_b128 v[196:199], v177
	ds_read_b128 v[200:203], v177 offset:1024
	ds_read_b128 v[204:207], v177 offset:2048
	ds_read_b128 v[208:211], v177 offset:3072
	global_load_lds_dwordx4 v[212:213], off
	v_lshl_add_u64 v[214:215], s[22:23], 0, v[152:153]
	s_add_i32 m0, s44, 0x2000
	s_nop 0
	global_load_lds_dwordx4 v[214:215], off
	s_barrier
	s_waitcnt lgkmcnt(0)
	v_mfma_f32_16x16x32_bf16 v[116:119], v[196:199], v[144:147], v[116:119]
	v_mfma_f32_16x16x32_bf16 v[112:115], v[204:207], v[144:147], v[112:115]
	v_mfma_f32_16x16x32_bf16 v[100:103], v[196:199], v[164:167], v[100:103]
	v_mfma_f32_16x16x32_bf16 v[96:99], v[204:207], v[164:167], v[96:99]
	v_mfma_f32_16x16x32_bf16 v[84:87], v[196:199], v[180:183], v[84:87]
	v_mfma_f32_16x16x32_bf16 v[80:83], v[204:207], v[180:183], v[80:83]
	v_mfma_f32_16x16x32_bf16 v[68:71], v[196:199], v[188:191], v[68:71]
	v_mfma_f32_16x16x32_bf16 v[64:67], v[204:207], v[188:191], v[64:67]
	v_mfma_f32_16x16x32_bf16 v[116:119], v[200:203], v[148:151], v[116:119]
	v_mfma_f32_16x16x32_bf16 v[112:115], v[208:211], v[148:151], v[112:115]
	v_mfma_f32_16x16x32_bf16 v[100:103], v[200:203], v[168:171], v[100:103]
	v_mfma_f32_16x16x32_bf16 v[96:99], v[208:211], v[168:171], v[96:99]
	v_mfma_f32_16x16x32_bf16 v[84:87], v[200:203], v[184:187], v[84:87]
	v_mfma_f32_16x16x32_bf16 v[80:83], v[208:211], v[184:187], v[80:83]
	v_mfma_f32_16x16x32_bf16 v[68:71], v[200:203], v[192:195], v[68:71]
	v_mfma_f32_16x16x32_bf16 v[64:67], v[208:211], v[192:195], v[64:67]
	s_mov_b32 m0, s1
	v_lshl_add_u64 v[216:217], s[24:25], 0, v[158:159]
	s_barrier
	ds_read_b128 v[144:147], v176 offset:16384
	ds_read_b128 v[148:151], v176 offset:17408
	ds_read_b128 v[164:167], v176 offset:18432
	ds_read_b128 v[168:171], v176 offset:19456
	ds_read_b128 v[180:183], v176 offset:20480
	ds_read_b128 v[184:187], v176 offset:21504
	ds_read_b128 v[188:191], v176 offset:22528
	ds_read_b128 v[192:195], v176 offset:23552
	global_load_lds_dwordx4 v[216:217], off
	v_lshl_add_u64 v[218:219], s[24:25], 0, v[154:155]
	s_mov_b32 m0, s7
	s_nop 0
	global_load_lds_dwordx4 v[218:219], off
	s_barrier
	s_waitcnt lgkmcnt(0)
	v_mfma_f32_16x16x32_bf16 v[60:63], v[128:131], v[144:147], v[60:63]
	v_mfma_f32_16x16x32_bf16 v[56:59], v[136:139], v[144:147], v[56:59]
	v_mfma_f32_16x16x32_bf16 v[44:47], v[128:131], v[164:167], v[44:47]
	v_mfma_f32_16x16x32_bf16 v[40:43], v[136:139], v[164:167], v[40:43]
	v_mfma_f32_16x16x32_bf16 v[28:31], v[128:131], v[180:183], v[28:31]
	v_mfma_f32_16x16x32_bf16 v[24:27], v[136:139], v[180:183], v[24:27]
	v_mfma_f32_16x16x32_bf16 v[12:15], v[128:131], v[188:191], v[12:15]
	v_mfma_f32_16x16x32_bf16 v[8:11], v[136:139], v[188:191], v[8:11]
	v_mfma_f32_16x16x32_bf16 v[60:63], v[132:135], v[148:151], v[60:63]
	v_mfma_f32_16x16x32_bf16 v[56:59], v[140:143], v[148:151], v[56:59]
	v_mfma_f32_16x16x32_bf16 v[44:47], v[132:135], v[168:171], v[44:47]
	v_mfma_f32_16x16x32_bf16 v[40:43], v[140:143], v[168:171], v[40:43]
	v_mfma_f32_16x16x32_bf16 v[28:31], v[132:135], v[184:187], v[28:31]
	v_mfma_f32_16x16x32_bf16 v[24:27], v[140:143], v[184:187], v[24:27]
	v_mfma_f32_16x16x32_bf16 v[12:15], v[132:135], v[192:195], v[12:15]
	v_mfma_f32_16x16x32_bf16 v[8:11], v[140:143], v[192:195], v[8:11]
	s_barrier
	s_add_u32 s44, s22, 0x20000
	s_addc_u32 s45, s23, 0
	s_add_i32 s46, s36, s27
	v_lshl_add_u64 v[128:129], s[44:45], 0, v[156:157]
	s_mov_b32 m0, s46
	s_nop 0
	global_load_lds_dwordx4 v[128:129], off
	v_lshl_add_u64 v[128:129], s[44:45], 0, v[152:153]
	s_add_i32 m0, s46, 0x2000
	s_nop 0
	global_load_lds_dwordx4 v[128:129], off
	s_waitcnt vmcnt(6)
	s_barrier
	v_mfma_f32_16x16x32_bf16 v[52:55], v[196:199], v[144:147], v[52:55]
	v_mfma_f32_16x16x32_bf16 v[48:51], v[204:207], v[144:147], v[48:51]
	v_mfma_f32_16x16x32_bf16 v[36:39], v[196:199], v[164:167], v[36:39]
	v_mfma_f32_16x16x32_bf16 v[32:35], v[204:207], v[164:167], v[32:35]
	v_mfma_f32_16x16x32_bf16 v[20:23], v[196:199], v[180:183], v[20:23]
	v_mfma_f32_16x16x32_bf16 v[16:19], v[204:207], v[180:183], v[16:19]
	v_mfma_f32_16x16x32_bf16 v[4:7], v[196:199], v[188:191], v[4:7]
	v_mfma_f32_16x16x32_bf16 v[0:3], v[204:207], v[188:191], v[0:3]
	v_mfma_f32_16x16x32_bf16 v[52:55], v[200:203], v[148:151], v[52:55]
	v_mfma_f32_16x16x32_bf16 v[48:51], v[208:211], v[148:151], v[48:51]
	v_mfma_f32_16x16x32_bf16 v[36:39], v[200:203], v[168:171], v[36:39]
	v_mfma_f32_16x16x32_bf16 v[32:35], v[208:211], v[168:171], v[32:35]
	v_mfma_f32_16x16x32_bf16 v[20:23], v[200:203], v[184:187], v[20:23]
	v_mfma_f32_16x16x32_bf16 v[16:19], v[208:211], v[184:187], v[16:19]
	v_mfma_f32_16x16x32_bf16 v[4:7], v[200:203], v[192:195], v[4:7]
	v_mfma_f32_16x16x32_bf16 v[0:3], v[208:211], v[192:195], v[0:3]
	s_add_i32 s44, 0, 0x18000
	v_add_u32_e32 v140, s44, v173
	s_barrier
	ds_read_b128 v[144:147], v176 offset:32768
	ds_read_b128 v[148:151], v176 offset:33792
	ds_read_b128 v[164:167], v176 offset:34816
	ds_read_b128 v[168:171], v176 offset:35840
	ds_read_b128 v[180:183], v176 offset:36864
	ds_read_b128 v[184:187], v176 offset:37888
	ds_read_b128 v[188:191], v176 offset:38912
	ds_read_b128 v[192:195], v176 offset:39936
	ds_read_b128 v[128:131], v140
	ds_read_b128 v[132:135], v140 offset:1024
	ds_read_b128 v[136:139], v140 offset:2048
	ds_read_b128 v[140:143], v140 offset:3072
	s_add_u32 s24, s24, 0x20000
	s_addc_u32 s25, s25, 0
	s_mov_b32 m0, s28
	v_lshl_add_u64 v[196:197], s[24:25], 0, v[158:159]
	global_load_lds_dwordx4 v[196:197], off
	v_lshl_add_u64 v[196:197], s[24:25], 0, v[154:155]
	s_mov_b32 m0, s29
	s_nop 0
	global_load_lds_dwordx4 v[196:197], off
	s_waitcnt lgkmcnt(0)
	s_barrier
	v_mfma_f32_16x16x32_bf16 v[124:127], v[128:131], v[144:147], v[124:127]
	v_mfma_f32_16x16x32_bf16 v[120:123], v[136:139], v[144:147], v[120:123]
	v_mfma_f32_16x16x32_bf16 v[108:111], v[128:131], v[164:167], v[108:111]
	v_mfma_f32_16x16x32_bf16 v[104:107], v[136:139], v[164:167], v[104:107]
	v_mfma_f32_16x16x32_bf16 v[92:95], v[128:131], v[180:183], v[92:95]
	v_mfma_f32_16x16x32_bf16 v[88:91], v[136:139], v[180:183], v[88:91]
	v_mfma_f32_16x16x32_bf16 v[76:79], v[128:131], v[188:191], v[76:79]
	v_mfma_f32_16x16x32_bf16 v[72:75], v[136:139], v[188:191], v[72:75]
	v_mfma_f32_16x16x32_bf16 v[124:127], v[132:135], v[148:151], v[124:127]
	v_mfma_f32_16x16x32_bf16 v[120:123], v[140:143], v[148:151], v[120:123]
	v_mfma_f32_16x16x32_bf16 v[108:111], v[132:135], v[168:171], v[108:111]
	v_mfma_f32_16x16x32_bf16 v[104:107], v[140:143], v[168:171], v[104:107]
	v_mfma_f32_16x16x32_bf16 v[92:95], v[132:135], v[184:187], v[92:95]
	v_mfma_f32_16x16x32_bf16 v[88:91], v[140:143], v[184:187], v[88:91]
	v_mfma_f32_16x16x32_bf16 v[76:79], v[132:135], v[192:195], v[76:79]
	v_mfma_f32_16x16x32_bf16 v[72:75], v[140:143], v[192:195], v[72:75]
	s_barrier
	s_add_i32 s24, 0, 0x1c000
	s_add_i32 s25, s44, s27
	v_add_u32_e32 v179, s24, v173
	v_lshl_add_u64 v[212:213], v[212:213], 0, s[4:5]
	s_mov_b32 m0, s25
	ds_read_b128 v[196:199], v179
	ds_read_b128 v[200:203], v179 offset:1024
	ds_read_b128 v[204:207], v179 offset:2048
	ds_read_b128 v[208:211], v179 offset:3072
	global_load_lds_dwordx4 v[212:213], off
	v_lshl_add_u64 v[212:213], v[214:215], 0, s[4:5]
	s_add_i32 m0, s25, 0x2000
	s_nop 0
	global_load_lds_dwordx4 v[212:213], off
	s_barrier
	s_waitcnt lgkmcnt(0)
	v_mfma_f32_16x16x32_bf16 v[116:119], v[196:199], v[144:147], v[116:119]
	v_mfma_f32_16x16x32_bf16 v[112:115], v[204:207], v[144:147], v[112:115]
	v_mfma_f32_16x16x32_bf16 v[100:103], v[196:199], v[164:167], v[100:103]
	v_mfma_f32_16x16x32_bf16 v[96:99], v[204:207], v[164:167], v[96:99]
	v_mfma_f32_16x16x32_bf16 v[84:87], v[196:199], v[180:183], v[84:87]
	v_mfma_f32_16x16x32_bf16 v[80:83], v[204:207], v[180:183], v[80:83]
	v_mfma_f32_16x16x32_bf16 v[68:71], v[196:199], v[188:191], v[68:71]
	v_mfma_f32_16x16x32_bf16 v[64:67], v[204:207], v[188:191], v[64:67]
	v_mfma_f32_16x16x32_bf16 v[116:119], v[200:203], v[148:151], v[116:119]
	v_mfma_f32_16x16x32_bf16 v[112:115], v[208:211], v[148:151], v[112:115]
	v_mfma_f32_16x16x32_bf16 v[100:103], v[200:203], v[168:171], v[100:103]
	v_mfma_f32_16x16x32_bf16 v[96:99], v[208:211], v[168:171], v[96:99]
	v_mfma_f32_16x16x32_bf16 v[84:87], v[200:203], v[184:187], v[84:87]
	v_mfma_f32_16x16x32_bf16 v[80:83], v[208:211], v[184:187], v[80:83]
	v_mfma_f32_16x16x32_bf16 v[68:71], v[200:203], v[192:195], v[68:71]
	v_mfma_f32_16x16x32_bf16 v[64:67], v[208:211], v[192:195], v[64:67]
	s_mov_b32 m0, s31
	v_lshl_add_u64 v[212:213], v[216:217], 0, s[4:5]
	s_barrier
	ds_read_b128 v[144:147], v176 offset:49152
	ds_read_b128 v[148:151], v176 offset:50176
	ds_read_b128 v[164:167], v176 offset:51200
	ds_read_b128 v[168:171], v176 offset:52224
	ds_read_b128 v[180:183], v176 offset:53248
	ds_read_b128 v[184:187], v176 offset:54272
	ds_read_b128 v[188:191], v176 offset:55296
	ds_read_b128 v[192:195], v176 offset:56320
	global_load_lds_dwordx4 v[212:213], off
	v_lshl_add_u64 v[212:213], v[218:219], 0, s[4:5]
	s_mov_b32 m0, s33
	s_nop 0
	global_load_lds_dwordx4 v[212:213], off
	s_barrier
	s_waitcnt lgkmcnt(0)
	v_mfma_f32_16x16x32_bf16 v[60:63], v[128:131], v[144:147], v[60:63]
	v_mfma_f32_16x16x32_bf16 v[56:59], v[136:139], v[144:147], v[56:59]
	v_mfma_f32_16x16x32_bf16 v[44:47], v[128:131], v[164:167], v[44:47]
	v_mfma_f32_16x16x32_bf16 v[40:43], v[136:139], v[164:167], v[40:43]
	v_mfma_f32_16x16x32_bf16 v[28:31], v[128:131], v[180:183], v[28:31]
	v_mfma_f32_16x16x32_bf16 v[24:27], v[136:139], v[180:183], v[24:27]
	v_mfma_f32_16x16x32_bf16 v[12:15], v[128:131], v[188:191], v[12:15]
	v_mfma_f32_16x16x32_bf16 v[8:11], v[136:139], v[188:191], v[8:11]
	v_mfma_f32_16x16x32_bf16 v[60:63], v[132:135], v[148:151], v[60:63]
	v_mfma_f32_16x16x32_bf16 v[56:59], v[140:143], v[148:151], v[56:59]
	v_mfma_f32_16x16x32_bf16 v[44:47], v[132:135], v[168:171], v[44:47]
	v_mfma_f32_16x16x32_bf16 v[40:43], v[140:143], v[168:171], v[40:43]
	v_mfma_f32_16x16x32_bf16 v[28:31], v[132:135], v[184:187], v[28:31]
	v_mfma_f32_16x16x32_bf16 v[24:27], v[140:143], v[184:187], v[24:27]
	v_mfma_f32_16x16x32_bf16 v[12:15], v[132:135], v[192:195], v[12:15]
	v_mfma_f32_16x16x32_bf16 v[8:11], v[140:143], v[192:195], v[8:11]
	s_barrier
	s_add_u32 s22, s22, 0x20080
	s_addc_u32 s23, s23, 0
	s_add_i32 s24, s24, s27
	v_lshl_add_u64 v[128:129], s[22:23], 0, v[156:157]
	s_mov_b32 m0, s24
	s_nop 0
	global_load_lds_dwordx4 v[128:129], off
	v_lshl_add_u64 v[128:129], s[22:23], 0, v[152:153]
	s_add_i32 m0, s24, 0x2000
	s_nop 0
	global_load_lds_dwordx4 v[128:129], off
	s_waitcnt vmcnt(6)
	s_barrier
	v_mfma_f32_16x16x32_bf16 v[52:55], v[196:199], v[144:147], v[52:55]
	v_mfma_f32_16x16x32_bf16 v[48:51], v[204:207], v[144:147], v[48:51]
	v_mfma_f32_16x16x32_bf16 v[36:39], v[196:199], v[164:167], v[36:39]
	v_mfma_f32_16x16x32_bf16 v[32:35], v[204:207], v[164:167], v[32:35]
	v_mfma_f32_16x16x32_bf16 v[20:23], v[196:199], v[180:183], v[20:23]
	v_mfma_f32_16x16x32_bf16 v[16:19], v[204:207], v[180:183], v[16:19]
	v_mfma_f32_16x16x32_bf16 v[4:7], v[196:199], v[188:191], v[4:7]
	v_mfma_f32_16x16x32_bf16 v[0:3], v[204:207], v[188:191], v[0:3]
	v_mfma_f32_16x16x32_bf16 v[52:55], v[200:203], v[148:151], v[52:55]
	v_mfma_f32_16x16x32_bf16 v[48:51], v[208:211], v[148:151], v[48:51]
	v_mfma_f32_16x16x32_bf16 v[36:39], v[200:203], v[168:171], v[36:39]
	v_mfma_f32_16x16x32_bf16 v[32:35], v[208:211], v[168:171], v[32:35]
	v_mfma_f32_16x16x32_bf16 v[20:23], v[200:203], v[184:187], v[20:23]
	v_mfma_f32_16x16x32_bf16 v[16:19], v[208:211], v[184:187], v[16:19]
	v_mfma_f32_16x16x32_bf16 v[4:7], v[200:203], v[192:195], v[4:7]
	v_mfma_f32_16x16x32_bf16 v[0:3], v[208:211], v[192:195], v[0:3]
	s_add_i32 s43, s43, 2
	s_add_u32 s10, s10, 0x100
	s_addc_u32 s11, s11, 0
	s_add_u32 s41, s41, 0x100
	s_addc_u32 s42, s42, 0
	s_cmp_gt_u32 s43, 5
	s_barrier
	s_cbranch_scc0 .LBB0_1285
	v_lshl_add_u32 v164, s38, 8, v172
	s_nop 0
	v_lshl_or_b32 v128, s0, 8, v174
	v_ashrrev_i32_e32 v165, 31, v164
	s_nop 1
	v_readlane_b32 s46, v252, 13
	v_readlane_b32 s47, v252, 14
	v_ashrrev_i32_e32 v129, 31, v128
	v_lshlrev_b64 v[130:131], 12, v[164:165]
	s_mov_b64 s[42:43], s[46:47]
	v_lshl_add_u64 v[130:131], s[42:43], 0, v[130:131]
	v_lshlrev_b64 v[132:133], 11, v[164:165]
	v_lshlrev_b64 v[166:167], 1, v[128:129]
	v_lshl_add_u64 v[132:133], s[82:83], 0, v[132:133]
	v_lshl_add_u64 v[128:129], v[130:131], 0, v[166:167]
	global_load_dwordx4 v[180:183], v[128:129], off offset:2048
	v_lshl_add_u64 v[222:223], v[132:133], 0, v[166:167]
	global_load_dwordx4 v[184:187], v[222:223], off
	global_load_dwordx4 v[188:191], v[128:129], off offset:2304
	global_load_dwordx4 v[192:195], v[222:223], off offset:256
	v_or_b32_e32 v128, 16, v164
	v_ashrrev_i32_e32 v129, 31, v128
	v_lshlrev_b64 v[130:131], 12, v[128:129]
	v_lshlrev_b64 v[128:129], 11, v[128:129]
	v_lshl_add_u64 v[130:131], s[42:43], 0, v[130:131]
	v_lshl_add_u64 v[128:129], s[82:83], 0, v[128:129]
	v_lshl_add_u64 v[130:131], v[130:131], 0, v[166:167]
	v_lshl_add_u64 v[224:225], v[128:129], 0, v[166:167]
	global_load_dwordx4 v[196:199], v[130:131], off offset:2048
	global_load_dwordx4 v[200:203], v[224:225], off
	v_or_b32_e32 v128, 32, v164
	v_or_b32_e32 v132, 48, v164
	v_ashrrev_i32_e32 v129, 31, v128
	v_ashrrev_i32_e32 v133, 31, v132
	v_lshlrev_b64 v[134:135], 12, v[128:129]
	v_lshlrev_b64 v[128:129], 11, v[128:129]
	v_lshlrev_b64 v[136:137], 12, v[132:133]
	v_lshlrev_b64 v[132:133], 11, v[132:133]
	v_lshl_add_u64 v[134:135], s[42:43], 0, v[134:135]
	v_lshl_add_u64 v[128:129], s[82:83], 0, v[128:129]
	v_lshl_add_u64 v[136:137], s[42:43], 0, v[136:137]
	v_lshl_add_u64 v[132:133], s[82:83], 0, v[132:133]
	v_lshl_add_u64 v[134:135], v[134:135], 0, v[166:167]
	v_lshl_add_u64 v[170:171], v[128:129], 0, v[166:167]
	v_lshl_add_u64 v[128:129], v[136:137], 0, v[166:167]
	v_lshl_add_u64 v[168:169], v[132:133], 0, v[166:167]
	global_load_dwordx4 v[204:207], v[130:131], off offset:2304
	global_load_dwordx4 v[208:211], v[224:225], off offset:256
	global_load_dwordx4 v[212:215], v[134:135], off offset:2048
	global_load_dwordx4 v[148:151], v[134:135], off offset:2304
	global_load_dwordx4 v[216:219], v[170:171], off
	global_load_dwordx4 v[144:147], v[170:171], off offset:256
	global_load_dwordx4 v[140:143], v[128:129], off offset:2048
	s_nop 0
	global_load_dwordx4 v[132:135], v[128:129], off offset:2304
	global_load_dwordx4 v[136:139], v[168:169], off
	s_nop 0
	global_load_dwordx4 v[128:131], v[168:169], off offset:256
	s_and_b64 vcc, exec, s[18:19]
	s_mov_b32 s0, s14
	s_mov_b32 s38, s12
	s_mov_b32 s15, s14
	s_mov_b32 s18, s12
	s_mov_b64 s[22:23], s[20:21]
	s_mov_b64 s[10:11], s[16:17]
	s_mov_b32 s13, s37
	s_nop 7
	s_nop 2
	s_waitcnt vmcnt(0)
	v_lshlrev_b32_e32 v228, 16, v184
	v_lshlrev_b32_e32 v226, 16, v180
	v_and_b32_e32 v227, 0xffff0000, v180
	v_and_b32_e32 v229, 0xffff0000, v184
	v_lshlrev_b32_e32 v180, 16, v181
	v_and_b32_e32 v181, 0xffff0000, v181
	v_lshlrev_b32_e32 v184, 16, v185
	v_and_b32_e32 v185, 0xffff0000, v185
	v_lshlrev_b32_e32 v230, 16, v182
	v_and_b32_e32 v231, 0xffff0000, v182
	v_lshlrev_b32_e32 v232, 16, v186
	v_and_b32_e32 v233, 0xffff0000, v186
	v_lshlrev_b32_e32 v182, 16, v183
	v_and_b32_e32 v183, 0xffff0000, v183
	v_lshlrev_b32_e32 v186, 16, v187
	v_and_b32_e32 v187, 0xffff0000, v187
	v_lshlrev_b32_e32 v234, 16, v188
	v_and_b32_e32 v235, 0xffff0000, v188
	v_lshlrev_b32_e32 v236, 16, v192
	v_and_b32_e32 v237, 0xffff0000, v192
	v_lshlrev_b32_e32 v188, 16, v189
	v_and_b32_e32 v189, 0xffff0000, v189
	v_lshlrev_b32_e32 v192, 16, v193
	v_and_b32_e32 v193, 0xffff0000, v193
	v_pk_fma_f32 v[124:125], v[124:125], v[226:227], v[228:229]
	v_pk_fma_f32 v[126:127], v[126:127], v[180:181], v[184:185]
	v_pk_fma_f32 v[120:121], v[120:121], v[230:231], v[232:233]
	v_pk_fma_f32 v[122:123], v[122:123], v[182:183], v[186:187]
	v_lshlrev_b32_e32 v238, 16, v190
	v_and_b32_e32 v239, 0xffff0000, v190
	v_lshlrev_b32_e32 v240, 16, v194
	v_pk_fma_f32 v[180:181], v[116:117], v[234:235], v[236:237]
	v_pk_fma_f32 v[182:183], v[118:119], v[188:189], v[192:193]
	v_cvt_pk_bf16_f32 v116, v124, v125
	v_cvt_pk_bf16_f32 v117, v126, v127
	v_cvt_pk_bf16_f32 v118, v120, v121
	v_cvt_pk_bf16_f32 v119, v122, v123
	v_and_b32_e32 v241, 0xffff0000, v194
	global_store_dwordx4 v[222:223], v[116:119], off
	s_nop 1
	v_pk_fma_f32 v[116:117], v[112:113], v[238:239], v[240:241]
	v_lshlrev_b32_e32 v112, 16, v191
	v_and_b32_e32 v113, 0xffff0000, v191
	v_lshlrev_b32_e32 v118, 16, v195
	v_and_b32_e32 v119, 0xffff0000, v195
	v_pk_fma_f32 v[118:119], v[114:115], v[112:113], v[118:119]
	v_cvt_pk_bf16_f32 v112, v180, v181
	v_cvt_pk_bf16_f32 v113, v182, v183
	v_cvt_pk_bf16_f32 v114, v116, v117
	v_cvt_pk_bf16_f32 v115, v118, v119
	global_store_dwordx4 v[222:223], v[112:115], off offset:256
	s_nop 1
	v_lshlrev_b32_e32 v112, 16, v196
	v_and_b32_e32 v113, 0xffff0000, v196
	v_lshlrev_b32_e32 v114, 16, v200
	v_and_b32_e32 v115, 0xffff0000, v200
	v_pk_fma_f32 v[108:109], v[108:109], v[112:113], v[114:115]
	v_lshlrev_b32_e32 v112, 16, v197
	v_and_b32_e32 v113, 0xffff0000, v197
	v_lshlrev_b32_e32 v114, 16, v201
	v_and_b32_e32 v115, 0xffff0000, v201
	v_pk_fma_f32 v[110:111], v[110:111], v[112:113], v[114:115]
	v_lshlrev_b32_e32 v112, 16, v198
	v_and_b32_e32 v113, 0xffff0000, v198
	v_lshlrev_b32_e32 v114, 16, v202
	v_and_b32_e32 v115, 0xffff0000, v202
	v_pk_fma_f32 v[112:113], v[104:105], v[112:113], v[114:115]
	v_lshlrev_b32_e32 v104, 16, v199
	v_and_b32_e32 v105, 0xffff0000, v199
	v_lshlrev_b32_e32 v114, 16, v203
	v_and_b32_e32 v115, 0xffff0000, v203
	v_pk_fma_f32 v[114:115], v[106:107], v[104:105], v[114:115]
	v_cvt_pk_bf16_f32 v104, v108, v109
	v_cvt_pk_bf16_f32 v105, v110, v111
	v_cvt_pk_bf16_f32 v106, v112, v113
	v_cvt_pk_bf16_f32 v107, v114, v115
	global_store_dwordx4 v[224:225], v[104:107], off
	s_nop 1
	v_lshlrev_b32_e32 v104, 16, v204
	v_and_b32_e32 v105, 0xffff0000, v204
	v_lshlrev_b32_e32 v106, 16, v208
	v_and_b32_e32 v107, 0xffff0000, v208
	v_pk_fma_f32 v[100:101], v[100:101], v[104:105], v[106:107]
	v_lshlrev_b32_e32 v104, 16, v205
	v_and_b32_e32 v105, 0xffff0000, v205
	v_lshlrev_b32_e32 v106, 16, v209
	v_and_b32_e32 v107, 0xffff0000, v209
	v_pk_fma_f32 v[102:103], v[102:103], v[104:105], v[106:107]
	v_lshlrev_b32_e32 v104, 16, v206
	v_and_b32_e32 v105, 0xffff0000, v206
	v_lshlrev_b32_e32 v106, 16, v210
	v_and_b32_e32 v107, 0xffff0000, v210
	v_pk_fma_f32 v[104:105], v[96:97], v[104:105], v[106:107]
	v_lshlrev_b32_e32 v96, 16, v207
	v_and_b32_e32 v97, 0xffff0000, v207
	v_lshlrev_b32_e32 v106, 16, v211
	v_and_b32_e32 v107, 0xffff0000, v211
	v_pk_fma_f32 v[106:107], v[98:99], v[96:97], v[106:107]
	v_cvt_pk_bf16_f32 v96, v100, v101
	v_cvt_pk_bf16_f32 v97, v102, v103
	v_cvt_pk_bf16_f32 v98, v104, v105
	v_cvt_pk_bf16_f32 v99, v106, v107
	global_store_dwordx4 v[224:225], v[96:99], off offset:256
	s_nop 1
	v_lshlrev_b32_e32 v96, 16, v212
	v_and_b32_e32 v97, 0xffff0000, v212
	v_lshlrev_b32_e32 v98, 16, v216
	v_and_b32_e32 v99, 0xffff0000, v216
	v_pk_fma_f32 v[92:93], v[92:93], v[96:97], v[98:99]
	v_lshlrev_b32_e32 v96, 16, v213
	v_and_b32_e32 v97, 0xffff0000, v213
	v_lshlrev_b32_e32 v98, 16, v217
	v_and_b32_e32 v99, 0xffff0000, v217
	v_pk_fma_f32 v[94:95], v[94:95], v[96:97], v[98:99]
	v_lshlrev_b32_e32 v96, 16, v214
	v_and_b32_e32 v97, 0xffff0000, v214
	v_lshlrev_b32_e32 v98, 16, v218
	v_and_b32_e32 v99, 0xffff0000, v218
	v_pk_fma_f32 v[96:97], v[88:89], v[96:97], v[98:99]
	v_lshlrev_b32_e32 v88, 16, v215
	v_and_b32_e32 v89, 0xffff0000, v215
	v_lshlrev_b32_e32 v98, 16, v219
	v_and_b32_e32 v99, 0xffff0000, v219
	v_pk_fma_f32 v[98:99], v[90:91], v[88:89], v[98:99]
	v_cvt_pk_bf16_f32 v88, v92, v93
	v_cvt_pk_bf16_f32 v89, v94, v95
	v_cvt_pk_bf16_f32 v90, v96, v97
	v_cvt_pk_bf16_f32 v91, v98, v99
	global_store_dwordx4 v[170:171], v[88:91], off
	s_nop 1
	v_lshlrev_b32_e32 v88, 16, v148
	v_and_b32_e32 v89, 0xffff0000, v148
	v_lshlrev_b32_e32 v90, 16, v144
	v_and_b32_e32 v91, 0xffff0000, v144
	v_pk_fma_f32 v[84:85], v[84:85], v[88:89], v[90:91]
	v_lshlrev_b32_e32 v88, 16, v149
	v_and_b32_e32 v89, 0xffff0000, v149
	v_lshlrev_b32_e32 v90, 16, v145
	v_and_b32_e32 v91, 0xffff0000, v145
	v_pk_fma_f32 v[86:87], v[86:87], v[88:89], v[90:91]
	v_lshlrev_b32_e32 v88, 16, v150
	v_and_b32_e32 v89, 0xffff0000, v150
	v_lshlrev_b32_e32 v90, 16, v146
	v_and_b32_e32 v91, 0xffff0000, v146
	v_pk_fma_f32 v[88:89], v[80:81], v[88:89], v[90:91]
	v_lshlrev_b32_e32 v80, 16, v151
	v_and_b32_e32 v81, 0xffff0000, v151
	v_lshlrev_b32_e32 v90, 16, v147
	v_and_b32_e32 v91, 0xffff0000, v147
	v_pk_fma_f32 v[90:91], v[82:83], v[80:81], v[90:91]
	v_cvt_pk_bf16_f32 v80, v84, v85
	v_cvt_pk_bf16_f32 v81, v86, v87
	v_cvt_pk_bf16_f32 v82, v88, v89
	v_cvt_pk_bf16_f32 v83, v90, v91
	global_store_dwordx4 v[170:171], v[80:83], off offset:256
	s_nop 1
	v_lshlrev_b32_e32 v80, 16, v140
	v_and_b32_e32 v81, 0xffff0000, v140
	v_lshlrev_b32_e32 v82, 16, v136
	v_and_b32_e32 v83, 0xffff0000, v136
	v_pk_fma_f32 v[76:77], v[76:77], v[80:81], v[82:83]
	v_lshlrev_b32_e32 v80, 16, v141
	v_and_b32_e32 v81, 0xffff0000, v141
	v_lshlrev_b32_e32 v82, 16, v137
	v_and_b32_e32 v83, 0xffff0000, v137
	v_pk_fma_f32 v[78:79], v[78:79], v[80:81], v[82:83]
	v_lshlrev_b32_e32 v80, 16, v142
	v_and_b32_e32 v81, 0xffff0000, v142
	v_lshlrev_b32_e32 v82, 16, v138
	v_and_b32_e32 v83, 0xffff0000, v138
	v_pk_fma_f32 v[80:81], v[72:73], v[80:81], v[82:83]
	v_lshlrev_b32_e32 v72, 16, v143
	v_and_b32_e32 v73, 0xffff0000, v143
	v_lshlrev_b32_e32 v82, 16, v139
	v_and_b32_e32 v83, 0xffff0000, v139
	v_pk_fma_f32 v[82:83], v[74:75], v[72:73], v[82:83]
	v_cvt_pk_bf16_f32 v72, v76, v77
	v_cvt_pk_bf16_f32 v73, v78, v79
	v_cvt_pk_bf16_f32 v74, v80, v81
	v_cvt_pk_bf16_f32 v75, v82, v83
	global_store_dwordx4 v[168:169], v[72:75], off
	s_nop 1
	v_lshlrev_b32_e32 v72, 16, v132
	v_and_b32_e32 v73, 0xffff0000, v132
	v_lshlrev_b32_e32 v74, 16, v128
	v_and_b32_e32 v75, 0xffff0000, v128
	v_pk_fma_f32 v[68:69], v[68:69], v[72:73], v[74:75]
	v_lshlrev_b32_e32 v72, 16, v133
	v_and_b32_e32 v73, 0xffff0000, v133
	v_lshlrev_b32_e32 v74, 16, v129
	v_and_b32_e32 v75, 0xffff0000, v129
	v_pk_fma_f32 v[70:71], v[70:71], v[72:73], v[74:75]
	v_lshlrev_b32_e32 v72, 16, v134
	v_and_b32_e32 v73, 0xffff0000, v134
	v_lshlrev_b32_e32 v74, 16, v130
	v_and_b32_e32 v75, 0xffff0000, v130
	v_pk_fma_f32 v[72:73], v[64:65], v[72:73], v[74:75]
	v_lshlrev_b32_e32 v64, 16, v135
	v_and_b32_e32 v65, 0xffff0000, v135
	v_lshlrev_b32_e32 v74, 16, v131
	v_and_b32_e32 v75, 0xffff0000, v131
	v_pk_fma_f32 v[74:75], v[66:67], v[64:65], v[74:75]
	v_cvt_pk_bf16_f32 v64, v68, v69
	v_cvt_pk_bf16_f32 v65, v70, v71
	v_cvt_pk_bf16_f32 v66, v72, v73
	v_cvt_pk_bf16_f32 v67, v74, v75
	global_store_dwordx4 v[168:169], v[64:67], off offset:256
	s_nop 1
	v_add_u32_e32 v64, 0x80, v164
	v_ashrrev_i32_e32 v65, 31, v64
	v_lshlrev_b64 v[66:67], 12, v[64:65]
	v_lshl_add_u64 v[66:67], s[42:43], 0, v[66:67]
	v_lshlrev_b64 v[64:65], 11, v[64:65]
	v_lshl_add_u64 v[66:67], v[66:67], 0, v[166:167]
	v_lshl_add_u64 v[64:65], s[82:83], 0, v[64:65]
	global_load_dwordx4 v[92:95], v[66:67], off offset:2048
	v_lshl_add_u64 v[132:133], v[64:65], 0, v[166:167]
	global_load_dwordx4 v[96:99], v[132:133], off
	global_load_dwordx4 v[100:103], v[66:67], off offset:2304
	global_load_dwordx4 v[104:107], v[132:133], off offset:256
	v_add_u32_e32 v64, 0x90, v164
	v_ashrrev_i32_e32 v65, 31, v64
	v_lshlrev_b64 v[66:67], 12, v[64:65]
	v_lshl_add_u64 v[66:67], s[42:43], 0, v[66:67]
	v_lshlrev_b64 v[64:65], 11, v[64:65]
	v_lshl_add_u64 v[66:67], v[66:67], 0, v[166:167]
	v_lshl_add_u64 v[64:65], s[82:83], 0, v[64:65]
	global_load_dwordx4 v[108:111], v[66:67], off offset:2048
	v_lshl_add_u64 v[134:135], v[64:65], 0, v[166:167]
	global_load_dwordx4 v[112:115], v[134:135], off
	global_load_dwordx4 v[116:119], v[66:67], off offset:2304
	global_load_dwordx4 v[120:123], v[134:135], off offset:256
	v_add_u32_e32 v64, 0xa0, v164
	v_ashrrev_i32_e32 v65, 31, v64
	v_lshlrev_b64 v[66:67], 12, v[64:65]
	v_lshl_add_u64 v[66:67], s[42:43], 0, v[66:67]
	v_lshlrev_b64 v[64:65], 11, v[64:65]
	v_lshl_add_u64 v[64:65], s[82:83], 0, v[64:65]
	v_lshl_add_u64 v[66:67], v[66:67], 0, v[166:167]
	v_lshl_add_u64 v[90:91], v[64:65], 0, v[166:167]
	global_load_dwordx4 v[124:127], v[66:67], off offset:2048
	global_load_dwordx4 v[84:87], v[66:67], off offset:2304
	global_load_dwordx4 v[128:131], v[90:91], off
	global_load_dwordx4 v[80:83], v[90:91], off offset:256
	v_add_u32_e32 v64, 0xb0, v164
	v_ashrrev_i32_e32 v65, 31, v64
	v_lshlrev_b64 v[66:67], 12, v[64:65]
	v_lshl_add_u64 v[66:67], s[42:43], 0, v[66:67]
	v_lshlrev_b64 v[64:65], 11, v[64:65]
	v_lshl_add_u64 v[64:65], s[82:83], 0, v[64:65]
	v_lshl_add_u64 v[66:67], v[66:67], 0, v[166:167]
	v_lshl_add_u64 v[88:89], v[64:65], 0, v[166:167]
	global_load_dwordx4 v[76:79], v[66:67], off offset:2048
	global_load_dwordx4 v[68:71], v[66:67], off offset:2304
	global_load_dwordx4 v[72:75], v[88:89], off
	s_nop 0
	global_load_dwordx4 v[64:67], v[88:89], off offset:256
	s_waitcnt vmcnt(0)
	v_lshlrev_b32_e32 v136, 16, v92
	v_and_b32_e32 v137, 0xffff0000, v92
	v_lshlrev_b32_e32 v138, 16, v96
	v_and_b32_e32 v139, 0xffff0000, v96
	v_lshlrev_b32_e32 v92, 16, v93
	v_and_b32_e32 v93, 0xffff0000, v93
	v_lshlrev_b32_e32 v96, 16, v97
	v_and_b32_e32 v97, 0xffff0000, v97
	v_pk_fma_f32 v[62:63], v[62:63], v[92:93], v[96:97]
	v_lshlrev_b32_e32 v92, 16, v94
	v_and_b32_e32 v93, 0xffff0000, v94
	v_lshlrev_b32_e32 v96, 16, v98
	v_and_b32_e32 v97, 0xffff0000, v98
	v_pk_fma_f32 v[92:93], v[56:57], v[92:93], v[96:97]
	v_lshlrev_b32_e32 v56, 16, v95
	v_and_b32_e32 v57, 0xffff0000, v95
	v_lshlrev_b32_e32 v94, 16, v99
	v_and_b32_e32 v95, 0xffff0000, v99
	v_pk_fma_f32 v[60:61], v[60:61], v[136:137], v[138:139]
	v_pk_fma_f32 v[94:95], v[58:59], v[56:57], v[94:95]
	v_cvt_pk_bf16_f32 v56, v60, v61
	v_cvt_pk_bf16_f32 v57, v62, v63
	v_cvt_pk_bf16_f32 v58, v92, v93
	v_cvt_pk_bf16_f32 v59, v94, v95
	global_store_dwordx4 v[132:133], v[56:59], off
	s_nop 1
	v_lshlrev_b32_e32 v56, 16, v100
	v_and_b32_e32 v57, 0xffff0000, v100
	v_lshlrev_b32_e32 v58, 16, v104
	v_and_b32_e32 v59, 0xffff0000, v104
	v_pk_fma_f32 v[52:53], v[52:53], v[56:57], v[58:59]
	v_lshlrev_b32_e32 v56, 16, v101
	v_and_b32_e32 v57, 0xffff0000, v101
	v_lshlrev_b32_e32 v58, 16, v105
	v_and_b32_e32 v59, 0xffff0000, v105
	v_pk_fma_f32 v[54:55], v[54:55], v[56:57], v[58:59]
	v_lshlrev_b32_e32 v56, 16, v102
	v_and_b32_e32 v57, 0xffff0000, v102
	v_lshlrev_b32_e32 v58, 16, v106
	v_and_b32_e32 v59, 0xffff0000, v106
	v_pk_fma_f32 v[56:57], v[48:49], v[56:57], v[58:59]
	v_lshlrev_b32_e32 v48, 16, v103
	v_and_b32_e32 v49, 0xffff0000, v103
	v_lshlrev_b32_e32 v58, 16, v107
	v_and_b32_e32 v59, 0xffff0000, v107
	v_pk_fma_f32 v[58:59], v[50:51], v[48:49], v[58:59]
	v_cvt_pk_bf16_f32 v48, v52, v53
	v_cvt_pk_bf16_f32 v49, v54, v55
	v_cvt_pk_bf16_f32 v50, v56, v57
	v_cvt_pk_bf16_f32 v51, v58, v59
	global_store_dwordx4 v[132:133], v[48:51], off offset:256
	s_nop 1
	v_lshlrev_b32_e32 v48, 16, v108
	v_and_b32_e32 v49, 0xffff0000, v108
	v_lshlrev_b32_e32 v50, 16, v112
	v_and_b32_e32 v51, 0xffff0000, v112
	v_pk_fma_f32 v[44:45], v[44:45], v[48:49], v[50:51]
	v_lshlrev_b32_e32 v48, 16, v109
	v_and_b32_e32 v49, 0xffff0000, v109
	v_lshlrev_b32_e32 v50, 16, v113
	v_and_b32_e32 v51, 0xffff0000, v113
	v_pk_fma_f32 v[46:47], v[46:47], v[48:49], v[50:51]
	v_lshlrev_b32_e32 v48, 16, v110
	v_and_b32_e32 v49, 0xffff0000, v110
	v_lshlrev_b32_e32 v50, 16, v114
	v_and_b32_e32 v51, 0xffff0000, v114
	v_pk_fma_f32 v[48:49], v[40:41], v[48:49], v[50:51]
	v_lshlrev_b32_e32 v40, 16, v111
	v_and_b32_e32 v41, 0xffff0000, v111
	v_lshlrev_b32_e32 v50, 16, v115
	v_and_b32_e32 v51, 0xffff0000, v115
	v_pk_fma_f32 v[50:51], v[42:43], v[40:41], v[50:51]
	v_cvt_pk_bf16_f32 v40, v44, v45
	v_cvt_pk_bf16_f32 v41, v46, v47
	v_cvt_pk_bf16_f32 v42, v48, v49
	v_cvt_pk_bf16_f32 v43, v50, v51
	global_store_dwordx4 v[134:135], v[40:43], off
	s_nop 1
	v_lshlrev_b32_e32 v40, 16, v116
	v_and_b32_e32 v41, 0xffff0000, v116
	v_lshlrev_b32_e32 v42, 16, v120
	v_and_b32_e32 v43, 0xffff0000, v120
	v_pk_fma_f32 v[36:37], v[36:37], v[40:41], v[42:43]
	v_lshlrev_b32_e32 v40, 16, v117
	v_and_b32_e32 v41, 0xffff0000, v117
	v_lshlrev_b32_e32 v42, 16, v121
	v_and_b32_e32 v43, 0xffff0000, v121
	v_pk_fma_f32 v[38:39], v[38:39], v[40:41], v[42:43]
	v_lshlrev_b32_e32 v40, 16, v118
	v_and_b32_e32 v41, 0xffff0000, v118
	v_lshlrev_b32_e32 v42, 16, v122
	v_and_b32_e32 v43, 0xffff0000, v122
	v_pk_fma_f32 v[40:41], v[32:33], v[40:41], v[42:43]
	v_lshlrev_b32_e32 v32, 16, v119
	v_and_b32_e32 v33, 0xffff0000, v119
	v_lshlrev_b32_e32 v42, 16, v123
	v_and_b32_e32 v43, 0xffff0000, v123
	v_pk_fma_f32 v[42:43], v[34:35], v[32:33], v[42:43]
	v_cvt_pk_bf16_f32 v32, v36, v37
	v_cvt_pk_bf16_f32 v33, v38, v39
	v_cvt_pk_bf16_f32 v34, v40, v41
	v_cvt_pk_bf16_f32 v35, v42, v43
	global_store_dwordx4 v[134:135], v[32:35], off offset:256
	s_nop 1
	v_lshlrev_b32_e32 v32, 16, v124
	v_and_b32_e32 v33, 0xffff0000, v124
	v_lshlrev_b32_e32 v34, 16, v128
	v_and_b32_e32 v35, 0xffff0000, v128
	v_pk_fma_f32 v[28:29], v[28:29], v[32:33], v[34:35]
	v_lshlrev_b32_e32 v32, 16, v125
	v_and_b32_e32 v33, 0xffff0000, v125
	v_lshlrev_b32_e32 v34, 16, v129
	v_and_b32_e32 v35, 0xffff0000, v129
	v_pk_fma_f32 v[30:31], v[30:31], v[32:33], v[34:35]
	v_lshlrev_b32_e32 v32, 16, v126
	v_and_b32_e32 v33, 0xffff0000, v126
	v_lshlrev_b32_e32 v34, 16, v130
	v_and_b32_e32 v35, 0xffff0000, v130
	v_pk_fma_f32 v[32:33], v[24:25], v[32:33], v[34:35]
	v_lshlrev_b32_e32 v24, 16, v127
	v_and_b32_e32 v25, 0xffff0000, v127
	v_lshlrev_b32_e32 v34, 16, v131
	v_and_b32_e32 v35, 0xffff0000, v131
	v_pk_fma_f32 v[34:35], v[26:27], v[24:25], v[34:35]
	v_cvt_pk_bf16_f32 v24, v28, v29
	v_cvt_pk_bf16_f32 v25, v30, v31
	v_cvt_pk_bf16_f32 v26, v32, v33
	v_cvt_pk_bf16_f32 v27, v34, v35
	global_store_dwordx4 v[90:91], v[24:27], off
	s_nop 1
	v_lshlrev_b32_e32 v24, 16, v84
	v_and_b32_e32 v25, 0xffff0000, v84
	v_lshlrev_b32_e32 v26, 16, v80
	v_and_b32_e32 v27, 0xffff0000, v80
	v_pk_fma_f32 v[20:21], v[20:21], v[24:25], v[26:27]
	v_lshlrev_b32_e32 v24, 16, v85
	v_and_b32_e32 v25, 0xffff0000, v85
	v_lshlrev_b32_e32 v26, 16, v81
	v_and_b32_e32 v27, 0xffff0000, v81
	v_pk_fma_f32 v[22:23], v[22:23], v[24:25], v[26:27]
	v_lshlrev_b32_e32 v24, 16, v86
	v_and_b32_e32 v25, 0xffff0000, v86
	v_lshlrev_b32_e32 v26, 16, v82
	v_and_b32_e32 v27, 0xffff0000, v82
	v_pk_fma_f32 v[24:25], v[16:17], v[24:25], v[26:27]
	v_lshlrev_b32_e32 v16, 16, v87
	v_and_b32_e32 v17, 0xffff0000, v87
	v_lshlrev_b32_e32 v26, 16, v83
	v_and_b32_e32 v27, 0xffff0000, v83
	v_pk_fma_f32 v[26:27], v[18:19], v[16:17], v[26:27]
	v_cvt_pk_bf16_f32 v16, v20, v21
	v_cvt_pk_bf16_f32 v17, v22, v23
	v_cvt_pk_bf16_f32 v18, v24, v25
	v_cvt_pk_bf16_f32 v19, v26, v27
	global_store_dwordx4 v[90:91], v[16:19], off offset:256
	s_nop 1
	v_lshlrev_b32_e32 v16, 16, v76
	v_and_b32_e32 v17, 0xffff0000, v76
	v_lshlrev_b32_e32 v18, 16, v72
	v_and_b32_e32 v19, 0xffff0000, v72
	v_pk_fma_f32 v[12:13], v[12:13], v[16:17], v[18:19]
	v_lshlrev_b32_e32 v16, 16, v77
	v_and_b32_e32 v17, 0xffff0000, v77
	v_lshlrev_b32_e32 v18, 16, v73
	v_and_b32_e32 v19, 0xffff0000, v73
	v_pk_fma_f32 v[14:15], v[14:15], v[16:17], v[18:19]
	v_lshlrev_b32_e32 v16, 16, v78
	v_and_b32_e32 v17, 0xffff0000, v78
	v_lshlrev_b32_e32 v18, 16, v74
	v_and_b32_e32 v19, 0xffff0000, v74
	v_pk_fma_f32 v[16:17], v[8:9], v[16:17], v[18:19]
	v_lshlrev_b32_e32 v8, 16, v79
	v_and_b32_e32 v9, 0xffff0000, v79
	v_lshlrev_b32_e32 v18, 16, v75
	v_and_b32_e32 v19, 0xffff0000, v75
	v_pk_fma_f32 v[18:19], v[10:11], v[8:9], v[18:19]
	v_cvt_pk_bf16_f32 v8, v12, v13
	v_cvt_pk_bf16_f32 v9, v14, v15
	v_cvt_pk_bf16_f32 v10, v16, v17
	v_cvt_pk_bf16_f32 v11, v18, v19
	global_store_dwordx4 v[88:89], v[8:11], off
	s_nop 1
	v_lshlrev_b32_e32 v8, 16, v68
	v_and_b32_e32 v9, 0xffff0000, v68
	v_lshlrev_b32_e32 v10, 16, v64
	v_and_b32_e32 v11, 0xffff0000, v64
	v_pk_fma_f32 v[4:5], v[4:5], v[8:9], v[10:11]
	v_lshlrev_b32_e32 v8, 16, v69
	v_and_b32_e32 v9, 0xffff0000, v69
	v_lshlrev_b32_e32 v10, 16, v65
	v_and_b32_e32 v11, 0xffff0000, v65
	v_pk_fma_f32 v[6:7], v[6:7], v[8:9], v[10:11]
	v_lshlrev_b32_e32 v8, 16, v70
	v_and_b32_e32 v9, 0xffff0000, v70
	v_lshlrev_b32_e32 v10, 16, v66
	v_and_b32_e32 v11, 0xffff0000, v66
	v_pk_fma_f32 v[8:9], v[0:1], v[8:9], v[10:11]
	v_lshlrev_b32_e32 v0, 16, v71
	v_and_b32_e32 v1, 0xffff0000, v71
	v_lshlrev_b32_e32 v10, 16, v67
	v_and_b32_e32 v11, 0xffff0000, v67
	v_pk_fma_f32 v[10:11], v[2:3], v[0:1], v[10:11]
	v_cvt_pk_bf16_f32 v0, v4, v5
	v_cvt_pk_bf16_f32 v1, v6, v7
	v_cvt_pk_bf16_f32 v2, v8, v9
	v_cvt_pk_bf16_f32 v3, v10, v11
	global_store_dwordx4 v[88:89], v[0:3], off offset:256
	s_cbranch_vccz .LBB0_1277
	s_waitcnt vmcnt(0)
	s_cmpk_gt_u32 s26, 0xff
	s_cbranch_scc1 .LBB0_1289
	s_barrier

.LBB0_1356:
	ds_read_b128 v[144:147], v190
	ds_read_b128 v[148:151], v190 offset:1024
	ds_read_b128 v[166:169], v190 offset:2048
	ds_read_b128 v[170:173], v190 offset:3072
	ds_read_b128 v[174:177], v190 offset:4096
	ds_read_b128 v[180:183], v190 offset:5120
	ds_read_b128 v[184:187], v190 offset:6144
	ds_read_b128 v[194:197], v190 offset:7168
	ds_read_b128 v[128:131], v189
	ds_read_b128 v[132:135], v189 offset:1024
	ds_read_b128 v[136:139], v189 offset:2048
	ds_read_b128 v[140:143], v189 offset:3072
	s_add_u32 s24, s10, 0xfffc0080
	s_addc_u32 s25, s11, -1
	s_cmp_eq_u32 s47, 12
	s_cselect_b32 s27, s15, s25
	s_cselect_b32 s26, s29, s24
	s_cselect_b32 s25, s17, s46
	s_cselect_b32 s24, s44, s45
	v_lshl_add_u64 v[198:199], s[10:11], 0, v[162:163]
	s_add_i32 m0, s7, 0xc000
	s_nop 0
	global_load_lds_dwordx4 v[198:199], off
	v_lshl_add_u64 v[198:199], s[10:11], 0, v[164:165]
	s_add_i32 m0, s7, 0xe000
	s_nop 0
	global_load_lds_dwordx4 v[198:199], off
	s_waitcnt lgkmcnt(0)
	s_barrier
	v_mfma_f32_16x16x32_bf16 v[124:127], v[128:131], v[144:147], v[124:127]
	v_mfma_f32_16x16x32_bf16 v[120:123], v[136:139], v[144:147], v[120:123]
	v_mfma_f32_16x16x32_bf16 v[108:111], v[128:131], v[166:169], v[108:111]
	v_mfma_f32_16x16x32_bf16 v[104:107], v[136:139], v[166:169], v[104:107]
	v_mfma_f32_16x16x32_bf16 v[92:95], v[128:131], v[174:177], v[92:95]
	v_mfma_f32_16x16x32_bf16 v[88:91], v[136:139], v[174:177], v[88:91]
	v_mfma_f32_16x16x32_bf16 v[76:79], v[128:131], v[184:187], v[76:79]
	v_mfma_f32_16x16x32_bf16 v[72:75], v[136:139], v[184:187], v[72:75]
	v_mfma_f32_16x16x32_bf16 v[124:127], v[132:135], v[148:151], v[124:127]
	v_mfma_f32_16x16x32_bf16 v[120:123], v[140:143], v[148:151], v[120:123]
	v_mfma_f32_16x16x32_bf16 v[108:111], v[132:135], v[170:173], v[108:111]
	v_mfma_f32_16x16x32_bf16 v[104:107], v[140:143], v[170:173], v[104:107]
	v_mfma_f32_16x16x32_bf16 v[92:95], v[132:135], v[180:183], v[92:95]
	v_mfma_f32_16x16x32_bf16 v[88:91], v[140:143], v[180:183], v[88:91]
	v_mfma_f32_16x16x32_bf16 v[76:79], v[132:135], v[194:197], v[76:79]
	v_mfma_f32_16x16x32_bf16 v[72:75], v[140:143], v[194:197], v[72:75]
	s_barrier
	s_add_i32 s48, s41, s33
	v_lshl_add_u64 v[214:215], s[24:25], 0, v[156:157]
	s_mov_b32 m0, s48
	ds_read_b128 v[198:201], v191
	ds_read_b128 v[202:205], v191 offset:1024
	ds_read_b128 v[206:209], v191 offset:2048
	ds_read_b128 v[210:213], v191 offset:3072
	global_load_lds_dwordx4 v[214:215], off
	v_lshl_add_u64 v[216:217], s[24:25], 0, v[152:153]
	s_add_i32 m0, s48, 0x2000
	s_nop 0
	global_load_lds_dwordx4 v[216:217], off
	s_barrier
	s_waitcnt lgkmcnt(0)
	v_mfma_f32_16x16x32_bf16 v[116:119], v[198:201], v[144:147], v[116:119]
	v_mfma_f32_16x16x32_bf16 v[112:115], v[206:209], v[144:147], v[112:115]
	v_mfma_f32_16x16x32_bf16 v[100:103], v[198:201], v[166:169], v[100:103]
	v_mfma_f32_16x16x32_bf16 v[96:99], v[206:209], v[166:169], v[96:99]
	v_mfma_f32_16x16x32_bf16 v[84:87], v[198:201], v[174:177], v[84:87]
	v_mfma_f32_16x16x32_bf16 v[80:83], v[206:209], v[174:177], v[80:83]
	v_mfma_f32_16x16x32_bf16 v[68:71], v[198:201], v[184:187], v[68:71]
	v_mfma_f32_16x16x32_bf16 v[64:67], v[206:209], v[184:187], v[64:67]
	v_mfma_f32_16x16x32_bf16 v[116:119], v[202:205], v[148:151], v[116:119]
	v_mfma_f32_16x16x32_bf16 v[112:115], v[210:213], v[148:151], v[112:115]
	v_mfma_f32_16x16x32_bf16 v[100:103], v[202:205], v[170:173], v[100:103]
	v_mfma_f32_16x16x32_bf16 v[96:99], v[210:213], v[170:173], v[96:99]
	v_mfma_f32_16x16x32_bf16 v[84:87], v[202:205], v[180:183], v[84:87]
	v_mfma_f32_16x16x32_bf16 v[80:83], v[210:213], v[180:183], v[80:83]
	v_mfma_f32_16x16x32_bf16 v[68:71], v[202:205], v[194:197], v[68:71]
	v_mfma_f32_16x16x32_bf16 v[64:67], v[210:213], v[194:197], v[64:67]
	s_mov_b32 m0, s7
	v_lshl_add_u64 v[218:219], s[26:27], 0, v[158:159]
	s_barrier
	ds_read_b128 v[144:147], v190 offset:16384
	ds_read_b128 v[148:151], v190 offset:17408
	ds_read_b128 v[166:169], v190 offset:18432
	ds_read_b128 v[170:173], v190 offset:19456
	ds_read_b128 v[174:177], v190 offset:20480
	ds_read_b128 v[180:183], v190 offset:21504
	ds_read_b128 v[184:187], v190 offset:22528
	ds_read_b128 v[194:197], v190 offset:23552
	global_load_lds_dwordx4 v[218:219], off
	v_lshl_add_u64 v[222:223], s[26:27], 0, v[154:155]
	s_mov_b32 m0, s35
	s_nop 0
	global_load_lds_dwordx4 v[222:223], off
	s_barrier
	s_waitcnt lgkmcnt(0)
	v_mfma_f32_16x16x32_bf16 v[60:63], v[128:131], v[144:147], v[60:63]
	v_mfma_f32_16x16x32_bf16 v[56:59], v[136:139], v[144:147], v[56:59]
	v_mfma_f32_16x16x32_bf16 v[44:47], v[128:131], v[166:169], v[44:47]
	v_mfma_f32_16x16x32_bf16 v[40:43], v[136:139], v[166:169], v[40:43]
	v_mfma_f32_16x16x32_bf16 v[28:31], v[128:131], v[174:177], v[28:31]
	v_mfma_f32_16x16x32_bf16 v[24:27], v[136:139], v[174:177], v[24:27]
	v_mfma_f32_16x16x32_bf16 v[12:15], v[128:131], v[184:187], v[12:15]
	v_mfma_f32_16x16x32_bf16 v[8:11], v[136:139], v[184:187], v[8:11]
	v_mfma_f32_16x16x32_bf16 v[60:63], v[132:135], v[148:151], v[60:63]
	v_mfma_f32_16x16x32_bf16 v[56:59], v[140:143], v[148:151], v[56:59]
	v_mfma_f32_16x16x32_bf16 v[44:47], v[132:135], v[170:173], v[44:47]
	v_mfma_f32_16x16x32_bf16 v[40:43], v[140:143], v[170:173], v[40:43]
	v_mfma_f32_16x16x32_bf16 v[28:31], v[132:135], v[180:183], v[28:31]
	v_mfma_f32_16x16x32_bf16 v[24:27], v[140:143], v[180:183], v[24:27]
	v_mfma_f32_16x16x32_bf16 v[12:15], v[132:135], v[194:197], v[12:15]
	v_mfma_f32_16x16x32_bf16 v[8:11], v[140:143], v[194:197], v[8:11]
	s_barrier
	s_add_u32 s48, s24, 0x40000
	s_addc_u32 s49, s25, 0
	s_add_i32 s50, s42, s33
	v_lshl_add_u64 v[128:129], s[48:49], 0, v[156:157]
	s_mov_b32 m0, s50
	s_nop 0
	global_load_lds_dwordx4 v[128:129], off
	v_lshl_add_u64 v[128:129], s[48:49], 0, v[152:153]
	s_add_i32 m0, s50, 0x2000
	s_nop 0
	global_load_lds_dwordx4 v[128:129], off
	s_waitcnt vmcnt(6)
	s_barrier
	v_mfma_f32_16x16x32_bf16 v[52:55], v[198:201], v[144:147], v[52:55]
	v_mfma_f32_16x16x32_bf16 v[48:51], v[206:209], v[144:147], v[48:51]
	v_mfma_f32_16x16x32_bf16 v[36:39], v[198:201], v[166:169], v[36:39]
	v_mfma_f32_16x16x32_bf16 v[32:35], v[206:209], v[166:169], v[32:35]
	v_mfma_f32_16x16x32_bf16 v[20:23], v[198:201], v[174:177], v[20:23]
	v_mfma_f32_16x16x32_bf16 v[16:19], v[206:209], v[174:177], v[16:19]
	v_mfma_f32_16x16x32_bf16 v[4:7], v[198:201], v[184:187], v[4:7]
	v_mfma_f32_16x16x32_bf16 v[0:3], v[206:209], v[184:187], v[0:3]
	v_mfma_f32_16x16x32_bf16 v[52:55], v[202:205], v[148:151], v[52:55]
	v_mfma_f32_16x16x32_bf16 v[48:51], v[210:213], v[148:151], v[48:51]
	v_mfma_f32_16x16x32_bf16 v[36:39], v[202:205], v[170:173], v[36:39]
	v_mfma_f32_16x16x32_bf16 v[32:35], v[210:213], v[170:173], v[32:35]
	v_mfma_f32_16x16x32_bf16 v[20:23], v[202:205], v[180:183], v[20:23]
	v_mfma_f32_16x16x32_bf16 v[16:19], v[210:213], v[180:183], v[16:19]
	v_mfma_f32_16x16x32_bf16 v[4:7], v[202:205], v[194:197], v[4:7]
	v_mfma_f32_16x16x32_bf16 v[0:3], v[210:213], v[194:197], v[0:3]
	s_add_i32 s48, 0, 0x18000
	v_add_u32_e32 v140, s48, v188
	s_barrier
	ds_read_b128 v[144:147], v190 offset:32768
	ds_read_b128 v[148:151], v190 offset:33792
	ds_read_b128 v[166:169], v190 offset:34816
	ds_read_b128 v[170:173], v190 offset:35840
	ds_read_b128 v[174:177], v190 offset:36864
	ds_read_b128 v[180:183], v190 offset:37888
	ds_read_b128 v[184:187], v190 offset:38912
	ds_read_b128 v[194:197], v190 offset:39936
	ds_read_b128 v[128:131], v140
	ds_read_b128 v[132:135], v140 offset:1024
	ds_read_b128 v[136:139], v140 offset:2048
	ds_read_b128 v[140:143], v140 offset:3072
	s_add_u32 s26, s26, 0x40000
	s_addc_u32 s27, s27, 0
	s_mov_b32 m0, s36
	v_lshl_add_u64 v[198:199], s[26:27], 0, v[158:159]
	global_load_lds_dwordx4 v[198:199], off
	v_lshl_add_u64 v[198:199], s[26:27], 0, v[154:155]
	s_mov_b32 m0, s37
	s_nop 0
	global_load_lds_dwordx4 v[198:199], off
	s_waitcnt lgkmcnt(0)
	s_barrier
	v_mfma_f32_16x16x32_bf16 v[124:127], v[128:131], v[144:147], v[124:127]
	v_mfma_f32_16x16x32_bf16 v[120:123], v[136:139], v[144:147], v[120:123]
	v_mfma_f32_16x16x32_bf16 v[108:111], v[128:131], v[166:169], v[108:111]
	v_mfma_f32_16x16x32_bf16 v[104:107], v[136:139], v[166:169], v[104:107]
	v_mfma_f32_16x16x32_bf16 v[92:95], v[128:131], v[174:177], v[92:95]
	v_mfma_f32_16x16x32_bf16 v[88:91], v[136:139], v[174:177], v[88:91]
	v_mfma_f32_16x16x32_bf16 v[76:79], v[128:131], v[184:187], v[76:79]
	v_mfma_f32_16x16x32_bf16 v[72:75], v[136:139], v[184:187], v[72:75]
	v_mfma_f32_16x16x32_bf16 v[124:127], v[132:135], v[148:151], v[124:127]
	v_mfma_f32_16x16x32_bf16 v[120:123], v[140:143], v[148:151], v[120:123]
	v_mfma_f32_16x16x32_bf16 v[108:111], v[132:135], v[170:173], v[108:111]
	v_mfma_f32_16x16x32_bf16 v[104:107], v[140:143], v[170:173], v[104:107]
	v_mfma_f32_16x16x32_bf16 v[92:95], v[132:135], v[180:183], v[92:95]
	v_mfma_f32_16x16x32_bf16 v[88:91], v[140:143], v[180:183], v[88:91]
	v_mfma_f32_16x16x32_bf16 v[76:79], v[132:135], v[194:197], v[76:79]
	v_mfma_f32_16x16x32_bf16 v[72:75], v[140:143], v[194:197], v[72:75]
	s_barrier
	s_add_i32 s26, 0, 0x1c000
	s_add_i32 s27, s48, s33
	v_add_u32_e32 v193, s26, v188
	v_lshl_add_u64 v[214:215], v[214:215], 0, s[12:13]
	s_mov_b32 m0, s27
	ds_read_b128 v[198:201], v193
	ds_read_b128 v[202:205], v193 offset:1024
	ds_read_b128 v[206:209], v193 offset:2048
	ds_read_b128 v[210:213], v193 offset:3072
	global_load_lds_dwordx4 v[214:215], off
	v_lshl_add_u64 v[214:215], v[216:217], 0, s[12:13]
	s_add_i32 m0, s27, 0x2000
	s_nop 0
	global_load_lds_dwordx4 v[214:215], off
	s_barrier
	s_waitcnt lgkmcnt(0)
	v_mfma_f32_16x16x32_bf16 v[116:119], v[198:201], v[144:147], v[116:119]
	v_mfma_f32_16x16x32_bf16 v[112:115], v[206:209], v[144:147], v[112:115]
	v_mfma_f32_16x16x32_bf16 v[100:103], v[198:201], v[166:169], v[100:103]
	v_mfma_f32_16x16x32_bf16 v[96:99], v[206:209], v[166:169], v[96:99]
	v_mfma_f32_16x16x32_bf16 v[84:87], v[198:201], v[174:177], v[84:87]
	v_mfma_f32_16x16x32_bf16 v[80:83], v[206:209], v[174:177], v[80:83]
	v_mfma_f32_16x16x32_bf16 v[68:71], v[198:201], v[184:187], v[68:71]
	v_mfma_f32_16x16x32_bf16 v[64:67], v[206:209], v[184:187], v[64:67]
	v_mfma_f32_16x16x32_bf16 v[116:119], v[202:205], v[148:151], v[116:119]
	v_mfma_f32_16x16x32_bf16 v[112:115], v[210:213], v[148:151], v[112:115]
	v_mfma_f32_16x16x32_bf16 v[100:103], v[202:205], v[170:173], v[100:103]
	v_mfma_f32_16x16x32_bf16 v[96:99], v[210:213], v[170:173], v[96:99]
	v_mfma_f32_16x16x32_bf16 v[84:87], v[202:205], v[180:183], v[84:87]
	v_mfma_f32_16x16x32_bf16 v[80:83], v[210:213], v[180:183], v[80:83]
	v_mfma_f32_16x16x32_bf16 v[68:71], v[202:205], v[194:197], v[68:71]
	v_mfma_f32_16x16x32_bf16 v[64:67], v[210:213], v[194:197], v[64:67]
	s_mov_b32 m0, s39
	v_lshl_add_u64 v[214:215], v[218:219], 0, s[12:13]
	s_barrier
	ds_read_b128 v[144:147], v190 offset:49152
	ds_read_b128 v[148:151], v190 offset:50176
	ds_read_b128 v[166:169], v190 offset:51200
	ds_read_b128 v[170:173], v190 offset:52224
	ds_read_b128 v[174:177], v190 offset:53248
	ds_read_b128 v[180:183], v190 offset:54272
	ds_read_b128 v[184:187], v190 offset:55296
	ds_read_b128 v[194:197], v190 offset:56320
	global_load_lds_dwordx4 v[214:215], off
	v_lshl_add_u64 v[214:215], v[222:223], 0, s[12:13]
	s_mov_b32 m0, s40
	s_nop 0
	global_load_lds_dwordx4 v[214:215], off
	s_barrier
	s_waitcnt lgkmcnt(0)
	v_mfma_f32_16x16x32_bf16 v[60:63], v[128:131], v[144:147], v[60:63]
	v_mfma_f32_16x16x32_bf16 v[56:59], v[136:139], v[144:147], v[56:59]
	v_mfma_f32_16x16x32_bf16 v[44:47], v[128:131], v[166:169], v[44:47]
	v_mfma_f32_16x16x32_bf16 v[40:43], v[136:139], v[166:169], v[40:43]
	v_mfma_f32_16x16x32_bf16 v[28:31], v[128:131], v[174:177], v[28:31]
	v_mfma_f32_16x16x32_bf16 v[24:27], v[136:139], v[174:177], v[24:27]
	v_mfma_f32_16x16x32_bf16 v[12:15], v[128:131], v[184:187], v[12:15]
	v_mfma_f32_16x16x32_bf16 v[8:11], v[136:139], v[184:187], v[8:11]
	v_mfma_f32_16x16x32_bf16 v[60:63], v[132:135], v[148:151], v[60:63]
	v_mfma_f32_16x16x32_bf16 v[56:59], v[140:143], v[148:151], v[56:59]
	v_mfma_f32_16x16x32_bf16 v[44:47], v[132:135], v[170:173], v[44:47]
	v_mfma_f32_16x16x32_bf16 v[40:43], v[140:143], v[170:173], v[40:43]
	v_mfma_f32_16x16x32_bf16 v[28:31], v[132:135], v[180:183], v[28:31]
	v_mfma_f32_16x16x32_bf16 v[24:27], v[140:143], v[180:183], v[24:27]
	v_mfma_f32_16x16x32_bf16 v[12:15], v[132:135], v[194:197], v[12:15]
	v_mfma_f32_16x16x32_bf16 v[8:11], v[140:143], v[194:197], v[8:11]
	s_barrier
	s_add_u32 s24, s24, 0x40080
	s_addc_u32 s25, s25, 0
	s_add_i32 s26, s26, s33
	v_lshl_add_u64 v[128:129], s[24:25], 0, v[156:157]
	s_mov_b32 m0, s26
	s_nop 0
	global_load_lds_dwordx4 v[128:129], off
	v_lshl_add_u64 v[128:129], s[24:25], 0, v[152:153]
	s_add_i32 m0, s26, 0x2000
	s_nop 0
	global_load_lds_dwordx4 v[128:129], off
	s_waitcnt vmcnt(6)
	s_barrier
	v_mfma_f32_16x16x32_bf16 v[52:55], v[198:201], v[144:147], v[52:55]
	v_mfma_f32_16x16x32_bf16 v[48:51], v[206:209], v[144:147], v[48:51]
	v_mfma_f32_16x16x32_bf16 v[36:39], v[198:201], v[166:169], v[36:39]
	v_mfma_f32_16x16x32_bf16 v[32:35], v[206:209], v[166:169], v[32:35]
	v_mfma_f32_16x16x32_bf16 v[20:23], v[198:201], v[174:177], v[20:23]
	v_mfma_f32_16x16x32_bf16 v[16:19], v[206:209], v[174:177], v[16:19]
	v_mfma_f32_16x16x32_bf16 v[4:7], v[198:201], v[184:187], v[4:7]
	v_mfma_f32_16x16x32_bf16 v[0:3], v[206:209], v[184:187], v[0:3]
	v_mfma_f32_16x16x32_bf16 v[52:55], v[202:205], v[148:151], v[52:55]
	v_mfma_f32_16x16x32_bf16 v[48:51], v[210:213], v[148:151], v[48:51]
	v_mfma_f32_16x16x32_bf16 v[36:39], v[202:205], v[170:173], v[36:39]
	v_mfma_f32_16x16x32_bf16 v[32:35], v[210:213], v[170:173], v[32:35]
	v_mfma_f32_16x16x32_bf16 v[20:23], v[202:205], v[180:183], v[20:23]
	v_mfma_f32_16x16x32_bf16 v[16:19], v[210:213], v[180:183], v[16:19]
	v_mfma_f32_16x16x32_bf16 v[4:7], v[202:205], v[194:197], v[4:7]
	v_mfma_f32_16x16x32_bf16 v[0:3], v[210:213], v[194:197], v[0:3]
	s_add_i32 s47, s47, 2
	s_add_u32 s10, s10, 0x100
	s_addc_u32 s11, s11, 0
	s_add_u32 s45, s45, 0x100
	s_addc_u32 s46, s46, 0
	s_cmp_gt_u32 s47, 13
	s_barrier
	s_cbranch_scc0 .LBB0_1356
	s_lshl_b32 s24, s4, 8
	s_ashr_i32 s25, s24, 31
	s_lshl_b32 s10, s4, 2
	s_nop 0
	v_lshl_add_u32 v166, s28, 8, v179
	s_ashr_i32 s11, s10, 31
	s_lshl_b64 s[28:29], s[24:25], 1
	v_readlane_b32 s50, v253, 40
	v_readlane_b32 s51, v253, 41
	s_add_u32 s26, s50, s28
	v_ashrrev_i32_e32 v167, 31, v166
	s_addc_u32 s27, s51, s29
	v_lshlrev_b64 v[204:205], 11, v[166:167]
	v_lshl_add_u64 v[128:129], s[26:27], 0, v[204:205]
	v_lshl_add_u64 v[206:207], v[128:129], 0, v[160:161]
	global_load_dwordx4 v[196:199], v[206:207], off
	global_load_dwordx4 v[200:203], v[206:207], off offset:256
	v_or_b32_e32 v182, 16, v166
	v_or_b32_e32 v174, 32, v166
	v_or_b32_e32 v168, 48, v166
	v_ashrrev_i32_e32 v183, 31, v182
	v_ashrrev_i32_e32 v175, 31, v174
	v_ashrrev_i32_e32 v169, 31, v168
	v_lshlrev_b64 v[186:187], 11, v[182:183]
	v_lshlrev_b64 v[180:181], 11, v[174:175]
	v_lshlrev_b64 v[172:173], 11, v[168:169]
	v_lshl_add_u64 v[128:129], s[26:27], 0, v[186:187]
	v_lshl_add_u64 v[130:131], s[26:27], 0, v[180:181]
	v_lshl_add_u64 v[132:133], s[26:27], 0, v[172:173]
	v_lshl_add_u64 v[184:185], v[128:129], 0, v[160:161]
	v_lshl_add_u64 v[176:177], v[130:131], 0, v[160:161]
	v_lshl_add_u64 v[170:171], v[132:133], 0, v[160:161]
	global_load_dwordx4 v[148:151], v[184:185], off
	global_load_dwordx4 v[144:147], v[184:185], off offset:256
	global_load_dwordx4 v[140:143], v[176:177], off
	global_load_dwordx4 v[136:139], v[176:177], off offset:256
	global_load_dwordx4 v[132:135], v[170:171], off
	global_load_dwordx4 v[128:131], v[170:171], off offset:256
	v_and_b32_e32 v194, 64, v192
	v_xor_b32_e32 v193, 16, v192
	v_add_u32_e32 v194, 64, v194
	v_cmp_lt_i32_e32 vcc, v193, v194
	v_xor_b32_e32 v195, 32, v192
	v_lshl_add_u64 v[204:205], s[50:51], 0, v[204:205]
	v_cndmask_b32_e32 v193, v192, v193, vcc
	v_cmp_lt_i32_e32 vcc, v195, v194
	v_lshlrev_b32_e32 v194, 2, v193
	s_nop 0
	v_cndmask_b32_e32 v195, v192, v195, vcc
	v_lshlrev_b32_e32 v193, 2, v195
	s_nop 7
	s_nop 3
	s_waitcnt vmcnt(0)
	v_lshlrev_b32_e32 v210, 16, v198
	v_and_b32_e32 v211, 0xffff0000, v198
	v_lshlrev_b32_e32 v208, 16, v196
	v_and_b32_e32 v209, 0xffff0000, v196
	v_lshlrev_b32_e32 v198, 16, v199
	v_and_b32_e32 v199, 0xffff0000, v199
	v_lshlrev_b32_e32 v214, 16, v202
	v_and_b32_e32 v215, 0xffff0000, v202
	v_lshlrev_b32_e32 v202, 16, v203
	v_and_b32_e32 v203, 0xffff0000, v203
	v_pk_add_f32 v[120:121], v[120:121], v[210:211]
	v_lshlrev_b32_e32 v196, 16, v197
	v_and_b32_e32 v197, 0xffff0000, v197
	v_pk_add_f32 v[124:125], v[124:125], v[208:209]
	v_pk_add_f32 v[122:123], v[122:123], v[198:199]
	v_pk_add_f32 v[198:199], v[114:115], v[202:203]
	v_cvt_pk_bf16_f32 v114, v120, v121
	v_pk_mul_f32 v[120:121], v[120:121], v[120:121]
	v_pk_add_f32 v[126:127], v[126:127], v[196:197]
	v_cvt_pk_bf16_f32 v115, v122, v123
	v_pk_mul_f32 v[122:123], v[122:123], v[122:123]
	v_pk_fma_f32 v[120:121], v[124:125], v[124:125], v[120:121]
	v_lshlrev_b32_e32 v212, 16, v200
	v_and_b32_e32 v213, 0xffff0000, v200
	v_lshlrev_b32_e32 v200, 16, v201
	v_and_b32_e32 v201, 0xffff0000, v201
	v_pk_add_f32 v[196:197], v[112:113], v[214:215]
	v_pk_fma_f32 v[122:123], v[126:127], v[126:127], v[122:123]
	v_add_f32_e32 v120, v120, v121
	v_pk_add_f32 v[116:117], v[116:117], v[212:213]
	v_pk_add_f32 v[118:119], v[118:119], v[200:201]
	v_pk_mul_f32 v[200:201], v[196:197], v[196:197]
	v_add_f32_e32 v120, v122, v120
	v_cvt_pk_bf16_f32 v112, v124, v125
	v_pk_fma_f32 v[124:125], v[116:117], v[116:117], v[200:201]
	v_add_f32_e32 v120, v123, v120
	v_pk_mul_f32 v[202:203], v[198:199], v[198:199]
	v_add_f32_e32 v120, v124, v120
	v_cvt_pk_bf16_f32 v113, v126, v127
	v_pk_fma_f32 v[126:127], v[118:119], v[118:119], v[202:203]
	v_add_f32_e32 v120, v125, v120
	v_add_f32_e32 v120, v126, v120
	v_add_f32_e32 v122, v127, v120
	ds_bpermute_b32 v123, v194, v122
	global_store_dwordx4 v[206:207], v[112:115], off
	v_lshl_add_u64 v[120:121], v[204:205], 0, s[28:29]
	s_nop 0
	v_cvt_pk_bf16_f32 v114, v116, v117
	s_waitcnt lgkmcnt(0)
	v_add_f32_e32 v112, v122, v123
	ds_bpermute_b32 v113, v193, v112
	v_cvt_pk_bf16_f32 v115, v118, v119
	v_cvt_pk_bf16_f32 v116, v196, v197
	v_cvt_pk_bf16_f32 v117, v198, v199
	v_lshl_add_u64 v[118:119], v[120:121], 0, v[160:161]
	global_store_dwordx4 v[118:119], v[114:117], off offset:256
	s_and_saveexec_b64 s[28:29], s[0:1]
	s_cbranch_execz .LBB0_1359
	s_waitcnt lgkmcnt(0)
	v_add_f32_e32 v114, v112, v113
	v_lshlrev_b64 v[112:113], 6, v[166:167]
	v_lshl_add_u64 v[112:113], s[86:87], 0, v[112:113]
	v_lshl_add_u64 v[112:113], s[10:11], 2, v[112:113]
	s_lshl_b32 s4, s38, 2
	v_lshl_add_u64 v[112:113], v[112:113], 0, s[4:5]
	global_store_dword v[112:113], v114, off

.LBB0_1441:
	ds_read_b128 v[184:187], v165
	ds_read_b128 v[188:191], v165 offset:1024
	ds_read_b128 v[192:195], v165 offset:2048
	ds_read_b128 v[196:199], v165 offset:3072
	ds_read_b128 v[200:203], v165 offset:4096
	ds_read_b128 v[204:207], v165 offset:5120
	ds_read_b128 v[208:211], v165 offset:6144
	ds_read_b128 v[212:215], v165 offset:7168
	ds_read_b128 v[144:147], v161
	ds_read_b128 v[148:151], v161 offset:1024
	ds_read_b128 v[172:175], v161 offset:2048
	ds_read_b128 v[180:183], v161 offset:3072
	s_add_u32 s4, s0, 0xfffc0080
	s_addc_u32 s5, s1, -1
	s_cmp_eq_u32 s45, 12
	s_cselect_b32 s11, s19, s5
	s_cselect_b32 s10, s41, s4
	s_cselect_b32 s5, s21, s44
	s_cselect_b32 s4, s42, s43
	v_lshl_add_u64 v[154:155], s[0:1], 0, v[140:141]
	s_add_i32 m0, s17, 0xc000
	s_nop 0
	global_load_lds_dwordx4 v[154:155], off
	v_lshl_add_u64 v[154:155], s[0:1], 0, v[142:143]
	s_add_i32 m0, s17, 0xe000
	s_nop 0
	global_load_lds_dwordx4 v[154:155], off
	s_waitcnt lgkmcnt(0)
	s_barrier
	v_mfma_f32_16x16x32_bf16 v[124:127], v[144:147], v[184:187], v[124:127]
	v_mfma_f32_16x16x32_bf16 v[120:123], v[172:175], v[184:187], v[120:123]
	v_mfma_f32_16x16x32_bf16 v[108:111], v[144:147], v[192:195], v[108:111]
	v_mfma_f32_16x16x32_bf16 v[104:107], v[172:175], v[192:195], v[104:107]
	v_mfma_f32_16x16x32_bf16 v[92:95], v[144:147], v[200:203], v[92:95]
	v_mfma_f32_16x16x32_bf16 v[88:91], v[172:175], v[200:203], v[88:91]
	v_mfma_f32_16x16x32_bf16 v[76:79], v[144:147], v[208:211], v[76:79]
	v_mfma_f32_16x16x32_bf16 v[72:75], v[172:175], v[208:211], v[72:75]
	v_mfma_f32_16x16x32_bf16 v[124:127], v[148:151], v[188:191], v[124:127]
	v_mfma_f32_16x16x32_bf16 v[120:123], v[180:183], v[188:191], v[120:123]
	v_mfma_f32_16x16x32_bf16 v[108:111], v[148:151], v[196:199], v[108:111]
	v_mfma_f32_16x16x32_bf16 v[104:107], v[180:183], v[196:199], v[104:107]
	v_mfma_f32_16x16x32_bf16 v[92:95], v[148:151], v[204:207], v[92:95]
	v_mfma_f32_16x16x32_bf16 v[88:91], v[180:183], v[204:207], v[88:91]
	v_mfma_f32_16x16x32_bf16 v[76:79], v[148:151], v[212:215], v[76:79]
	v_mfma_f32_16x16x32_bf16 v[72:75], v[180:183], v[212:215], v[72:75]
	s_barrier
	s_add_i32 s46, s37, s15
	v_lshl_add_u64 v[154:155], s[4:5], 0, v[132:133]
	s_mov_b32 m0, s46
	ds_read_b128 v[216:219], v167
	ds_read_b128 v[222:225], v167 offset:1024
	ds_read_b128 v[226:229], v167 offset:2048
	ds_read_b128 v[230:233], v167 offset:3072
	global_load_lds_dwordx4 v[154:155], off
	v_lshl_add_u64 v[158:159], s[4:5], 0, v[128:129]
	s_add_i32 m0, s46, 0x2000
	s_nop 0
	global_load_lds_dwordx4 v[158:159], off
	s_barrier
	s_waitcnt lgkmcnt(0)
	v_mfma_f32_16x16x32_bf16 v[116:119], v[216:219], v[184:187], v[116:119]
	v_mfma_f32_16x16x32_bf16 v[112:115], v[226:229], v[184:187], v[112:115]
	v_mfma_f32_16x16x32_bf16 v[100:103], v[216:219], v[192:195], v[100:103]
	v_mfma_f32_16x16x32_bf16 v[96:99], v[226:229], v[192:195], v[96:99]
	v_mfma_f32_16x16x32_bf16 v[84:87], v[216:219], v[200:203], v[84:87]
	v_mfma_f32_16x16x32_bf16 v[80:83], v[226:229], v[200:203], v[80:83]
	v_mfma_f32_16x16x32_bf16 v[68:71], v[216:219], v[208:211], v[68:71]
	v_mfma_f32_16x16x32_bf16 v[64:67], v[226:229], v[208:211], v[64:67]
	v_mfma_f32_16x16x32_bf16 v[116:119], v[222:225], v[188:191], v[116:119]
	v_mfma_f32_16x16x32_bf16 v[112:115], v[230:233], v[188:191], v[112:115]
	v_mfma_f32_16x16x32_bf16 v[100:103], v[222:225], v[196:199], v[100:103]
	v_mfma_f32_16x16x32_bf16 v[96:99], v[230:233], v[196:199], v[96:99]
	v_mfma_f32_16x16x32_bf16 v[84:87], v[222:225], v[204:207], v[84:87]
	v_mfma_f32_16x16x32_bf16 v[80:83], v[230:233], v[204:207], v[80:83]
	v_mfma_f32_16x16x32_bf16 v[68:71], v[222:225], v[212:215], v[68:71]
	v_mfma_f32_16x16x32_bf16 v[64:67], v[230:233], v[212:215], v[64:67]
	s_mov_b32 m0, s17
	v_lshl_add_u64 v[162:163], s[10:11], 0, v[134:135]
	s_barrier
	ds_read_b128 v[184:187], v165 offset:16384
	ds_read_b128 v[188:191], v165 offset:17408
	ds_read_b128 v[192:195], v165 offset:18432
	ds_read_b128 v[196:199], v165 offset:19456
	ds_read_b128 v[200:203], v165 offset:20480
	ds_read_b128 v[204:207], v165 offset:21504
	ds_read_b128 v[208:211], v165 offset:22528
	ds_read_b128 v[212:215], v165 offset:23552
	global_load_lds_dwordx4 v[162:163], off
	v_lshl_add_u64 v[168:169], s[10:11], 0, v[130:131]
	s_mov_b32 m0, s28
	s_nop 0
	global_load_lds_dwordx4 v[168:169], off
	s_barrier
	s_waitcnt lgkmcnt(0)
	v_mfma_f32_16x16x32_bf16 v[60:63], v[144:147], v[184:187], v[60:63]
	v_mfma_f32_16x16x32_bf16 v[56:59], v[172:175], v[184:187], v[56:59]
	v_mfma_f32_16x16x32_bf16 v[44:47], v[144:147], v[192:195], v[44:47]
	v_mfma_f32_16x16x32_bf16 v[40:43], v[172:175], v[192:195], v[40:43]
	v_mfma_f32_16x16x32_bf16 v[28:31], v[144:147], v[200:203], v[28:31]
	v_mfma_f32_16x16x32_bf16 v[24:27], v[172:175], v[200:203], v[24:27]
	v_mfma_f32_16x16x32_bf16 v[12:15], v[144:147], v[208:211], v[12:15]
	v_mfma_f32_16x16x32_bf16 v[8:11], v[172:175], v[208:211], v[8:11]
	v_mfma_f32_16x16x32_bf16 v[60:63], v[148:151], v[188:191], v[60:63]
	v_mfma_f32_16x16x32_bf16 v[56:59], v[180:183], v[188:191], v[56:59]
	v_mfma_f32_16x16x32_bf16 v[44:47], v[148:151], v[196:199], v[44:47]
	v_mfma_f32_16x16x32_bf16 v[40:43], v[180:183], v[196:199], v[40:43]
	v_mfma_f32_16x16x32_bf16 v[28:31], v[148:151], v[204:207], v[28:31]
	v_mfma_f32_16x16x32_bf16 v[24:27], v[180:183], v[204:207], v[24:27]
	v_mfma_f32_16x16x32_bf16 v[12:15], v[148:151], v[212:215], v[12:15]
	v_mfma_f32_16x16x32_bf16 v[8:11], v[180:183], v[212:215], v[8:11]
	s_barrier
	s_add_u32 s46, s4, 0x40000
	s_addc_u32 s47, s5, 0
	s_add_i32 s48, s38, s15
	v_lshl_add_u64 v[144:145], s[46:47], 0, v[132:133]
	s_mov_b32 m0, s48
	s_nop 0
	global_load_lds_dwordx4 v[144:145], off
	v_lshl_add_u64 v[144:145], s[46:47], 0, v[128:129]
	s_add_i32 m0, s48, 0x2000
	s_nop 0
	global_load_lds_dwordx4 v[144:145], off
	s_waitcnt vmcnt(6)
	s_barrier
	v_mfma_f32_16x16x32_bf16 v[52:55], v[216:219], v[184:187], v[52:55]
	v_mfma_f32_16x16x32_bf16 v[48:51], v[226:229], v[184:187], v[48:51]
	v_mfma_f32_16x16x32_bf16 v[36:39], v[216:219], v[192:195], v[36:39]
	v_mfma_f32_16x16x32_bf16 v[32:35], v[226:229], v[192:195], v[32:35]
	v_mfma_f32_16x16x32_bf16 v[20:23], v[216:219], v[200:203], v[20:23]
	v_mfma_f32_16x16x32_bf16 v[16:19], v[226:229], v[200:203], v[16:19]
	v_mfma_f32_16x16x32_bf16 v[4:7], v[216:219], v[208:211], v[4:7]
	v_mfma_f32_16x16x32_bf16 v[0:3], v[226:229], v[208:211], v[0:3]
	v_mfma_f32_16x16x32_bf16 v[52:55], v[222:225], v[188:191], v[52:55]
	v_mfma_f32_16x16x32_bf16 v[48:51], v[230:233], v[188:191], v[48:51]
	v_mfma_f32_16x16x32_bf16 v[36:39], v[222:225], v[196:199], v[36:39]
	v_mfma_f32_16x16x32_bf16 v[32:35], v[230:233], v[196:199], v[32:35]
	v_mfma_f32_16x16x32_bf16 v[20:23], v[222:225], v[204:207], v[20:23]
	v_mfma_f32_16x16x32_bf16 v[16:19], v[230:233], v[204:207], v[16:19]
	v_mfma_f32_16x16x32_bf16 v[4:7], v[222:225], v[212:215], v[4:7]
	v_mfma_f32_16x16x32_bf16 v[0:3], v[230:233], v[212:215], v[0:3]
	s_add_i32 s46, 0, 0x18000
	v_add_u32_e32 v152, s46, v157
	s_barrier
	ds_read_b128 v[184:187], v165 offset:32768
	ds_read_b128 v[188:191], v165 offset:33792
	ds_read_b128 v[192:195], v165 offset:34816
	ds_read_b128 v[196:199], v165 offset:35840
	ds_read_b128 v[200:203], v165 offset:36864
	ds_read_b128 v[204:207], v165 offset:37888
	ds_read_b128 v[208:211], v165 offset:38912
	ds_read_b128 v[212:215], v165 offset:39936
	ds_read_b128 v[144:147], v152
	ds_read_b128 v[148:151], v152 offset:1024
	ds_read_b128 v[172:175], v152 offset:2048
	ds_read_b128 v[180:183], v152 offset:3072
	s_add_u32 s10, s10, 0x40000
	s_addc_u32 s11, s11, 0
	s_mov_b32 m0, s29
	v_lshl_add_u64 v[176:177], s[10:11], 0, v[134:135]
	global_load_lds_dwordx4 v[176:177], off
	v_lshl_add_u64 v[176:177], s[10:11], 0, v[130:131]
	s_mov_b32 m0, s31
	s_nop 0
	global_load_lds_dwordx4 v[176:177], off
	s_waitcnt lgkmcnt(0)
	s_barrier
	v_mfma_f32_16x16x32_bf16 v[124:127], v[144:147], v[184:187], v[124:127]
	v_mfma_f32_16x16x32_bf16 v[120:123], v[172:175], v[184:187], v[120:123]
	v_mfma_f32_16x16x32_bf16 v[108:111], v[144:147], v[192:195], v[108:111]
	v_mfma_f32_16x16x32_bf16 v[104:107], v[172:175], v[192:195], v[104:107]
	v_mfma_f32_16x16x32_bf16 v[92:95], v[144:147], v[200:203], v[92:95]
	v_mfma_f32_16x16x32_bf16 v[88:91], v[172:175], v[200:203], v[88:91]
	v_mfma_f32_16x16x32_bf16 v[76:79], v[144:147], v[208:211], v[76:79]
	v_mfma_f32_16x16x32_bf16 v[72:75], v[172:175], v[208:211], v[72:75]
	v_mfma_f32_16x16x32_bf16 v[124:127], v[148:151], v[188:191], v[124:127]
	v_mfma_f32_16x16x32_bf16 v[120:123], v[180:183], v[188:191], v[120:123]
	v_mfma_f32_16x16x32_bf16 v[108:111], v[148:151], v[196:199], v[108:111]
	v_mfma_f32_16x16x32_bf16 v[104:107], v[180:183], v[196:199], v[104:107]
	v_mfma_f32_16x16x32_bf16 v[92:95], v[148:151], v[204:207], v[92:95]
	v_mfma_f32_16x16x32_bf16 v[88:91], v[180:183], v[204:207], v[88:91]
	v_mfma_f32_16x16x32_bf16 v[76:79], v[148:151], v[212:215], v[76:79]
	v_mfma_f32_16x16x32_bf16 v[72:75], v[180:183], v[212:215], v[72:75]
	s_barrier
	s_add_i32 s10, 0, 0x1c000
	s_add_i32 s11, s46, s15
	v_add_u32_e32 v152, s10, v157
	v_lshl_add_u64 v[154:155], v[154:155], 0, s[12:13]
	s_mov_b32 m0, s11
	ds_read_b128 v[216:219], v152
	ds_read_b128 v[222:225], v152 offset:1024
	ds_read_b128 v[226:229], v152 offset:2048
	ds_read_b128 v[230:233], v152 offset:3072
	global_load_lds_dwordx4 v[154:155], off
	v_lshl_add_u64 v[154:155], v[158:159], 0, s[12:13]
	s_add_i32 m0, s11, 0x2000
	s_nop 0
	global_load_lds_dwordx4 v[154:155], off
	s_barrier
	s_waitcnt lgkmcnt(0)
	v_mfma_f32_16x16x32_bf16 v[116:119], v[216:219], v[184:187], v[116:119]
	v_mfma_f32_16x16x32_bf16 v[112:115], v[226:229], v[184:187], v[112:115]
	v_mfma_f32_16x16x32_bf16 v[100:103], v[216:219], v[192:195], v[100:103]
	v_mfma_f32_16x16x32_bf16 v[96:99], v[226:229], v[192:195], v[96:99]
	v_mfma_f32_16x16x32_bf16 v[84:87], v[216:219], v[200:203], v[84:87]
	v_mfma_f32_16x16x32_bf16 v[80:83], v[226:229], v[200:203], v[80:83]
	v_mfma_f32_16x16x32_bf16 v[68:71], v[216:219], v[208:211], v[68:71]
	v_mfma_f32_16x16x32_bf16 v[64:67], v[226:229], v[208:211], v[64:67]
	v_mfma_f32_16x16x32_bf16 v[116:119], v[222:225], v[188:191], v[116:119]
	v_mfma_f32_16x16x32_bf16 v[112:115], v[230:233], v[188:191], v[112:115]
	v_mfma_f32_16x16x32_bf16 v[100:103], v[222:225], v[196:199], v[100:103]
	v_mfma_f32_16x16x32_bf16 v[96:99], v[230:233], v[196:199], v[96:99]
	v_mfma_f32_16x16x32_bf16 v[84:87], v[222:225], v[204:207], v[84:87]
	v_mfma_f32_16x16x32_bf16 v[80:83], v[230:233], v[204:207], v[80:83]
	v_mfma_f32_16x16x32_bf16 v[68:71], v[222:225], v[212:215], v[68:71]
	v_mfma_f32_16x16x32_bf16 v[64:67], v[230:233], v[212:215], v[64:67]
	s_mov_b32 m0, s35
	v_lshl_add_u64 v[154:155], v[162:163], 0, s[12:13]
	s_barrier
	ds_read_b128 v[184:187], v165 offset:49152
	ds_read_b128 v[188:191], v165 offset:50176
	ds_read_b128 v[192:195], v165 offset:51200
	ds_read_b128 v[196:199], v165 offset:52224
	ds_read_b128 v[200:203], v165 offset:53248
	ds_read_b128 v[204:207], v165 offset:54272
	ds_read_b128 v[208:211], v165 offset:55296
	ds_read_b128 v[212:215], v165 offset:56320
	global_load_lds_dwordx4 v[154:155], off
	v_lshl_add_u64 v[154:155], v[168:169], 0, s[12:13]
	s_mov_b32 m0, s36
	s_nop 0
	global_load_lds_dwordx4 v[154:155], off
	s_barrier
	s_waitcnt lgkmcnt(0)
	v_mfma_f32_16x16x32_bf16 v[60:63], v[144:147], v[184:187], v[60:63]
	v_mfma_f32_16x16x32_bf16 v[56:59], v[172:175], v[184:187], v[56:59]
	v_mfma_f32_16x16x32_bf16 v[44:47], v[144:147], v[192:195], v[44:47]
	v_mfma_f32_16x16x32_bf16 v[40:43], v[172:175], v[192:195], v[40:43]
	v_mfma_f32_16x16x32_bf16 v[28:31], v[144:147], v[200:203], v[28:31]
	v_mfma_f32_16x16x32_bf16 v[24:27], v[172:175], v[200:203], v[24:27]
	v_mfma_f32_16x16x32_bf16 v[12:15], v[144:147], v[208:211], v[12:15]
	v_mfma_f32_16x16x32_bf16 v[8:11], v[172:175], v[208:211], v[8:11]
	v_mfma_f32_16x16x32_bf16 v[60:63], v[148:151], v[188:191], v[60:63]
	v_mfma_f32_16x16x32_bf16 v[56:59], v[180:183], v[188:191], v[56:59]
	v_mfma_f32_16x16x32_bf16 v[44:47], v[148:151], v[196:199], v[44:47]
	v_mfma_f32_16x16x32_bf16 v[40:43], v[180:183], v[196:199], v[40:43]
	v_mfma_f32_16x16x32_bf16 v[28:31], v[148:151], v[204:207], v[28:31]
	v_mfma_f32_16x16x32_bf16 v[24:27], v[180:183], v[204:207], v[24:27]
	v_mfma_f32_16x16x32_bf16 v[12:15], v[148:151], v[212:215], v[12:15]
	v_mfma_f32_16x16x32_bf16 v[8:11], v[180:183], v[212:215], v[8:11]
	s_barrier
	s_add_u32 s4, s4, 0x40080
	s_addc_u32 s5, s5, 0
	s_add_i32 s10, s10, s15
	v_lshl_add_u64 v[144:145], s[4:5], 0, v[132:133]
	s_mov_b32 m0, s10
	s_nop 0
	global_load_lds_dwordx4 v[144:145], off
	v_lshl_add_u64 v[144:145], s[4:5], 0, v[128:129]
	s_add_i32 m0, s10, 0x2000
	s_nop 0
	global_load_lds_dwordx4 v[144:145], off
	s_waitcnt vmcnt(6)
	s_barrier
	v_mfma_f32_16x16x32_bf16 v[52:55], v[216:219], v[184:187], v[52:55]
	v_mfma_f32_16x16x32_bf16 v[48:51], v[226:229], v[184:187], v[48:51]
	v_mfma_f32_16x16x32_bf16 v[36:39], v[216:219], v[192:195], v[36:39]
	v_mfma_f32_16x16x32_bf16 v[32:35], v[226:229], v[192:195], v[32:35]
	v_mfma_f32_16x16x32_bf16 v[20:23], v[216:219], v[200:203], v[20:23]
	v_mfma_f32_16x16x32_bf16 v[16:19], v[226:229], v[200:203], v[16:19]
	v_mfma_f32_16x16x32_bf16 v[4:7], v[216:219], v[208:211], v[4:7]
	v_mfma_f32_16x16x32_bf16 v[0:3], v[226:229], v[208:211], v[0:3]
	v_mfma_f32_16x16x32_bf16 v[52:55], v[222:225], v[188:191], v[52:55]
	v_mfma_f32_16x16x32_bf16 v[48:51], v[230:233], v[188:191], v[48:51]
	v_mfma_f32_16x16x32_bf16 v[36:39], v[222:225], v[196:199], v[36:39]
	v_mfma_f32_16x16x32_bf16 v[32:35], v[230:233], v[196:199], v[32:35]
	v_mfma_f32_16x16x32_bf16 v[20:23], v[222:225], v[204:207], v[20:23]
	v_mfma_f32_16x16x32_bf16 v[16:19], v[230:233], v[204:207], v[16:19]
	v_mfma_f32_16x16x32_bf16 v[4:7], v[222:225], v[212:215], v[4:7]
	v_mfma_f32_16x16x32_bf16 v[0:3], v[230:233], v[212:215], v[0:3]
	s_add_i32 s45, s45, 2
	s_add_u32 s0, s0, 0x100
	s_addc_u32 s1, s1, 0
	s_add_u32 s43, s43, 0x100
	s_addc_u32 s44, s44, 0
	s_cmp_gt_u32 s45, 13
	s_barrier
	s_cbranch_scc0 .LBB0_1441
	v_lshl_add_u32 v168, s72, 8, v153
	v_ashrrev_i32_e32 v169, 31, v168
	v_or_b32_e32 v162, 16, v168
	v_lshlrev_b64 v[144:145], 6, v[168:169]
	v_ashrrev_i32_e32 v163, 31, v162
	v_or_b32_e32 v158, 32, v168
	v_lshl_add_u64 v[144:145], v[138:139], 0, v[144:145]
	v_lshlrev_b64 v[146:147], 6, v[162:163]
	v_ashrrev_i32_e32 v159, 31, v158
	v_lshl_add_u64 v[146:147], v[138:139], 0, v[146:147]
	global_load_dwordx4 v[172:175], v[144:145], off
	global_load_dwordx4 v[180:183], v[146:147], off
	v_lshlrev_b64 v[144:145], 6, v[158:159]
	v_or_b32_e32 v154, 48, v168
	v_lshl_add_u64 v[144:145], v[138:139], 0, v[144:145]
	v_ashrrev_i32_e32 v155, 31, v154
	global_load_dwordx4 v[184:187], v[144:145], off
	v_lshlrev_b64 v[144:145], 6, v[154:155]
	v_lshl_add_u64 v[144:145], v[138:139], 0, v[144:145]
	global_load_dwordx4 v[188:191], v[144:145], off
	v_add_u32_e32 v150, 0x80, v168
	v_ashrrev_i32_e32 v151, 31, v150
	v_lshlrev_b64 v[144:145], 6, v[150:151]
	v_add_u32_e32 v148, 0x90, v168
	v_lshl_add_u64 v[144:145], v[138:139], 0, v[144:145]
	v_ashrrev_i32_e32 v149, 31, v148
	global_load_dwordx4 v[192:195], v[144:145], off
	v_lshlrev_b64 v[144:145], 6, v[148:149]
	v_lshl_add_u64 v[144:145], v[138:139], 0, v[144:145]
	global_load_dwordx4 v[196:199], v[144:145], off
	v_and_b32_e32 v145, 64, v171
	v_add_u32_e32 v146, 0xa0, v168
	v_add_u32_e32 v144, 0xb0, v168
	v_add_u32_e32 v160, 64, v145
	v_ashrrev_i32_e32 v147, 31, v146
	v_ashrrev_i32_e32 v145, 31, v144
	v_lshlrev_b64 v[200:201], 6, v[146:147]
	v_lshlrev_b64 v[202:203], 6, v[144:145]
	v_lshl_add_u64 v[200:201], v[138:139], 0, v[200:201]
	v_lshl_add_u64 v[204:205], v[138:139], 0, v[202:203]
	global_load_dwordx4 v[200:203], v[200:201], off
	s_nop 0
	global_load_dwordx4 v[204:207], v[204:205], off
	v_xor_b32_e32 v152, 16, v171
	v_cmp_lt_i32_e32 vcc, v152, v160
	v_xor_b32_e32 v156, 32, v171
	v_mov_b64_e32 v[176:177], s[16:17]
	v_cndmask_b32_e32 v152, v171, v152, vcc
	v_lshlrev_b32_e32 v152, 2, v152
	v_cmp_lt_i32_e32 vcc, v156, v160
	v_lshlrev_b64 v[168:169], 7, v[168:169]
	s_mov_b32 s72, s18
	v_cndmask_b32_e32 v156, v171, v156, vcc
	v_lshlrev_b32_e32 v156, 2, v156
	s_mov_b32 s21, s18
	s_mov_b32 s19, s40
	s_waitcnt vmcnt(0)
	v_mov_b32_e32 v208, v173
	v_mov_b32_e32 v209, v174
	v_mov_b32_e32 v173, v175
	v_mov_b32_e32 v174, v181
	v_mov_b32_e32 v175, v182
	v_mov_b32_e32 v181, v183
	v_pk_add_f32 v[172:173], v[208:209], v[172:173]
	v_pk_add_f32 v[174:175], v[174:175], v[180:181]
	v_mov_b32_e32 v181, v172
	v_mov_b32_e32 v180, v174
	v_mov_b32_e32 v172, v175
	v_mov_b32_e32 v182, v185
	v_mov_b32_e32 v183, v186
	v_mov_b32_e32 v185, v187
	v_mov_b32_e32 v186, v189
	v_mov_b32_e32 v187, v190
	v_mov_b32_e32 v189, v191
	v_pk_add_f32 v[172:173], v[180:181], v[172:173]
	v_pk_add_f32 v[182:183], v[182:183], v[184:185]
	v_pk_add_f32 v[184:185], v[186:187], v[188:189]
	ds_bpermute_b32 v181, v152, v173
	ds_bpermute_b32 v180, v152, v172
	v_mov_b32_e32 v174, v184
	v_mov_b32_e32 v175, v182
	v_mov_b32_e32 v182, v185
	v_pk_add_f32 v[174:175], v[174:175], v[182:183]
	ds_bpermute_b32 v183, v152, v175
	ds_bpermute_b32 v182, v152, v174
	s_waitcnt lgkmcnt(0)
	v_pk_add_f32 v[172:173], v[172:173], v[180:181]
	ds_bpermute_b32 v181, v156, v173
	ds_bpermute_b32 v180, v156, v172
	v_mov_b32_e32 v184, v193
	v_pk_add_f32 v[174:175], v[174:175], v[182:183]
	ds_bpermute_b32 v183, v156, v175
	ds_bpermute_b32 v182, v156, v174
	s_waitcnt lgkmcnt(2)
	v_pk_add_f32 v[172:173], v[172:173], v[180:181]
	v_mov_b32_e32 v185, v194
	v_mov_b32_e32 v193, v195
	v_mov_b32_e32 v186, v197
	v_mov_b32_e32 v187, v198
	v_pk_fma_f32 v[172:173], v[172:173], s[14:15], v[176:177] op_sel_hi:[1,0,0]
	v_mov_b32_e32 v197, v199
	v_pk_add_f32 v[184:185], v[184:185], v[192:193]
	v_mul_f32_e32 v160, 0x4b800000, v173
	v_cmp_gt_f32_e32 vcc, s39, v173
	v_pk_add_f32 v[180:181], v[186:187], v[196:197]
	s_waitcnt lgkmcnt(0)
	v_pk_add_f32 v[174:175], v[174:175], v[182:183]
	v_cndmask_b32_e32 v160, v173, v160, vcc
	v_mov_b32_e32 v182, v180
	v_mov_b32_e32 v183, v184
	v_mov_b32_e32 v184, v181
	v_rsq_f32_e32 v160, v160
	v_pk_add_f32 v[180:181], v[182:183], v[184:185]
	ds_bpermute_b32 v183, v152, v181
	ds_bpermute_b32 v182, v152, v180
	v_pk_fma_f32 v[174:175], v[174:175], s[14:15], v[176:177] op_sel_hi:[1,0,0]
	v_mul_f32_e32 v164, 0x4b800000, v172
	v_cmp_gt_f32_e64 s[0:1], s39, v172
	v_mul_f32_e32 v170, 0x45800000, v160
	v_mul_f32_e32 v166, 0x4b800000, v175
	v_cndmask_b32_e64 v164, v172, v164, s[0:1]
	v_cmp_gt_f32_e64 s[4:5], s39, v175
	v_cndmask_b32_e32 v172, v160, v170, vcc
	v_mul_f32_e32 v160, 0x4b800000, v174
	v_cmp_gt_f32_e32 vcc, s39, v174
	v_cndmask_b32_e64 v166, v175, v166, s[4:5]
	v_mov_b32_e32 v184, v205
	v_cndmask_b32_e32 v160, v174, v160, vcc
	s_waitcnt lgkmcnt(0)
	v_pk_add_f32 v[174:175], v[180:181], v[182:183]
	ds_bpermute_b32 v181, v156, v175
	ds_bpermute_b32 v180, v156, v174
	v_mov_b32_e32 v185, v206
	v_mov_b32_e32 v205, v207
	v_pk_add_f32 v[184:185], v[184:185], v[204:205]
	v_rsq_f32_e32 v164, v164
	s_waitcnt lgkmcnt(0)
	v_pk_add_f32 v[174:175], v[174:175], v[180:181]
	v_mov_b32_e32 v180, v201
	v_mov_b32_e32 v181, v202
	v_mov_b32_e32 v201, v203
	v_pk_add_f32 v[180:181], v[180:181], v[200:201]
	v_mov_b32_e32 v186, v184
	v_mov_b32_e32 v187, v180
	v_mov_b32_e32 v180, v185
	v_rsq_f32_e32 v166, v166
	v_pk_add_f32 v[180:181], v[186:187], v[180:181]
	ds_bpermute_b32 v185, v152, v181
	ds_bpermute_b32 v184, v152, v180
	v_mul_f32_e32 v173, 0x45800000, v164
	v_cndmask_b32_e64 v182, v164, v173, s[0:1]
	v_mul_f32_e32 v164, 0x45800000, v166
	v_pk_fma_f32 v[174:175], v[174:175], s[14:15], v[176:177] op_sel_hi:[1,0,0]
	v_cndmask_b32_e64 v170, v166, v164, s[4:5]
	v_mul_f32_e32 v166, 0x4b800000, v175
	v_cmp_gt_f32_e64 s[0:1], s39, v175
	v_mul_f32_e32 v152, 0x4b800000, v174
	v_cmp_gt_f32_e64 s[4:5], s39, v174
	v_cndmask_b32_e64 v166, v175, v166, s[0:1]
	v_rsq_f32_e32 v160, v160
	v_cndmask_b32_e64 v152, v174, v152, s[4:5]
	s_waitcnt lgkmcnt(0)
	v_pk_add_f32 v[174:175], v[180:181], v[184:185]
	ds_bpermute_b32 v181, v156, v175
	ds_bpermute_b32 v180, v156, v174
	v_rsq_f32_e32 v173, v166
	v_mul_f32_e32 v164, 0x45800000, v160
	v_cndmask_b32_e32 v166, v160, v164, vcc
	v_rsq_f32_e32 v152, v152
	s_waitcnt lgkmcnt(0)
	v_pk_add_f32 v[174:175], v[174:175], v[180:181]
	v_mul_f32_e32 v156, 0x45800000, v173
	v_pk_fma_f32 v[174:175], v[174:175], s[14:15], v[176:177] op_sel_hi:[1,0,0]
	v_cndmask_b32_e64 v164, v173, v156, s[0:1]
	v_mul_f32_e32 v160, 0x4b800000, v175
	v_cmp_gt_f32_e32 vcc, s39, v175
	v_cmp_gt_f32_e64 s[0:1], s39, v174
	v_mul_f32_e32 v156, 0x45800000, v152
	v_cndmask_b32_e32 v160, v175, v160, vcc
	v_rsq_f32_e32 v173, v160
	v_mul_f32_e32 v160, 0x4b800000, v174
	v_cndmask_b32_e64 v160, v174, v160, s[0:1]
	v_rsq_f32_e32 v174, v160
	v_cndmask_b32_e64 v160, v152, v156, s[4:5]
	v_mul_f32_e32 v152, 0x45800000, v173
	v_cndmask_b32_e32 v156, v173, v152, vcc
	v_mul_f32_e32 v152, 0x45800000, v174
	v_cndmask_b32_e64 v152, v174, v152, s[0:1]
	s_lshl_b32 s0, s70, 8
	s_or_b32 s0, s0, s33
	s_ashr_i32 s4, s0, 6
	s_ashr_i32 s5, s4, 31
	s_lshl_b64 s[0:1], s[4:5], 22
	v_pk_mul_f32 v[124:125], v[124:125], v[172:173] op_sel_hi:[1,0]
	v_pk_mul_f32 v[120:121], v[120:121], v[172:173] op_sel_hi:[1,0]
	s_add_u32 s0, s84, s0
	v_pk_mul_f32 v[126:127], v[126:127], v[172:173] op_sel_hi:[1,0]
	v_pk_mul_f32 v[122:123], v[122:123], v[172:173] op_sel_hi:[1,0]
	v_max_f32_e32 v124, 0, v124
	v_max_f32_e32 v120, 0, v120
	v_max_f32_e32 v125, 0, v125
	v_max_f32_e32 v121, 0, v121
	s_addc_u32 s1, s85, s1
	s_or_b32 s4, s4, 2
	v_pk_mul_f32 v[124:125], v[124:125], v[124:125]
	v_pk_mul_f32 v[174:175], v[120:121], v[120:121]
	v_max_f32_e32 v120, 0, v126
	v_max_f32_e32 v122, 0, v122
	v_max_f32_e32 v121, 0, v127
	v_max_f32_e32 v123, 0, v123
	s_ashr_i32 s5, s4, 31
	v_pk_mul_f32 v[126:127], v[120:121], v[120:121]
	v_pk_mul_f32 v[176:177], v[122:123], v[122:123]
	v_cvt_pk_bf16_f32 v120, v124, v125
	v_lshl_add_u64 v[124:125], s[0:1], 0, v[168:169]
	v_pk_mul_f32 v[116:117], v[116:117], v[172:173] op_sel_hi:[1,0]
	v_pk_mul_f32 v[112:113], v[112:113], v[172:173] op_sel_hi:[1,0]
	s_lshl_b64 s[4:5], s[4:5], 22
	v_cvt_pk_bf16_f32 v121, v126, v127
	v_cvt_pk_bf16_f32 v122, v174, v175
	v_cvt_pk_bf16_f32 v123, v176, v177
	v_lshl_add_u64 v[124:125], v[124:125], 0, v[136:137]
	v_pk_mul_f32 v[118:119], v[118:119], v[172:173] op_sel_hi:[1,0]
	v_pk_mul_f32 v[114:115], v[114:115], v[172:173] op_sel_hi:[1,0]
	v_max_f32_e32 v116, 0, v116
	v_max_f32_e32 v112, 0, v112
	v_max_f32_e32 v117, 0, v117
	v_max_f32_e32 v113, 0, v113
	s_add_u32 s4, s84, s4
	global_store_dwordx4 v[124:125], v[120:123], off nt
	v_pk_mul_f32 v[116:117], v[116:117], v[116:117]
	v_max_f32_e32 v114, 0, v114
	v_pk_mul_f32 v[120:121], v[112:113], v[112:113]
	v_max_f32_e32 v112, 0, v118
	v_max_f32_e32 v113, 0, v119
	v_max_f32_e32 v115, 0, v115
	s_addc_u32 s5, s85, s5
	v_pk_mul_f32 v[118:119], v[112:113], v[112:113]
	v_pk_mul_f32 v[122:123], v[114:115], v[114:115]
	v_cvt_pk_bf16_f32 v112, v116, v117
	v_lshl_add_u64 v[116:117], s[4:5], 0, v[168:169]
	v_pk_mul_f32 v[108:109], v[108:109], v[182:183] op_sel_hi:[1,0]
	v_pk_mul_f32 v[104:105], v[104:105], v[182:183] op_sel_hi:[1,0]
	v_cvt_pk_bf16_f32 v113, v118, v119
	v_cvt_pk_bf16_f32 v114, v120, v121
	v_cvt_pk_bf16_f32 v115, v122, v123
	v_lshl_add_u64 v[116:117], v[116:117], 0, v[136:137]
	v_pk_mul_f32 v[110:111], v[110:111], v[182:183] op_sel_hi:[1,0]
	v_pk_mul_f32 v[106:107], v[106:107], v[182:183] op_sel_hi:[1,0]
	v_max_f32_e32 v108, 0, v108
	v_max_f32_e32 v104, 0, v104
	v_max_f32_e32 v109, 0, v109
	v_max_f32_e32 v105, 0, v105
	global_store_dwordx4 v[116:117], v[112:115], off nt
	v_pk_mul_f32 v[108:109], v[108:109], v[108:109]
	v_max_f32_e32 v106, 0, v106
	v_lshlrev_b64 v[112:113], 7, v[162:163]
	v_pk_mul_f32 v[114:115], v[104:105], v[104:105]
	v_max_f32_e32 v104, 0, v110
	v_max_f32_e32 v105, 0, v111
	v_max_f32_e32 v107, 0, v107
	v_pk_mul_f32 v[110:111], v[104:105], v[104:105]
	v_pk_mul_f32 v[116:117], v[106:107], v[106:107]
	v_cvt_pk_bf16_f32 v104, v108, v109
	v_lshl_add_u64 v[108:109], s[0:1], 0, v[112:113]
	v_pk_mul_f32 v[100:101], v[100:101], v[182:183] op_sel_hi:[1,0]
	v_pk_mul_f32 v[96:97], v[96:97], v[182:183] op_sel_hi:[1,0]
	v_cvt_pk_bf16_f32 v105, v110, v111
	v_cvt_pk_bf16_f32 v106, v114, v115
	v_cvt_pk_bf16_f32 v107, v116, v117
	v_lshl_add_u64 v[108:109], v[108:109], 0, v[136:137]
	v_pk_mul_f32 v[102:103], v[102:103], v[182:183] op_sel_hi:[1,0]
	v_pk_mul_f32 v[98:99], v[98:99], v[182:183] op_sel_hi:[1,0]
	v_max_f32_e32 v100, 0, v100
	v_max_f32_e32 v96, 0, v96
	v_max_f32_e32 v101, 0, v101
	v_max_f32_e32 v97, 0, v97
	global_store_dwordx4 v[108:109], v[104:107], off nt
	v_pk_mul_f32 v[100:101], v[100:101], v[100:101]
	v_max_f32_e32 v98, 0, v98
	v_pk_mul_f32 v[104:105], v[96:97], v[96:97]
	v_max_f32_e32 v96, 0, v102
	v_max_f32_e32 v97, 0, v103
	v_max_f32_e32 v99, 0, v99
	v_pk_mul_f32 v[102:103], v[96:97], v[96:97]
	v_pk_mul_f32 v[106:107], v[98:99], v[98:99]
	v_cvt_pk_bf16_f32 v96, v100, v101
	v_lshl_add_u64 v[100:101], s[4:5], 0, v[112:113]
	v_pk_mul_f32 v[92:93], v[92:93], v[170:171] op_sel_hi:[1,0]
	v_pk_mul_f32 v[88:89], v[88:89], v[170:171] op_sel_hi:[1,0]
	v_cvt_pk_bf16_f32 v97, v102, v103
	v_cvt_pk_bf16_f32 v98, v104, v105
	v_cvt_pk_bf16_f32 v99, v106, v107
	v_lshl_add_u64 v[100:101], v[100:101], 0, v[136:137]
	v_pk_mul_f32 v[94:95], v[94:95], v[170:171] op_sel_hi:[1,0]
	v_pk_mul_f32 v[90:91], v[90:91], v[170:171] op_sel_hi:[1,0]
	v_max_f32_e32 v92, 0, v92
	v_max_f32_e32 v88, 0, v88
	v_max_f32_e32 v93, 0, v93
	v_max_f32_e32 v89, 0, v89
	global_store_dwordx4 v[100:101], v[96:99], off nt
	v_pk_mul_f32 v[92:93], v[92:93], v[92:93]
	v_max_f32_e32 v90, 0, v90
	v_lshlrev_b64 v[96:97], 7, v[158:159]
	v_pk_mul_f32 v[98:99], v[88:89], v[88:89]
	v_max_f32_e32 v88, 0, v94
	v_max_f32_e32 v89, 0, v95
	v_max_f32_e32 v91, 0, v91
	v_pk_mul_f32 v[94:95], v[88:89], v[88:89]
	v_pk_mul_f32 v[100:101], v[90:91], v[90:91]
	v_cvt_pk_bf16_f32 v88, v92, v93
	v_lshl_add_u64 v[92:93], s[0:1], 0, v[96:97]
	v_pk_mul_f32 v[84:85], v[84:85], v[170:171] op_sel_hi:[1,0]
	v_pk_mul_f32 v[80:81], v[80:81], v[170:171] op_sel_hi:[1,0]
	v_cvt_pk_bf16_f32 v89, v94, v95
	v_cvt_pk_bf16_f32 v90, v98, v99
	v_cvt_pk_bf16_f32 v91, v100, v101
	v_lshl_add_u64 v[92:93], v[92:93], 0, v[136:137]
	v_pk_mul_f32 v[86:87], v[86:87], v[170:171] op_sel_hi:[1,0]
	v_pk_mul_f32 v[82:83], v[82:83], v[170:171] op_sel_hi:[1,0]
	v_max_f32_e32 v84, 0, v84
	v_max_f32_e32 v80, 0, v80
	v_max_f32_e32 v85, 0, v85
	v_max_f32_e32 v81, 0, v81
	global_store_dwordx4 v[92:93], v[88:91], off nt
	v_pk_mul_f32 v[84:85], v[84:85], v[84:85]
	v_max_f32_e32 v82, 0, v82
	v_pk_mul_f32 v[88:89], v[80:81], v[80:81]
	v_max_f32_e32 v80, 0, v86
	v_max_f32_e32 v81, 0, v87
	v_max_f32_e32 v83, 0, v83
	v_pk_mul_f32 v[86:87], v[80:81], v[80:81]
	v_pk_mul_f32 v[90:91], v[82:83], v[82:83]
	v_cvt_pk_bf16_f32 v80, v84, v85
	v_lshl_add_u64 v[84:85], s[4:5], 0, v[96:97]
	v_pk_mul_f32 v[76:77], v[76:77], v[166:167] op_sel_hi:[1,0]
	v_pk_mul_f32 v[72:73], v[72:73], v[166:167] op_sel_hi:[1,0]
	v_cvt_pk_bf16_f32 v81, v86, v87
	v_cvt_pk_bf16_f32 v82, v88, v89
	v_cvt_pk_bf16_f32 v83, v90, v91
	v_lshl_add_u64 v[84:85], v[84:85], 0, v[136:137]
	v_pk_mul_f32 v[78:79], v[78:79], v[166:167] op_sel_hi:[1,0]
	v_pk_mul_f32 v[74:75], v[74:75], v[166:167] op_sel_hi:[1,0]
	v_max_f32_e32 v76, 0, v76
	v_max_f32_e32 v72, 0, v72
	v_max_f32_e32 v77, 0, v77
	v_max_f32_e32 v73, 0, v73
	global_store_dwordx4 v[84:85], v[80:83], off nt
	v_pk_mul_f32 v[76:77], v[76:77], v[76:77]
	v_max_f32_e32 v74, 0, v74
	v_lshlrev_b64 v[80:81], 7, v[154:155]
	v_pk_mul_f32 v[82:83], v[72:73], v[72:73]
	v_max_f32_e32 v72, 0, v78
	v_max_f32_e32 v73, 0, v79
	v_max_f32_e32 v75, 0, v75
	v_pk_mul_f32 v[78:79], v[72:73], v[72:73]
	v_pk_mul_f32 v[84:85], v[74:75], v[74:75]
	v_cvt_pk_bf16_f32 v72, v76, v77
	v_lshl_add_u64 v[76:77], s[0:1], 0, v[80:81]
	v_pk_mul_f32 v[68:69], v[68:69], v[166:167] op_sel_hi:[1,0]
	v_pk_mul_f32 v[64:65], v[64:65], v[166:167] op_sel_hi:[1,0]
	v_cvt_pk_bf16_f32 v73, v78, v79
	v_cvt_pk_bf16_f32 v74, v82, v83
	v_cvt_pk_bf16_f32 v75, v84, v85
	v_lshl_add_u64 v[76:77], v[76:77], 0, v[136:137]
	v_pk_mul_f32 v[70:71], v[70:71], v[166:167] op_sel_hi:[1,0]
	v_pk_mul_f32 v[66:67], v[66:67], v[166:167] op_sel_hi:[1,0]
	v_max_f32_e32 v68, 0, v68
	v_max_f32_e32 v64, 0, v64
	v_max_f32_e32 v69, 0, v69
	v_max_f32_e32 v65, 0, v65
	global_store_dwordx4 v[76:77], v[72:75], off nt
	v_pk_mul_f32 v[68:69], v[68:69], v[68:69]
	v_max_f32_e32 v66, 0, v66
	v_pk_mul_f32 v[72:73], v[64:65], v[64:65]
	v_max_f32_e32 v64, 0, v70
	v_max_f32_e32 v65, 0, v71
	v_max_f32_e32 v67, 0, v67
	v_pk_mul_f32 v[70:71], v[64:65], v[64:65]
	v_pk_mul_f32 v[74:75], v[66:67], v[66:67]
	v_cvt_pk_bf16_f32 v64, v68, v69
	v_lshl_add_u64 v[68:69], s[4:5], 0, v[80:81]
	v_pk_mul_f32 v[60:61], v[60:61], v[164:165] op_sel_hi:[1,0]
	v_pk_mul_f32 v[56:57], v[56:57], v[164:165] op_sel_hi:[1,0]
	v_cvt_pk_bf16_f32 v65, v70, v71
	v_cvt_pk_bf16_f32 v66, v72, v73
	v_cvt_pk_bf16_f32 v67, v74, v75
	v_lshl_add_u64 v[68:69], v[68:69], 0, v[136:137]
	v_pk_mul_f32 v[62:63], v[62:63], v[164:165] op_sel_hi:[1,0]
	v_pk_mul_f32 v[58:59], v[58:59], v[164:165] op_sel_hi:[1,0]
	v_max_f32_e32 v60, 0, v60
	v_max_f32_e32 v56, 0, v56
	v_max_f32_e32 v61, 0, v61
	v_max_f32_e32 v57, 0, v57
	global_store_dwordx4 v[68:69], v[64:67], off nt
	v_pk_mul_f32 v[60:61], v[60:61], v[60:61]
	v_max_f32_e32 v58, 0, v58
	v_lshlrev_b64 v[64:65], 7, v[150:151]
	v_pk_mul_f32 v[66:67], v[56:57], v[56:57]
	v_max_f32_e32 v56, 0, v62
	v_max_f32_e32 v57, 0, v63
	v_max_f32_e32 v59, 0, v59
	v_pk_mul_f32 v[62:63], v[56:57], v[56:57]
	v_pk_mul_f32 v[68:69], v[58:59], v[58:59]
	v_cvt_pk_bf16_f32 v56, v60, v61
	v_lshl_add_u64 v[60:61], s[0:1], 0, v[64:65]
	v_pk_mul_f32 v[52:53], v[52:53], v[164:165] op_sel_hi:[1,0]
	v_pk_mul_f32 v[48:49], v[48:49], v[164:165] op_sel_hi:[1,0]
	v_cvt_pk_bf16_f32 v57, v62, v63
	v_cvt_pk_bf16_f32 v58, v66, v67
	v_cvt_pk_bf16_f32 v59, v68, v69
	v_lshl_add_u64 v[60:61], v[60:61], 0, v[136:137]
	v_pk_mul_f32 v[54:55], v[54:55], v[164:165] op_sel_hi:[1,0]
	v_pk_mul_f32 v[50:51], v[50:51], v[164:165] op_sel_hi:[1,0]
	v_max_f32_e32 v52, 0, v52
	v_max_f32_e32 v48, 0, v48
	v_max_f32_e32 v53, 0, v53
	v_max_f32_e32 v49, 0, v49
	global_store_dwordx4 v[60:61], v[56:59], off nt
	v_pk_mul_f32 v[52:53], v[52:53], v[52:53]
	v_max_f32_e32 v50, 0, v50
	v_pk_mul_f32 v[56:57], v[48:49], v[48:49]
	v_max_f32_e32 v48, 0, v54
	v_max_f32_e32 v49, 0, v55
	v_max_f32_e32 v51, 0, v51
	v_pk_mul_f32 v[54:55], v[48:49], v[48:49]
	v_pk_mul_f32 v[58:59], v[50:51], v[50:51]
	v_cvt_pk_bf16_f32 v48, v52, v53
	v_lshl_add_u64 v[52:53], s[4:5], 0, v[64:65]
	v_pk_mul_f32 v[44:45], v[44:45], v[160:161] op_sel_hi:[1,0]
	v_pk_mul_f32 v[40:41], v[40:41], v[160:161] op_sel_hi:[1,0]
	v_cvt_pk_bf16_f32 v49, v54, v55
	v_cvt_pk_bf16_f32 v50, v56, v57
	v_cvt_pk_bf16_f32 v51, v58, v59
	v_lshl_add_u64 v[52:53], v[52:53], 0, v[136:137]
	v_pk_mul_f32 v[46:47], v[46:47], v[160:161] op_sel_hi:[1,0]
	v_pk_mul_f32 v[42:43], v[42:43], v[160:161] op_sel_hi:[1,0]
	v_max_f32_e32 v44, 0, v44
	v_max_f32_e32 v40, 0, v40
	v_max_f32_e32 v45, 0, v45
	v_max_f32_e32 v41, 0, v41
	global_store_dwordx4 v[52:53], v[48:51], off nt
	v_pk_mul_f32 v[44:45], v[44:45], v[44:45]
	v_max_f32_e32 v42, 0, v42
	v_lshlrev_b64 v[48:49], 7, v[148:149]
	v_pk_mul_f32 v[50:51], v[40:41], v[40:41]
	v_max_f32_e32 v40, 0, v46
	v_max_f32_e32 v41, 0, v47
	v_max_f32_e32 v43, 0, v43
	v_pk_mul_f32 v[46:47], v[40:41], v[40:41]
	v_pk_mul_f32 v[52:53], v[42:43], v[42:43]
	v_cvt_pk_bf16_f32 v40, v44, v45
	v_lshl_add_u64 v[44:45], s[0:1], 0, v[48:49]
	v_pk_mul_f32 v[36:37], v[36:37], v[160:161] op_sel_hi:[1,0]
	v_pk_mul_f32 v[32:33], v[32:33], v[160:161] op_sel_hi:[1,0]
	v_cvt_pk_bf16_f32 v41, v46, v47
	v_cvt_pk_bf16_f32 v42, v50, v51
	v_cvt_pk_bf16_f32 v43, v52, v53
	v_lshl_add_u64 v[44:45], v[44:45], 0, v[136:137]
	v_pk_mul_f32 v[38:39], v[38:39], v[160:161] op_sel_hi:[1,0]
	v_pk_mul_f32 v[34:35], v[34:35], v[160:161] op_sel_hi:[1,0]
	v_max_f32_e32 v36, 0, v36
	v_max_f32_e32 v32, 0, v32
	v_max_f32_e32 v37, 0, v37
	v_max_f32_e32 v33, 0, v33
	global_store_dwordx4 v[44:45], v[40:43], off nt
	v_pk_mul_f32 v[36:37], v[36:37], v[36:37]
	v_max_f32_e32 v34, 0, v34
	v_pk_mul_f32 v[40:41], v[32:33], v[32:33]
	v_max_f32_e32 v32, 0, v38
	v_max_f32_e32 v33, 0, v39
	v_max_f32_e32 v35, 0, v35
	v_pk_mul_f32 v[38:39], v[32:33], v[32:33]
	v_pk_mul_f32 v[42:43], v[34:35], v[34:35]
	v_cvt_pk_bf16_f32 v32, v36, v37
	v_lshl_add_u64 v[36:37], s[4:5], 0, v[48:49]
	v_pk_mul_f32 v[28:29], v[28:29], v[156:157] op_sel_hi:[1,0]
	v_pk_mul_f32 v[24:25], v[24:25], v[156:157] op_sel_hi:[1,0]
	v_cvt_pk_bf16_f32 v33, v38, v39
	v_cvt_pk_bf16_f32 v34, v40, v41
	v_cvt_pk_bf16_f32 v35, v42, v43
	v_lshl_add_u64 v[36:37], v[36:37], 0, v[136:137]
	v_pk_mul_f32 v[30:31], v[30:31], v[156:157] op_sel_hi:[1,0]
	v_pk_mul_f32 v[26:27], v[26:27], v[156:157] op_sel_hi:[1,0]
	v_max_f32_e32 v28, 0, v28
	v_max_f32_e32 v24, 0, v24
	v_max_f32_e32 v29, 0, v29
	v_max_f32_e32 v25, 0, v25
	global_store_dwordx4 v[36:37], v[32:35], off nt
	v_pk_mul_f32 v[28:29], v[28:29], v[28:29]
	v_max_f32_e32 v26, 0, v26
	v_lshlrev_b64 v[32:33], 7, v[146:147]
	v_pk_mul_f32 v[34:35], v[24:25], v[24:25]
	v_max_f32_e32 v24, 0, v30
	v_max_f32_e32 v25, 0, v31
	v_max_f32_e32 v27, 0, v27
	v_pk_mul_f32 v[30:31], v[24:25], v[24:25]
	v_pk_mul_f32 v[36:37], v[26:27], v[26:27]
	v_cvt_pk_bf16_f32 v24, v28, v29
	v_lshl_add_u64 v[28:29], s[0:1], 0, v[32:33]
	v_pk_mul_f32 v[20:21], v[20:21], v[156:157] op_sel_hi:[1,0]
	v_pk_mul_f32 v[16:17], v[16:17], v[156:157] op_sel_hi:[1,0]
	v_cvt_pk_bf16_f32 v25, v30, v31
	v_cvt_pk_bf16_f32 v26, v34, v35
	v_cvt_pk_bf16_f32 v27, v36, v37
	v_lshl_add_u64 v[28:29], v[28:29], 0, v[136:137]
	v_pk_mul_f32 v[22:23], v[22:23], v[156:157] op_sel_hi:[1,0]
	v_pk_mul_f32 v[18:19], v[18:19], v[156:157] op_sel_hi:[1,0]
	v_max_f32_e32 v20, 0, v20
	v_max_f32_e32 v16, 0, v16
	v_max_f32_e32 v21, 0, v21
	v_max_f32_e32 v17, 0, v17
	global_store_dwordx4 v[28:29], v[24:27], off nt
	v_pk_mul_f32 v[20:21], v[20:21], v[20:21]
	v_max_f32_e32 v18, 0, v18
	v_pk_mul_f32 v[24:25], v[16:17], v[16:17]
	v_max_f32_e32 v16, 0, v22
	v_max_f32_e32 v17, 0, v23
	v_max_f32_e32 v19, 0, v19
	v_pk_mul_f32 v[22:23], v[16:17], v[16:17]
	v_pk_mul_f32 v[26:27], v[18:19], v[18:19]
	v_cvt_pk_bf16_f32 v16, v20, v21
	v_lshl_add_u64 v[20:21], s[4:5], 0, v[32:33]
	v_pk_mul_f32 v[12:13], v[12:13], v[152:153] op_sel_hi:[1,0]
	v_pk_mul_f32 v[8:9], v[8:9], v[152:153] op_sel_hi:[1,0]
	v_cvt_pk_bf16_f32 v17, v22, v23
	v_cvt_pk_bf16_f32 v18, v24, v25
	v_cvt_pk_bf16_f32 v19, v26, v27
	v_lshl_add_u64 v[20:21], v[20:21], 0, v[136:137]
	v_pk_mul_f32 v[14:15], v[14:15], v[152:153] op_sel_hi:[1,0]
	v_pk_mul_f32 v[10:11], v[10:11], v[152:153] op_sel_hi:[1,0]
	v_max_f32_e32 v12, 0, v12
	v_max_f32_e32 v8, 0, v8
	v_max_f32_e32 v13, 0, v13
	v_max_f32_e32 v9, 0, v9
	global_store_dwordx4 v[20:21], v[16:19], off nt
	v_pk_mul_f32 v[12:13], v[12:13], v[12:13]
	v_max_f32_e32 v10, 0, v10
	v_lshlrev_b64 v[16:17], 7, v[144:145]
	v_pk_mul_f32 v[18:19], v[8:9], v[8:9]
	v_max_f32_e32 v8, 0, v14
	v_max_f32_e32 v9, 0, v15
	v_max_f32_e32 v11, 0, v11
	v_pk_mul_f32 v[14:15], v[8:9], v[8:9]
	v_pk_mul_f32 v[20:21], v[10:11], v[10:11]
	v_cvt_pk_bf16_f32 v8, v12, v13
	v_lshl_add_u64 v[12:13], s[0:1], 0, v[16:17]
	v_pk_mul_f32 v[4:5], v[4:5], v[152:153] op_sel_hi:[1,0]
	v_pk_mul_f32 v[0:1], v[0:1], v[152:153] op_sel_hi:[1,0]
	v_cvt_pk_bf16_f32 v9, v14, v15
	v_cvt_pk_bf16_f32 v10, v18, v19
	v_cvt_pk_bf16_f32 v11, v20, v21
	v_lshl_add_u64 v[12:13], v[12:13], 0, v[136:137]
	v_pk_mul_f32 v[6:7], v[6:7], v[152:153] op_sel_hi:[1,0]
	v_pk_mul_f32 v[2:3], v[2:3], v[152:153] op_sel_hi:[1,0]
	v_max_f32_e32 v4, 0, v4
	v_max_f32_e32 v0, 0, v0
	v_max_f32_e32 v5, 0, v5
	v_max_f32_e32 v1, 0, v1
	global_store_dwordx4 v[12:13], v[8:11], off nt
	v_pk_mul_f32 v[4:5], v[4:5], v[4:5]
	v_max_f32_e32 v2, 0, v2
	v_pk_mul_f32 v[8:9], v[0:1], v[0:1]
	v_max_f32_e32 v0, 0, v6
	v_max_f32_e32 v1, 0, v7
	v_max_f32_e32 v3, 0, v3
	v_pk_mul_f32 v[6:7], v[0:1], v[0:1]
	v_pk_mul_f32 v[10:11], v[2:3], v[2:3]
	v_cvt_pk_bf16_f32 v0, v4, v5
	v_lshl_add_u64 v[4:5], s[4:5], 0, v[16:17]
	v_cvt_pk_bf16_f32 v1, v6, v7
	v_cvt_pk_bf16_f32 v2, v8, v9
	v_cvt_pk_bf16_f32 v3, v10, v11
	v_lshl_add_u64 v[4:5], v[4:5], 0, v[136:137]
	s_and_b64 vcc, exec, s[24:25]
	s_mov_b32 s70, s20
	s_mov_b32 s24, s20
	s_mov_b64 s[4:5], s[26:27]
	s_mov_b64 s[0:1], s[22:23]
	global_store_dwordx4 v[4:5], v[0:3], off nt
	s_cbranch_vccz .LBB0_1433
	s_waitcnt vmcnt(0)
	s_cmpk_gt_u32 s7, 0xff
	s_cbranch_scc1 .LBB0_1445
	s_barrier

.LBB0_1512:
	ds_read_b128 v[144:147], v204
	ds_read_b128 v[148:151], v204 offset:1024
	ds_read_b128 v[172:175], v204 offset:2048
	ds_read_b128 v[176:179], v204 offset:3072
	ds_read_b128 v[180:183], v204 offset:4096
	ds_read_b128 v[184:187], v204 offset:5120
	ds_read_b128 v[188:191], v204 offset:6144
	ds_read_b128 v[192:195], v204 offset:7168
	ds_read_b128 v[128:131], v203
	ds_read_b128 v[132:135], v203 offset:1024
	ds_read_b128 v[136:139], v203 offset:2048
	ds_read_b128 v[140:143], v203 offset:3072
	s_add_u32 s26, s24, 0x3fc000
	s_addc_u32 s27, s25, 0
	s_cmp_eq_u32 s49, 60
	s_cselect_b32 s30, s7, s26
	s_cselect_b32 s31, s5, s27
	s_cselect_b32 s26, s15, s17
	s_cselect_b32 s27, s8, s48
	s_add_u32 s28, s30, 0x400000
	s_addc_u32 s29, s31, 0
	v_lshl_add_u64 v[196:197], s[24:25], 0, v[168:169]
	s_add_i32 m0, s33, 0xc000
	s_nop 0
	global_load_lds_dwordx4 v[196:197], off
	v_lshl_add_u64 v[196:197], s[24:25], 0, v[170:171]
	s_add_i32 m0, s33, 0xe000
	s_nop 0
	global_load_lds_dwordx4 v[196:197], off
	s_waitcnt lgkmcnt(0)
	s_barrier
	v_mfma_f32_16x16x32_bf16 v[124:127], v[128:131], v[144:147], v[124:127]
	v_mfma_f32_16x16x32_bf16 v[120:123], v[136:139], v[144:147], v[120:123]
	v_mfma_f32_16x16x32_bf16 v[108:111], v[128:131], v[172:175], v[108:111]
	v_mfma_f32_16x16x32_bf16 v[104:107], v[136:139], v[172:175], v[104:107]
	v_mfma_f32_16x16x32_bf16 v[92:95], v[128:131], v[180:183], v[92:95]
	v_mfma_f32_16x16x32_bf16 v[88:91], v[136:139], v[180:183], v[88:91]
	v_mfma_f32_16x16x32_bf16 v[76:79], v[128:131], v[188:191], v[76:79]
	v_mfma_f32_16x16x32_bf16 v[72:75], v[136:139], v[188:191], v[72:75]
	v_mfma_f32_16x16x32_bf16 v[124:127], v[132:135], v[148:151], v[124:127]
	v_mfma_f32_16x16x32_bf16 v[120:123], v[140:143], v[148:151], v[120:123]
	v_mfma_f32_16x16x32_bf16 v[108:111], v[132:135], v[176:179], v[108:111]
	v_mfma_f32_16x16x32_bf16 v[104:107], v[140:143], v[176:179], v[104:107]
	v_mfma_f32_16x16x32_bf16 v[92:95], v[132:135], v[184:187], v[92:95]
	v_mfma_f32_16x16x32_bf16 v[88:91], v[140:143], v[184:187], v[88:91]
	v_mfma_f32_16x16x32_bf16 v[76:79], v[132:135], v[192:195], v[76:79]
	v_mfma_f32_16x16x32_bf16 v[72:75], v[140:143], v[192:195], v[72:75]
	s_barrier
	s_add_i32 s50, s44, s13
	v_lshl_add_u64 v[200:201], s[26:27], 0, v[156:157]
	s_mov_b32 m0, s50
	ds_read_b128 v[196:199], v205
	ds_read_b128 v[208:211], v205 offset:1024
	ds_read_b128 v[212:215], v205 offset:2048
	ds_read_b128 v[216:219], v205 offset:3072
	global_load_lds_dwordx4 v[200:201], off
	v_lshl_add_u64 v[200:201], s[26:27], 0, v[152:153]
	s_add_i32 m0, s50, 0x2000
	s_nop 0
	global_load_lds_dwordx4 v[200:201], off
	s_barrier
	s_waitcnt lgkmcnt(0)
	v_mfma_f32_16x16x32_bf16 v[116:119], v[196:199], v[144:147], v[116:119]
	v_mfma_f32_16x16x32_bf16 v[112:115], v[212:215], v[144:147], v[112:115]
	v_mfma_f32_16x16x32_bf16 v[100:103], v[196:199], v[172:175], v[100:103]
	v_mfma_f32_16x16x32_bf16 v[96:99], v[212:215], v[172:175], v[96:99]
	v_mfma_f32_16x16x32_bf16 v[84:87], v[196:199], v[180:183], v[84:87]
	v_mfma_f32_16x16x32_bf16 v[80:83], v[212:215], v[180:183], v[80:83]
	v_mfma_f32_16x16x32_bf16 v[68:71], v[196:199], v[188:191], v[68:71]
	v_mfma_f32_16x16x32_bf16 v[64:67], v[212:215], v[188:191], v[64:67]
	v_mfma_f32_16x16x32_bf16 v[116:119], v[208:211], v[148:151], v[116:119]
	v_mfma_f32_16x16x32_bf16 v[112:115], v[216:219], v[148:151], v[112:115]
	v_mfma_f32_16x16x32_bf16 v[100:103], v[208:211], v[176:179], v[100:103]
	v_mfma_f32_16x16x32_bf16 v[96:99], v[216:219], v[176:179], v[96:99]
	v_mfma_f32_16x16x32_bf16 v[84:87], v[208:211], v[184:187], v[84:87]
	v_mfma_f32_16x16x32_bf16 v[80:83], v[216:219], v[184:187], v[80:83]
	v_mfma_f32_16x16x32_bf16 v[68:71], v[208:211], v[192:195], v[68:71]
	v_mfma_f32_16x16x32_bf16 v[64:67], v[216:219], v[192:195], v[64:67]
	s_mov_b32 m0, s33
	v_lshl_add_u64 v[200:201], s[30:31], 0, v[158:159]
	s_barrier
	ds_read_b128 v[144:147], v204 offset:16384
	ds_read_b128 v[148:151], v204 offset:17408
	ds_read_b128 v[172:175], v204 offset:18432
	ds_read_b128 v[176:179], v204 offset:19456
	ds_read_b128 v[180:183], v204 offset:20480
	ds_read_b128 v[184:187], v204 offset:21504
	ds_read_b128 v[188:191], v204 offset:22528
	ds_read_b128 v[192:195], v204 offset:23552
	global_load_lds_dwordx4 v[200:201], off
	v_lshl_add_u64 v[200:201], s[30:31], 0, v[154:155]
	s_mov_b32 m0, s35
	s_nop 0
	global_load_lds_dwordx4 v[200:201], off
	s_barrier
	s_waitcnt lgkmcnt(0)
	v_mfma_f32_16x16x32_bf16 v[60:63], v[128:131], v[144:147], v[60:63]
	v_mfma_f32_16x16x32_bf16 v[56:59], v[136:139], v[144:147], v[56:59]
	v_mfma_f32_16x16x32_bf16 v[44:47], v[128:131], v[172:175], v[44:47]
	v_mfma_f32_16x16x32_bf16 v[40:43], v[136:139], v[172:175], v[40:43]
	v_mfma_f32_16x16x32_bf16 v[28:31], v[128:131], v[180:183], v[28:31]
	v_mfma_f32_16x16x32_bf16 v[24:27], v[136:139], v[180:183], v[24:27]
	v_mfma_f32_16x16x32_bf16 v[12:15], v[128:131], v[188:191], v[12:15]
	v_mfma_f32_16x16x32_bf16 v[8:11], v[136:139], v[188:191], v[8:11]
	v_mfma_f32_16x16x32_bf16 v[60:63], v[132:135], v[148:151], v[60:63]
	v_mfma_f32_16x16x32_bf16 v[56:59], v[140:143], v[148:151], v[56:59]
	v_mfma_f32_16x16x32_bf16 v[44:47], v[132:135], v[176:179], v[44:47]
	v_mfma_f32_16x16x32_bf16 v[40:43], v[140:143], v[176:179], v[40:43]
	v_mfma_f32_16x16x32_bf16 v[28:31], v[132:135], v[184:187], v[28:31]
	v_mfma_f32_16x16x32_bf16 v[24:27], v[140:143], v[184:187], v[24:27]
	v_mfma_f32_16x16x32_bf16 v[12:15], v[132:135], v[192:195], v[12:15]
	v_mfma_f32_16x16x32_bf16 v[8:11], v[140:143], v[192:195], v[8:11]
	s_barrier
	s_add_u32 s50, s26, 0x4000
	s_addc_u32 s51, s27, 0
	s_add_i32 s52, s45, s13
	v_lshl_add_u64 v[128:129], s[50:51], 0, v[156:157]
	s_mov_b32 m0, s52
	s_nop 0
	global_load_lds_dwordx4 v[128:129], off
	v_lshl_add_u64 v[128:129], s[50:51], 0, v[152:153]
	s_add_i32 m0, s52, 0x2000
	s_nop 0
	global_load_lds_dwordx4 v[128:129], off
	s_waitcnt vmcnt(6)
	s_barrier
	v_mfma_f32_16x16x32_bf16 v[52:55], v[196:199], v[144:147], v[52:55]
	v_mfma_f32_16x16x32_bf16 v[48:51], v[212:215], v[144:147], v[48:51]
	v_mfma_f32_16x16x32_bf16 v[36:39], v[196:199], v[172:175], v[36:39]
	v_mfma_f32_16x16x32_bf16 v[32:35], v[212:215], v[172:175], v[32:35]
	v_mfma_f32_16x16x32_bf16 v[20:23], v[196:199], v[180:183], v[20:23]
	v_mfma_f32_16x16x32_bf16 v[16:19], v[212:215], v[180:183], v[16:19]
	v_mfma_f32_16x16x32_bf16 v[4:7], v[196:199], v[188:191], v[4:7]
	v_mfma_f32_16x16x32_bf16 v[0:3], v[212:215], v[188:191], v[0:3]
	v_mfma_f32_16x16x32_bf16 v[52:55], v[208:211], v[148:151], v[52:55]
	v_mfma_f32_16x16x32_bf16 v[48:51], v[216:219], v[148:151], v[48:51]
	v_mfma_f32_16x16x32_bf16 v[36:39], v[208:211], v[176:179], v[36:39]
	v_mfma_f32_16x16x32_bf16 v[32:35], v[216:219], v[176:179], v[32:35]
	v_mfma_f32_16x16x32_bf16 v[20:23], v[208:211], v[184:187], v[20:23]
	v_mfma_f32_16x16x32_bf16 v[16:19], v[216:219], v[184:187], v[16:19]
	v_mfma_f32_16x16x32_bf16 v[4:7], v[208:211], v[192:195], v[4:7]
	v_mfma_f32_16x16x32_bf16 v[0:3], v[216:219], v[192:195], v[0:3]
	s_add_i32 s50, 0, 0x18000
	v_add_u32_e32 v140, s50, v202
	s_barrier
	ds_read_b128 v[144:147], v204 offset:32768
	ds_read_b128 v[148:151], v204 offset:33792
	ds_read_b128 v[172:175], v204 offset:34816
	ds_read_b128 v[176:179], v204 offset:35840
	ds_read_b128 v[180:183], v204 offset:36864
	ds_read_b128 v[184:187], v204 offset:37888
	ds_read_b128 v[188:191], v204 offset:38912
	ds_read_b128 v[192:195], v204 offset:39936
	ds_read_b128 v[128:131], v140
	ds_read_b128 v[132:135], v140 offset:1024
	ds_read_b128 v[136:139], v140 offset:2048
	ds_read_b128 v[140:143], v140 offset:3072
	s_add_u32 s30, s30, 0x4000
	s_addc_u32 s31, s31, 0
	s_mov_b32 m0, s36
	v_lshl_add_u64 v[196:197], s[30:31], 0, v[158:159]
	global_load_lds_dwordx4 v[196:197], off
	v_lshl_add_u64 v[196:197], s[30:31], 0, v[154:155]
	s_mov_b32 m0, s37
	s_nop 0
	global_load_lds_dwordx4 v[196:197], off
	s_waitcnt lgkmcnt(0)
	s_barrier
	v_mfma_f32_16x16x32_bf16 v[124:127], v[128:131], v[144:147], v[124:127]
	v_mfma_f32_16x16x32_bf16 v[120:123], v[136:139], v[144:147], v[120:123]
	v_mfma_f32_16x16x32_bf16 v[108:111], v[128:131], v[172:175], v[108:111]
	v_mfma_f32_16x16x32_bf16 v[104:107], v[136:139], v[172:175], v[104:107]
	v_mfma_f32_16x16x32_bf16 v[92:95], v[128:131], v[180:183], v[92:95]
	v_mfma_f32_16x16x32_bf16 v[88:91], v[136:139], v[180:183], v[88:91]
	v_mfma_f32_16x16x32_bf16 v[76:79], v[128:131], v[188:191], v[76:79]
	v_mfma_f32_16x16x32_bf16 v[72:75], v[136:139], v[188:191], v[72:75]
	v_mfma_f32_16x16x32_bf16 v[124:127], v[132:135], v[148:151], v[124:127]
	v_mfma_f32_16x16x32_bf16 v[120:123], v[140:143], v[148:151], v[120:123]
	v_mfma_f32_16x16x32_bf16 v[108:111], v[132:135], v[176:179], v[108:111]
	v_mfma_f32_16x16x32_bf16 v[104:107], v[140:143], v[176:179], v[104:107]
	v_mfma_f32_16x16x32_bf16 v[92:95], v[132:135], v[184:187], v[92:95]
	v_mfma_f32_16x16x32_bf16 v[88:91], v[140:143], v[184:187], v[88:91]
	v_mfma_f32_16x16x32_bf16 v[76:79], v[132:135], v[192:195], v[76:79]
	v_mfma_f32_16x16x32_bf16 v[72:75], v[140:143], v[192:195], v[72:75]
	s_barrier
	s_add_i32 s51, 0, 0x1c000
	s_add_u32 s30, s26, 0x20000
	v_add_u32_e32 v200, s51, v202
	s_addc_u32 s31, s27, 0
	s_add_i32 s50, s50, s13
	ds_read_b128 v[196:199], v200
	ds_read_b128 v[208:211], v200 offset:1024
	ds_read_b128 v[212:215], v200 offset:2048
	ds_read_b128 v[216:219], v200 offset:3072
	v_lshl_add_u64 v[200:201], s[30:31], 0, v[156:157]
	s_mov_b32 m0, s50
	s_nop 0
	global_load_lds_dwordx4 v[200:201], off
	v_lshl_add_u64 v[200:201], s[30:31], 0, v[152:153]
	s_add_i32 m0, s50, 0x2000
	s_nop 0
	global_load_lds_dwordx4 v[200:201], off
	s_barrier
	s_waitcnt lgkmcnt(0)
	v_mfma_f32_16x16x32_bf16 v[116:119], v[196:199], v[144:147], v[116:119]
	v_mfma_f32_16x16x32_bf16 v[112:115], v[212:215], v[144:147], v[112:115]
	v_mfma_f32_16x16x32_bf16 v[100:103], v[196:199], v[172:175], v[100:103]
	v_mfma_f32_16x16x32_bf16 v[96:99], v[212:215], v[172:175], v[96:99]
	v_mfma_f32_16x16x32_bf16 v[84:87], v[196:199], v[180:183], v[84:87]
	v_mfma_f32_16x16x32_bf16 v[80:83], v[212:215], v[180:183], v[80:83]
	v_mfma_f32_16x16x32_bf16 v[68:71], v[196:199], v[188:191], v[68:71]
	v_mfma_f32_16x16x32_bf16 v[64:67], v[212:215], v[188:191], v[64:67]
	v_mfma_f32_16x16x32_bf16 v[116:119], v[208:211], v[148:151], v[116:119]
	v_mfma_f32_16x16x32_bf16 v[112:115], v[216:219], v[148:151], v[112:115]
	v_mfma_f32_16x16x32_bf16 v[100:103], v[208:211], v[176:179], v[100:103]
	v_mfma_f32_16x16x32_bf16 v[96:99], v[216:219], v[176:179], v[96:99]
	v_mfma_f32_16x16x32_bf16 v[84:87], v[208:211], v[184:187], v[84:87]
	v_mfma_f32_16x16x32_bf16 v[80:83], v[216:219], v[184:187], v[80:83]
	v_mfma_f32_16x16x32_bf16 v[68:71], v[208:211], v[192:195], v[68:71]
	v_mfma_f32_16x16x32_bf16 v[64:67], v[216:219], v[192:195], v[64:67]
	s_mov_b32 m0, s41
	v_lshl_add_u64 v[200:201], s[28:29], 0, v[158:159]
	s_barrier
	ds_read_b128 v[144:147], v204 offset:49152
	ds_read_b128 v[148:151], v204 offset:50176
	ds_read_b128 v[172:175], v204 offset:51200
	ds_read_b128 v[176:179], v204 offset:52224
	ds_read_b128 v[180:183], v204 offset:53248
	ds_read_b128 v[184:187], v204 offset:54272
	ds_read_b128 v[188:191], v204 offset:55296
	ds_read_b128 v[192:195], v204 offset:56320
	global_load_lds_dwordx4 v[200:201], off
	v_lshl_add_u64 v[200:201], s[28:29], 0, v[154:155]
	s_mov_b32 m0, s42
	s_nop 0
	global_load_lds_dwordx4 v[200:201], off
	s_barrier
	s_waitcnt lgkmcnt(0)
	v_mfma_f32_16x16x32_bf16 v[60:63], v[128:131], v[144:147], v[60:63]
	v_mfma_f32_16x16x32_bf16 v[56:59], v[136:139], v[144:147], v[56:59]
	v_mfma_f32_16x16x32_bf16 v[44:47], v[128:131], v[172:175], v[44:47]
	v_mfma_f32_16x16x32_bf16 v[40:43], v[136:139], v[172:175], v[40:43]
	v_mfma_f32_16x16x32_bf16 v[28:31], v[128:131], v[180:183], v[28:31]
	v_mfma_f32_16x16x32_bf16 v[24:27], v[136:139], v[180:183], v[24:27]
	v_mfma_f32_16x16x32_bf16 v[12:15], v[128:131], v[188:191], v[12:15]
	v_mfma_f32_16x16x32_bf16 v[8:11], v[136:139], v[188:191], v[8:11]
	v_mfma_f32_16x16x32_bf16 v[60:63], v[132:135], v[148:151], v[60:63]
	v_mfma_f32_16x16x32_bf16 v[56:59], v[140:143], v[148:151], v[56:59]
	v_mfma_f32_16x16x32_bf16 v[44:47], v[132:135], v[176:179], v[44:47]
	v_mfma_f32_16x16x32_bf16 v[40:43], v[140:143], v[176:179], v[40:43]
	v_mfma_f32_16x16x32_bf16 v[28:31], v[132:135], v[184:187], v[28:31]
	v_mfma_f32_16x16x32_bf16 v[24:27], v[140:143], v[184:187], v[24:27]
	v_mfma_f32_16x16x32_bf16 v[12:15], v[132:135], v[192:195], v[12:15]
	v_mfma_f32_16x16x32_bf16 v[8:11], v[140:143], v[192:195], v[8:11]
	s_barrier
	s_add_u32 s26, s26, 0x24000
	s_addc_u32 s27, s27, 0
	s_add_i32 s28, s51, s13
	v_lshl_add_u64 v[128:129], s[26:27], 0, v[156:157]
	s_mov_b32 m0, s28
	s_nop 0
	global_load_lds_dwordx4 v[128:129], off
	v_lshl_add_u64 v[128:129], s[26:27], 0, v[152:153]
	s_add_i32 m0, s28, 0x2000
	s_nop 0
	global_load_lds_dwordx4 v[128:129], off
	s_waitcnt vmcnt(6)
	s_barrier
	v_mfma_f32_16x16x32_bf16 v[52:55], v[196:199], v[144:147], v[52:55]
	v_mfma_f32_16x16x32_bf16 v[48:51], v[212:215], v[144:147], v[48:51]
	v_mfma_f32_16x16x32_bf16 v[36:39], v[196:199], v[172:175], v[36:39]
	v_mfma_f32_16x16x32_bf16 v[32:35], v[212:215], v[172:175], v[32:35]
	v_mfma_f32_16x16x32_bf16 v[20:23], v[196:199], v[180:183], v[20:23]
	v_mfma_f32_16x16x32_bf16 v[16:19], v[212:215], v[180:183], v[16:19]
	v_mfma_f32_16x16x32_bf16 v[4:7], v[196:199], v[188:191], v[4:7]
	v_mfma_f32_16x16x32_bf16 v[0:3], v[212:215], v[188:191], v[0:3]
	v_mfma_f32_16x16x32_bf16 v[52:55], v[208:211], v[148:151], v[52:55]
	v_mfma_f32_16x16x32_bf16 v[48:51], v[216:219], v[148:151], v[48:51]
	v_mfma_f32_16x16x32_bf16 v[36:39], v[208:211], v[176:179], v[36:39]
	v_mfma_f32_16x16x32_bf16 v[32:35], v[216:219], v[176:179], v[32:35]
	v_mfma_f32_16x16x32_bf16 v[20:23], v[208:211], v[184:187], v[20:23]
	v_mfma_f32_16x16x32_bf16 v[16:19], v[216:219], v[184:187], v[16:19]
	v_mfma_f32_16x16x32_bf16 v[4:7], v[208:211], v[192:195], v[4:7]
	v_mfma_f32_16x16x32_bf16 v[0:3], v[216:219], v[192:195], v[0:3]
	s_add_i32 s49, s49, 2
	s_add_u32 s17, s17, 0x40000
	s_addc_u32 s48, s48, 0
	s_add_u32 s24, s24, 0x800000
	s_addc_u32 s25, s25, 0
	s_cmp_gt_u32 s49, 61
	s_barrier
	s_cbranch_scc0 .LBB0_1512
	s_nop 0
	s_lshl_b32 s24, s4, 8
	v_readlane_b32 s68, v253, 38
	v_readlane_b32 s69, v253, 39
	s_ashr_i32 s25, s24, 31
	s_lshl_b32 s4, s4, 2
	v_readlane_b32 s70, v253, 40
	v_readlane_b32 s71, v253, 41
	s_mov_b64 s[48:49], s[68:69]
	v_lshl_add_u32 v178, s6, 8, v163
	s_ashr_i32 s5, s4, 31
	s_lshl_b64 s[26:27], s[24:25], 1
	s_mov_b64 s[50:51], s[70:71]
	s_add_u32 s26, s50, s26
	v_ashrrev_i32_e32 v179, 31, v178
	s_addc_u32 s27, s51, s27
	v_lshlrev_b64 v[128:129], 11, v[178:179]
	v_lshl_add_u64 v[128:129], s[26:27], 0, v[128:129]
	v_lshl_add_u64 v[128:129], v[128:129], 0, v[160:161]
	global_load_dwordx4 v[180:183], v[128:129], off
	global_load_dwordx4 v[184:187], v[128:129], off offset:256
	v_or_b32_e32 v176, 16, v178
	v_or_b32_e32 v174, 32, v178
	v_or_b32_e32 v172, 48, v178
	v_ashrrev_i32_e32 v177, 31, v176
	v_ashrrev_i32_e32 v175, 31, v174
	v_ashrrev_i32_e32 v173, 31, v172
	v_lshlrev_b64 v[128:129], 11, v[176:177]
	v_lshlrev_b64 v[130:131], 11, v[174:175]
	v_lshlrev_b64 v[132:133], 11, v[172:173]
	v_lshl_add_u64 v[128:129], s[26:27], 0, v[128:129]
	v_lshl_add_u64 v[130:131], s[26:27], 0, v[130:131]
	v_lshl_add_u64 v[132:133], s[26:27], 0, v[132:133]
	v_lshl_add_u64 v[128:129], v[128:129], 0, v[160:161]
	v_lshl_add_u64 v[130:131], v[130:131], 0, v[160:161]
	v_lshl_add_u64 v[188:189], v[132:133], 0, v[160:161]
	global_load_dwordx4 v[148:151], v[128:129], off
	global_load_dwordx4 v[144:147], v[128:129], off offset:256
	global_load_dwordx4 v[140:143], v[130:131], off
	global_load_dwordx4 v[136:139], v[130:131], off offset:256
	global_load_dwordx4 v[132:135], v[188:189], off
	s_nop 0
	global_load_dwordx4 v[128:131], v[188:189], off offset:256
	v_and_b32_e32 v189, 64, v206
	v_xor_b32_e32 v188, 16, v206
	v_add_u32_e32 v196, 64, v189
	v_cmp_lt_i32_e32 vcc, v188, v196
	s_nop 1
	v_cndmask_b32_e32 v188, v206, v188, vcc
	v_lshlrev_b32_e32 v207, 2, v188
	s_nop 7
	s_nop 0
	s_waitcnt vmcnt(0)
	v_lshlrev_b32_e32 v190, 16, v182
	v_and_b32_e32 v191, 0xffff0000, v182
	v_lshlrev_b32_e32 v188, 16, v180
	v_and_b32_e32 v189, 0xffff0000, v180
	v_lshlrev_b32_e32 v180, 16, v181
	v_and_b32_e32 v181, 0xffff0000, v181
	v_lshlrev_b32_e32 v182, 16, v183
	v_and_b32_e32 v183, 0xffff0000, v183
	v_pk_add_f32 v[120:121], v[120:121], v[190:191]
	v_pk_add_f32 v[126:127], v[126:127], v[180:181]
	v_pk_add_f32 v[124:125], v[124:125], v[188:189]
	v_pk_add_f32 v[122:123], v[122:123], v[182:183]
	v_mul_f32_e32 v180, v120, v120
	v_mul_f32_e32 v181, v121, v121
	v_lshlrev_b32_e32 v194, 16, v186
	v_and_b32_e32 v195, 0xffff0000, v186
	v_mul_f32_e32 v182, v122, v122
	v_fmac_f32_e32 v180, v124, v124
	v_fmac_f32_e32 v181, v125, v125
	v_lshlrev_b32_e32 v192, 16, v184
	v_and_b32_e32 v193, 0xffff0000, v184
	v_lshlrev_b32_e32 v184, 16, v185
	v_and_b32_e32 v185, 0xffff0000, v185
	v_pk_add_f32 v[112:113], v[112:113], v[194:195]
	v_mul_f32_e32 v183, v123, v123
	v_fmac_f32_e32 v182, v126, v126
	v_add_f32_e32 v180, v180, v181
	v_lshlrev_b32_e32 v186, 16, v187
	v_and_b32_e32 v187, 0xffff0000, v187
	v_pk_add_f32 v[118:119], v[118:119], v[184:185]
	v_pk_add_f32 v[116:117], v[116:117], v[192:193]
	v_mul_f32_e32 v184, v112, v112
	v_fmac_f32_e32 v183, v127, v127
	v_add_f32_e32 v180, v182, v180
	v_pk_add_f32 v[114:115], v[114:115], v[186:187]
	v_mul_f32_e32 v185, v113, v113
	v_fmac_f32_e32 v184, v116, v116
	v_add_f32_e32 v180, v183, v180
	v_mul_f32_e32 v186, v114, v114
	v_fmac_f32_e32 v185, v117, v117
	v_add_f32_e32 v180, v184, v180
	v_mul_f32_e32 v187, v115, v115
	v_fmac_f32_e32 v186, v118, v118
	v_add_f32_e32 v180, v185, v180
	v_add_f32_e32 v180, v186, v180
	v_fmac_f32_e32 v187, v119, v119
	v_add_f32_e32 v180, v187, v180
	ds_bpermute_b32 v181, v207, v180
	v_xor_b32_e32 v182, 32, v206
	v_cmp_lt_i32_e32 vcc, v182, v196
	v_lshlrev_b64 v[188:189], 6, v[178:179]
	s_waitcnt lgkmcnt(0)
	v_add_f32_e32 v180, v180, v181
	v_cndmask_b32_e32 v182, v206, v182, vcc
	v_lshlrev_b32_e32 v208, 2, v182
	ds_bpermute_b32 v181, v208, v180
	s_and_saveexec_b64 s[28:29], s[0:1]
	s_cbranch_execz .LBB0_1515
	s_waitcnt lgkmcnt(0)
	v_add_f32_e32 v182, v180, v181
	v_lshl_add_u64 v[180:181], s[88:89], 0, v[188:189]
	v_lshl_add_u64 v[180:181], s[4:5], 2, v[180:181]
	s_lshl_b32 s8, s40, 2
	v_lshl_add_u64 v[180:181], v[180:181], 0, s[8:9]
	global_store_dword v[180:181], v182, off sc1
